# GEMM K-loops: base + half-tile step kept in an idle SGPR pair; the last VGPR address chains (36 v_lshl_add_u64) removed in nine loops
# baseline (speedup 1.0000x reference)
.LBB0_305:
	s_add_u32 s30, s4, 0xfffc0080
	s_addc_u32 s31, s5, -1
	s_add_i32 s52, 0, 0x10000
	ds_read_b128 v[150:153], v133
	ds_read_b128 v[156:159], v133 offset:1024
	ds_read_b128 v[160:163], v133 offset:2048
	ds_read_b128 v[164:167], v133 offset:3072
	s_cmp_eq_u32 s51, 12
	s_cselect_b32 s35, s27, s31
	s_cselect_b32 s34, s26, s30
	s_cselect_b32 s31, s29, s25
	s_cselect_b32 s30, s28, s23
	s_add_i32 m0, s42, 0xc000
	ds_read_b128 v[168:171], v155
	ds_read_b128 v[172:175], v155 offset:1024
	ds_read_b128 v[176:179], v155 offset:2048
	ds_read_b128 v[180:183], v155 offset:3072
	ds_read_b128 v[184:187], v155 offset:4096
	ds_read_b128 v[188:191], v155 offset:5120
	ds_read_b128 v[198:201], v155 offset:6144
	ds_read_b128 v[202:205], v155 offset:7168
	global_load_lds_dwordx4 v146, s[4:5]
	s_add_i32 m0, s42, 0xe000
	s_nop 0
	global_load_lds_dwordx4 v148, s[4:5]
	s_waitcnt lgkmcnt(8)
	s_barrier
	s_waitcnt lgkmcnt(0)
	s_setprio 1
	s_waitcnt lgkmcnt(0)
	v_mfma_f32_16x16x32_bf16 v[126:129], v[150:153], v[168:171], v[126:129]
	v_mfma_f32_16x16x32_bf16 v[122:125], v[160:163], v[168:171], v[122:125]
	v_mfma_f32_16x16x32_bf16 v[110:113], v[150:153], v[176:179], v[110:113]
	v_mfma_f32_16x16x32_bf16 v[106:109], v[160:163], v[176:179], v[106:109]
	v_mfma_f32_16x16x32_bf16 v[94:97], v[150:153], v[184:187], v[94:97]
	v_mfma_f32_16x16x32_bf16 v[90:93], v[160:163], v[184:187], v[90:93]
	v_mfma_f32_16x16x32_bf16 v[78:81], v[150:153], v[198:201], v[78:81]
	v_mfma_f32_16x16x32_bf16 v[74:77], v[160:163], v[198:201], v[74:77]
	v_mfma_f32_16x16x32_bf16 v[126:129], v[156:159], v[172:175], v[126:129]
	v_mfma_f32_16x16x32_bf16 v[122:125], v[164:167], v[172:175], v[122:125]
	v_mfma_f32_16x16x32_bf16 v[110:113], v[156:159], v[180:183], v[110:113]
	v_mfma_f32_16x16x32_bf16 v[106:109], v[164:167], v[180:183], v[106:109]
	v_mfma_f32_16x16x32_bf16 v[94:97], v[156:159], v[188:191], v[94:97]
	v_mfma_f32_16x16x32_bf16 v[90:93], v[164:167], v[188:191], v[90:93]
	v_mfma_f32_16x16x32_bf16 v[78:81], v[156:159], v[202:205], v[78:81]
	v_mfma_f32_16x16x32_bf16 v[74:77], v[164:167], v[202:205], v[74:77]
	s_setprio 0
	s_barrier
	s_add_i32 s54, 0, 0x14000
	s_add_i32 s52, s52, s41
	s_mov_b32 m0, s52
	ds_read_b128 v[206:209], v133 offset:16384
	ds_read_b128 v[210:213], v133 offset:17408
	ds_read_b128 v[214:217], v133 offset:18432
	ds_read_b128 v[218:221], v133 offset:19456
	global_load_lds_dwordx4 v132, s[30:31]
	s_add_i32 m0, s52, 0x2000
	s_nop 0
	global_load_lds_dwordx4 v136, s[30:31]
	s_barrier
	s_waitcnt lgkmcnt(0)
	s_setprio 1
	s_waitcnt lgkmcnt(0)
	v_mfma_f32_16x16x32_bf16 v[118:121], v[206:209], v[168:171], v[118:121]
	v_mfma_f32_16x16x32_bf16 v[114:117], v[214:217], v[168:171], v[114:117]
	v_mfma_f32_16x16x32_bf16 v[102:105], v[206:209], v[176:179], v[102:105]
	v_mfma_f32_16x16x32_bf16 v[98:101], v[214:217], v[176:179], v[98:101]
	v_mfma_f32_16x16x32_bf16 v[86:89], v[206:209], v[184:187], v[86:89]
	v_mfma_f32_16x16x32_bf16 v[82:85], v[214:217], v[184:187], v[82:85]
	v_mfma_f32_16x16x32_bf16 v[70:73], v[206:209], v[198:201], v[70:73]
	v_mfma_f32_16x16x32_bf16 v[66:69], v[214:217], v[198:201], v[66:69]
	v_mfma_f32_16x16x32_bf16 v[118:121], v[210:213], v[172:175], v[118:121]
	v_mfma_f32_16x16x32_bf16 v[114:117], v[218:221], v[172:175], v[114:117]
	v_mfma_f32_16x16x32_bf16 v[102:105], v[210:213], v[180:183], v[102:105]
	v_mfma_f32_16x16x32_bf16 v[98:101], v[218:221], v[180:183], v[98:101]
	v_mfma_f32_16x16x32_bf16 v[86:89], v[210:213], v[188:191], v[86:89]
	v_mfma_f32_16x16x32_bf16 v[82:85], v[218:221], v[188:191], v[82:85]
	v_mfma_f32_16x16x32_bf16 v[70:73], v[210:213], v[202:205], v[70:73]
	v_mfma_f32_16x16x32_bf16 v[66:69], v[218:221], v[202:205], v[66:69]
	s_setprio 0
	s_mov_b32 m0, s42
	s_add_u32 s58, s34, s66
	s_addc_u32 s59, s35, s67
	s_barrier
	ds_read_b128 v[168:171], v155 offset:16384
	ds_read_b128 v[172:175], v155 offset:17408
	ds_read_b128 v[176:179], v155 offset:18432
	ds_read_b128 v[180:183], v155 offset:19456
	ds_read_b128 v[184:187], v155 offset:20480
	ds_read_b128 v[188:191], v155 offset:21504
	ds_read_b128 v[198:201], v155 offset:22528
	ds_read_b128 v[202:205], v155 offset:23552
	global_load_lds_dwordx4 v130, s[34:35]
	s_mov_b32 m0, s43
	s_nop 0
	global_load_lds_dwordx4 v134, s[34:35]
	s_barrier
	s_waitcnt lgkmcnt(0)
	s_setprio 1
	s_waitcnt lgkmcnt(0)
	v_mfma_f32_16x16x32_bf16 v[62:65], v[150:153], v[168:171], v[62:65]
	v_mfma_f32_16x16x32_bf16 v[58:61], v[160:163], v[168:171], v[58:61]
	v_mfma_f32_16x16x32_bf16 v[44:47], v[150:153], v[176:179], v[44:47]
	v_mfma_f32_16x16x32_bf16 v[40:43], v[160:163], v[176:179], v[40:43]
	v_mfma_f32_16x16x32_bf16 v[28:31], v[150:153], v[184:187], v[28:31]
	v_mfma_f32_16x16x32_bf16 v[24:27], v[160:163], v[184:187], v[24:27]
	v_mfma_f32_16x16x32_bf16 v[12:15], v[150:153], v[198:201], v[12:15]
	v_mfma_f32_16x16x32_bf16 v[8:11], v[160:163], v[198:201], v[8:11]
	v_mfma_f32_16x16x32_bf16 v[62:65], v[156:159], v[172:175], v[62:65]
	v_mfma_f32_16x16x32_bf16 v[58:61], v[164:167], v[172:175], v[58:61]
	v_mfma_f32_16x16x32_bf16 v[44:47], v[156:159], v[180:183], v[44:47]
	v_mfma_f32_16x16x32_bf16 v[40:43], v[164:167], v[180:183], v[40:43]
	v_mfma_f32_16x16x32_bf16 v[28:31], v[156:159], v[188:191], v[28:31]
	v_mfma_f32_16x16x32_bf16 v[24:27], v[164:167], v[188:191], v[24:27]
	v_mfma_f32_16x16x32_bf16 v[12:15], v[156:159], v[202:205], v[12:15]
	v_mfma_f32_16x16x32_bf16 v[8:11], v[164:167], v[202:205], v[8:11]
	s_setprio 0
	s_barrier
	s_add_u32 s52, s30, 0x40000
	s_addc_u32 s53, s31, 0
	s_add_i32 s54, s54, s41
	s_mov_b32 m0, s54
	s_nop 0
	global_load_lds_dwordx4 v132, s[52:53]
	s_add_i32 m0, s54, 0x2000
	s_nop 0
	global_load_lds_dwordx4 v136, s[52:53]
	s_waitcnt vmcnt(6)
	s_barrier
	s_setprio 1
	v_mfma_f32_16x16x32_bf16 v[54:57], v[206:209], v[168:171], v[54:57]
	v_mfma_f32_16x16x32_bf16 v[50:53], v[214:217], v[168:171], v[50:53]
	v_mfma_f32_16x16x32_bf16 v[36:39], v[206:209], v[176:179], v[36:39]
	v_mfma_f32_16x16x32_bf16 v[32:35], v[214:217], v[176:179], v[32:35]
	v_mfma_f32_16x16x32_bf16 v[20:23], v[206:209], v[184:187], v[20:23]
	v_mfma_f32_16x16x32_bf16 v[16:19], v[214:217], v[184:187], v[16:19]
	v_mfma_f32_16x16x32_bf16 v[4:7], v[206:209], v[198:201], v[4:7]
	v_mfma_f32_16x16x32_bf16 v[0:3], v[214:217], v[198:201], v[0:3]
	v_mfma_f32_16x16x32_bf16 v[54:57], v[210:213], v[172:175], v[54:57]
	v_mfma_f32_16x16x32_bf16 v[50:53], v[218:221], v[172:175], v[50:53]
	v_mfma_f32_16x16x32_bf16 v[36:39], v[210:213], v[180:183], v[36:39]
	v_mfma_f32_16x16x32_bf16 v[32:35], v[218:221], v[180:183], v[32:35]
	v_mfma_f32_16x16x32_bf16 v[20:23], v[210:213], v[188:191], v[20:23]
	v_mfma_f32_16x16x32_bf16 v[16:19], v[218:221], v[188:191], v[16:19]
	v_mfma_f32_16x16x32_bf16 v[4:7], v[210:213], v[202:205], v[4:7]
	v_mfma_f32_16x16x32_bf16 v[0:3], v[218:221], v[202:205], v[0:3]
	s_setprio 0
	s_add_i32 s52, 0, 0x18000
	s_barrier
	ds_read_b128 v[150:153], v133 offset:32768
	ds_read_b128 v[156:159], v133 offset:33792
	ds_read_b128 v[160:163], v133 offset:34816
	ds_read_b128 v[164:167], v133 offset:35840
	s_add_u32 s34, s34, 0x40000
	s_addc_u32 s35, s35, 0
	s_mov_b32 m0, s44
	ds_read_b128 v[168:171], v155 offset:32768
	ds_read_b128 v[172:175], v155 offset:33792
	ds_read_b128 v[176:179], v155 offset:34816
	ds_read_b128 v[180:183], v155 offset:35840
	ds_read_b128 v[184:187], v155 offset:36864
	ds_read_b128 v[188:191], v155 offset:37888
	ds_read_b128 v[198:201], v155 offset:38912
	ds_read_b128 v[202:205], v155 offset:39936
	global_load_lds_dwordx4 v130, s[34:35]
	s_mov_b32 m0, s45
	s_nop 0
	global_load_lds_dwordx4 v134, s[34:35]
	s_waitcnt lgkmcnt(8)
	s_barrier
	s_waitcnt lgkmcnt(0)
	s_setprio 1
	s_waitcnt lgkmcnt(0)
	v_mfma_f32_16x16x32_bf16 v[126:129], v[150:153], v[168:171], v[126:129]
	v_mfma_f32_16x16x32_bf16 v[122:125], v[160:163], v[168:171], v[122:125]
	v_mfma_f32_16x16x32_bf16 v[110:113], v[150:153], v[176:179], v[110:113]
	v_mfma_f32_16x16x32_bf16 v[106:109], v[160:163], v[176:179], v[106:109]
	v_mfma_f32_16x16x32_bf16 v[94:97], v[150:153], v[184:187], v[94:97]
	v_mfma_f32_16x16x32_bf16 v[90:93], v[160:163], v[184:187], v[90:93]
	v_mfma_f32_16x16x32_bf16 v[78:81], v[150:153], v[198:201], v[78:81]
	v_mfma_f32_16x16x32_bf16 v[74:77], v[160:163], v[198:201], v[74:77]
	v_mfma_f32_16x16x32_bf16 v[126:129], v[156:159], v[172:175], v[126:129]
	v_mfma_f32_16x16x32_bf16 v[122:125], v[164:167], v[172:175], v[122:125]
	v_mfma_f32_16x16x32_bf16 v[110:113], v[156:159], v[180:183], v[110:113]
	v_mfma_f32_16x16x32_bf16 v[106:109], v[164:167], v[180:183], v[106:109]
	v_mfma_f32_16x16x32_bf16 v[94:97], v[156:159], v[188:191], v[94:97]
	v_mfma_f32_16x16x32_bf16 v[90:93], v[164:167], v[188:191], v[90:93]
	v_mfma_f32_16x16x32_bf16 v[78:81], v[156:159], v[202:205], v[78:81]
	v_mfma_f32_16x16x32_bf16 v[74:77], v[164:167], v[202:205], v[74:77]
	s_setprio 0
	s_barrier
	s_add_i32 s34, 0, 0x1c000
	s_add_i32 s35, s52, s41
	s_add_u32 s52, s30, s66
	s_addc_u32 s53, s31, s67
	s_mov_b32 m0, s35
	ds_read_b128 v[206:209], v133 offset:49152
	ds_read_b128 v[210:213], v133 offset:50176
	ds_read_b128 v[214:217], v133 offset:51200
	ds_read_b128 v[218:221], v133 offset:52224
	global_load_lds_dwordx4 v132, s[52:53]
	s_add_i32 m0, s35, 0x2000
	s_nop 0
	global_load_lds_dwordx4 v136, s[52:53]
	s_barrier
	s_waitcnt lgkmcnt(0)
	s_setprio 1
	s_waitcnt lgkmcnt(0)
	v_mfma_f32_16x16x32_bf16 v[118:121], v[206:209], v[168:171], v[118:121]
	v_mfma_f32_16x16x32_bf16 v[114:117], v[214:217], v[168:171], v[114:117]
	v_mfma_f32_16x16x32_bf16 v[102:105], v[206:209], v[176:179], v[102:105]
	v_mfma_f32_16x16x32_bf16 v[98:101], v[214:217], v[176:179], v[98:101]
	v_mfma_f32_16x16x32_bf16 v[86:89], v[206:209], v[184:187], v[86:89]
	v_mfma_f32_16x16x32_bf16 v[82:85], v[214:217], v[184:187], v[82:85]
	v_mfma_f32_16x16x32_bf16 v[70:73], v[206:209], v[198:201], v[70:73]
	v_mfma_f32_16x16x32_bf16 v[66:69], v[214:217], v[198:201], v[66:69]
	v_mfma_f32_16x16x32_bf16 v[118:121], v[210:213], v[172:175], v[118:121]
	v_mfma_f32_16x16x32_bf16 v[114:117], v[218:221], v[172:175], v[114:117]
	v_mfma_f32_16x16x32_bf16 v[102:105], v[210:213], v[180:183], v[102:105]
	v_mfma_f32_16x16x32_bf16 v[98:101], v[218:221], v[180:183], v[98:101]
	v_mfma_f32_16x16x32_bf16 v[86:89], v[210:213], v[188:191], v[86:89]
	v_mfma_f32_16x16x32_bf16 v[82:85], v[218:221], v[188:191], v[82:85]
	v_mfma_f32_16x16x32_bf16 v[70:73], v[210:213], v[202:205], v[70:73]
	v_mfma_f32_16x16x32_bf16 v[66:69], v[218:221], v[202:205], v[66:69]
	s_setprio 0
	s_mov_b32 m0, s46
	s_barrier
	ds_read_b128 v[168:171], v155 offset:49152
	ds_read_b128 v[172:175], v155 offset:50176
	ds_read_b128 v[176:179], v155 offset:51200
	ds_read_b128 v[180:183], v155 offset:52224
	ds_read_b128 v[184:187], v155 offset:53248
	ds_read_b128 v[188:191], v155 offset:54272
	ds_read_b128 v[198:201], v155 offset:55296
	ds_read_b128 v[202:205], v155 offset:56320
	global_load_lds_dwordx4 v130, s[58:59]
	s_mov_b32 m0, s47
	s_nop 0
	global_load_lds_dwordx4 v134, s[58:59]
	s_barrier
	s_waitcnt lgkmcnt(0)
	s_setprio 1
	s_waitcnt lgkmcnt(0)
	v_mfma_f32_16x16x32_bf16 v[62:65], v[150:153], v[168:171], v[62:65]
	v_mfma_f32_16x16x32_bf16 v[58:61], v[160:163], v[168:171], v[58:61]
	v_mfma_f32_16x16x32_bf16 v[44:47], v[150:153], v[176:179], v[44:47]
	v_mfma_f32_16x16x32_bf16 v[40:43], v[160:163], v[176:179], v[40:43]
	v_mfma_f32_16x16x32_bf16 v[28:31], v[150:153], v[184:187], v[28:31]
	v_mfma_f32_16x16x32_bf16 v[24:27], v[160:163], v[184:187], v[24:27]
	v_mfma_f32_16x16x32_bf16 v[12:15], v[150:153], v[198:201], v[12:15]
	v_mfma_f32_16x16x32_bf16 v[8:11], v[160:163], v[198:201], v[8:11]
	v_mfma_f32_16x16x32_bf16 v[62:65], v[156:159], v[172:175], v[62:65]
	v_mfma_f32_16x16x32_bf16 v[58:61], v[164:167], v[172:175], v[58:61]
	v_mfma_f32_16x16x32_bf16 v[44:47], v[156:159], v[180:183], v[44:47]
	v_mfma_f32_16x16x32_bf16 v[40:43], v[164:167], v[180:183], v[40:43]
	v_mfma_f32_16x16x32_bf16 v[28:31], v[156:159], v[188:191], v[28:31]
	v_mfma_f32_16x16x32_bf16 v[24:27], v[164:167], v[188:191], v[24:27]
	v_mfma_f32_16x16x32_bf16 v[12:15], v[156:159], v[202:205], v[12:15]
	v_mfma_f32_16x16x32_bf16 v[8:11], v[164:167], v[202:205], v[8:11]
	s_setprio 0
	s_barrier
	s_add_u32 s30, s30, 0x40080
	s_addc_u32 s31, s31, 0
	s_add_i32 s34, s34, s41
	s_mov_b32 m0, s34
	s_nop 0
	global_load_lds_dwordx4 v132, s[30:31]
	s_add_i32 m0, s34, 0x2000
	s_nop 0
	global_load_lds_dwordx4 v136, s[30:31]
	s_waitcnt vmcnt(6)
	s_barrier
	s_setprio 1
	v_mfma_f32_16x16x32_bf16 v[54:57], v[206:209], v[168:171], v[54:57]
	v_mfma_f32_16x16x32_bf16 v[50:53], v[214:217], v[168:171], v[50:53]
	v_mfma_f32_16x16x32_bf16 v[36:39], v[206:209], v[176:179], v[36:39]
	v_mfma_f32_16x16x32_bf16 v[32:35], v[214:217], v[176:179], v[32:35]
	v_mfma_f32_16x16x32_bf16 v[20:23], v[206:209], v[184:187], v[20:23]
	v_mfma_f32_16x16x32_bf16 v[16:19], v[214:217], v[184:187], v[16:19]
	v_mfma_f32_16x16x32_bf16 v[4:7], v[206:209], v[198:201], v[4:7]
	v_mfma_f32_16x16x32_bf16 v[0:3], v[214:217], v[198:201], v[0:3]
	v_mfma_f32_16x16x32_bf16 v[54:57], v[210:213], v[172:175], v[54:57]
	v_mfma_f32_16x16x32_bf16 v[50:53], v[218:221], v[172:175], v[50:53]
	v_mfma_f32_16x16x32_bf16 v[36:39], v[210:213], v[180:183], v[36:39]
	v_mfma_f32_16x16x32_bf16 v[32:35], v[218:221], v[180:183], v[32:35]
	v_mfma_f32_16x16x32_bf16 v[20:23], v[210:213], v[188:191], v[20:23]
	v_mfma_f32_16x16x32_bf16 v[16:19], v[218:221], v[188:191], v[16:19]
	v_mfma_f32_16x16x32_bf16 v[4:7], v[210:213], v[202:205], v[4:7]
	v_mfma_f32_16x16x32_bf16 v[0:3], v[218:221], v[202:205], v[0:3]
	s_setprio 0
	s_add_i32 s51, s51, 2
	s_add_u32 s4, s4, 0x100
	s_addc_u32 s5, s5, 0
	s_add_u32 s23, s23, 0x100
	s_addc_u32 s25, s25, 0
	s_cmp_gt_u32 s51, 13
	s_barrier
	s_cbranch_scc0 .LBB0_305
	v_lshl_add_u32 v156, s50, 8, v139
	v_ashrrev_i32_e32 v48, 31, v156
	v_alignbit_b32 v150, v48, v156, 6
	v_mad_u64_u32 v[150:151], s[4:5], v150, s71, 0
	v_mad_i32_i24 v151, v48, s71, v151
	v_lshlrev_b32_e32 v48, 3, v156
	s_cmp_lg_u32 s49, 0
	v_and_b32_e32 v48, 0x78, v48
	s_cselect_b64 s[30:31], -1, 0
	s_and_b64 vcc, exec, s[30:31]
	v_lshl_add_u32 v157, s49, 8, v145
	v_lshlrev_b32_e32 v48, 1, v48
	s_cbranch_vccz .LBB0_314
	v_ashrrev_i32_e32 v152, 3, v157
	v_ashrrev_i32_e32 v153, 31, v152
	v_lshl_add_u64 v[152:153], v[150:151], 0, v[152:153]
	v_lshlrev_b64 v[152:153], 10, v[152:153]
	v_lshl_add_u64 v[152:153], s[18:19], 0, v[152:153]
	v_lshl_add_u64 v[152:153], v[152:153], 0, v[48:49]
	v_ashrrev_i32_e32 v159, 5, v156
	v_add_u32_e32 v158, v159, v140
	s_cbranch_execnz .LBB0_309

.LBB0_641:
	s_add_u32 s24, s22, 0x100
	s_addc_u32 s25, s23, 0
	s_add_i32 s50, 0, 0x10000
	ds_read_b128 v[146:149], v131
	ds_read_b128 v[150:153], v131 offset:1024
	ds_read_b128 v[154:157], v131 offset:2048
	ds_read_b128 v[158:161], v131 offset:3072
	s_cmp_eq_u32 s49, 4
	s_cselect_b32 s29, s19, s25
	s_cselect_b32 s28, s18, s24
	s_cselect_b32 s27, s21, s48
	s_cselect_b32 s26, s20, s5
	v_lshl_add_u64 v[198:199], s[22:23], 0, v[138:139]
	s_add_i32 m0, s38, 0xc000
	ds_read_b128 v[162:165], v144
	ds_read_b128 v[166:169], v144 offset:1024
	ds_read_b128 v[170:173], v144 offset:2048
	ds_read_b128 v[174:177], v144 offset:3072
	ds_read_b128 v[178:181], v144 offset:4096
	ds_read_b128 v[182:185], v144 offset:5120
	ds_read_b128 v[186:189], v144 offset:6144
	ds_read_b128 v[190:193], v144 offset:7168
	global_load_lds_dwordx4 v[198:199], off
	v_lshl_add_u64 v[198:199], s[22:23], 0, v[140:141]
	s_add_i32 m0, s38, 0xe000
	s_nop 0
	global_load_lds_dwordx4 v[198:199], off
	s_waitcnt lgkmcnt(8)
	s_barrier
	s_waitcnt lgkmcnt(0)
	s_setprio 1
	s_waitcnt lgkmcnt(0)
	v_mfma_f32_16x16x32_bf16 v[126:129], v[146:149], v[162:165], v[126:129]
	v_mfma_f32_16x16x32_bf16 v[122:125], v[154:157], v[162:165], v[122:125]
	v_mfma_f32_16x16x32_bf16 v[118:121], v[146:149], v[170:173], v[118:121]
	v_mfma_f32_16x16x32_bf16 v[114:117], v[154:157], v[170:173], v[114:117]
	v_mfma_f32_16x16x32_bf16 v[106:109], v[146:149], v[178:181], v[106:109]
	v_mfma_f32_16x16x32_bf16 v[98:101], v[154:157], v[178:181], v[98:101]
	v_mfma_f32_16x16x32_bf16 v[90:93], v[146:149], v[186:189], v[90:93]
	v_mfma_f32_16x16x32_bf16 v[82:85], v[154:157], v[186:189], v[82:85]
	v_mfma_f32_16x16x32_bf16 v[126:129], v[150:153], v[166:169], v[126:129]
	v_mfma_f32_16x16x32_bf16 v[122:125], v[158:161], v[166:169], v[122:125]
	v_mfma_f32_16x16x32_bf16 v[118:121], v[150:153], v[174:177], v[118:121]
	v_mfma_f32_16x16x32_bf16 v[114:117], v[158:161], v[174:177], v[114:117]
	v_mfma_f32_16x16x32_bf16 v[106:109], v[150:153], v[182:185], v[106:109]
	v_mfma_f32_16x16x32_bf16 v[98:101], v[158:161], v[182:185], v[98:101]
	v_mfma_f32_16x16x32_bf16 v[90:93], v[150:153], v[190:193], v[90:93]
	v_mfma_f32_16x16x32_bf16 v[82:85], v[158:161], v[190:193], v[82:85]
	s_setprio 0
	s_barrier
	s_add_i32 s51, 0, 0x14000
	s_add_i32 s22, s50, s37
	s_mov_b32 m0, s22
	ds_read_b128 v[198:201], v131 offset:16384
	ds_read_b128 v[202:205], v131 offset:17408
	ds_read_b128 v[206:209], v131 offset:18432
	ds_read_b128 v[210:213], v131 offset:19456
	global_load_lds_dwordx4 v48, s[26:27]
	s_add_i32 m0, s22, 0x2000
	s_nop 0
	global_load_lds_dwordx4 v130, s[26:27]
	s_barrier
	s_waitcnt lgkmcnt(0)
	s_setprio 1
	s_waitcnt lgkmcnt(0)
	v_mfma_f32_16x16x32_bf16 v[110:113], v[198:201], v[162:165], v[110:113]
	v_mfma_f32_16x16x32_bf16 v[102:105], v[206:209], v[162:165], v[102:105]
	v_mfma_f32_16x16x32_bf16 v[94:97], v[198:201], v[170:173], v[94:97]
	v_mfma_f32_16x16x32_bf16 v[86:89], v[206:209], v[170:173], v[86:89]
	v_mfma_f32_16x16x32_bf16 v[78:81], v[198:201], v[178:181], v[78:81]
	v_mfma_f32_16x16x32_bf16 v[74:77], v[206:209], v[178:181], v[74:77]
	v_mfma_f32_16x16x32_bf16 v[70:73], v[198:201], v[186:189], v[70:73]
	v_mfma_f32_16x16x32_bf16 v[66:69], v[206:209], v[186:189], v[66:69]
	v_mfma_f32_16x16x32_bf16 v[110:113], v[202:205], v[166:169], v[110:113]
	v_mfma_f32_16x16x32_bf16 v[102:105], v[210:213], v[166:169], v[102:105]
	v_mfma_f32_16x16x32_bf16 v[94:97], v[202:205], v[174:177], v[94:97]
	v_mfma_f32_16x16x32_bf16 v[86:89], v[210:213], v[174:177], v[86:89]
	v_mfma_f32_16x16x32_bf16 v[78:81], v[202:205], v[182:185], v[78:81]
	v_mfma_f32_16x16x32_bf16 v[74:77], v[210:213], v[182:185], v[74:77]
	v_mfma_f32_16x16x32_bf16 v[70:73], v[202:205], v[190:193], v[70:73]
	v_mfma_f32_16x16x32_bf16 v[66:69], v[210:213], v[190:193], v[66:69]
	s_setprio 0
	s_mov_b32 m0, s38
	s_add_u32 s58, s28, s66
	s_addc_u32 s59, s29, s67
	s_barrier
	ds_read_b128 v[162:165], v144 offset:16384
	ds_read_b128 v[166:169], v144 offset:17408
	ds_read_b128 v[170:173], v144 offset:18432
	ds_read_b128 v[174:177], v144 offset:19456
	ds_read_b128 v[178:181], v144 offset:20480
	ds_read_b128 v[182:185], v144 offset:21504
	ds_read_b128 v[186:189], v144 offset:22528
	ds_read_b128 v[190:193], v144 offset:23552
	global_load_lds_dwordx4 v134, s[28:29]
	s_mov_b32 m0, s39
	s_nop 0
	global_load_lds_dwordx4 v132, s[28:29]
	s_barrier
	s_waitcnt lgkmcnt(0)
	s_setprio 1
	s_waitcnt lgkmcnt(0)
	v_mfma_f32_16x16x32_bf16 v[62:65], v[146:149], v[162:165], v[62:65]
	v_mfma_f32_16x16x32_bf16 v[58:61], v[154:157], v[162:165], v[58:61]
	v_mfma_f32_16x16x32_bf16 v[54:57], v[146:149], v[170:173], v[54:57]
	v_mfma_f32_16x16x32_bf16 v[50:53], v[154:157], v[170:173], v[50:53]
	v_mfma_f32_16x16x32_bf16 v[36:39], v[146:149], v[178:181], v[36:39]
	v_mfma_f32_16x16x32_bf16 v[32:35], v[154:157], v[178:181], v[32:35]
	v_mfma_f32_16x16x32_bf16 v[20:23], v[146:149], v[186:189], v[20:23]
	v_mfma_f32_16x16x32_bf16 v[16:19], v[154:157], v[186:189], v[16:19]
	v_mfma_f32_16x16x32_bf16 v[62:65], v[150:153], v[166:169], v[62:65]
	v_mfma_f32_16x16x32_bf16 v[58:61], v[158:161], v[166:169], v[58:61]
	v_mfma_f32_16x16x32_bf16 v[54:57], v[150:153], v[174:177], v[54:57]
	v_mfma_f32_16x16x32_bf16 v[50:53], v[158:161], v[174:177], v[50:53]
	v_mfma_f32_16x16x32_bf16 v[36:39], v[150:153], v[182:185], v[36:39]
	v_mfma_f32_16x16x32_bf16 v[32:35], v[158:161], v[182:185], v[32:35]
	v_mfma_f32_16x16x32_bf16 v[20:23], v[150:153], v[190:193], v[20:23]
	v_mfma_f32_16x16x32_bf16 v[16:19], v[158:161], v[190:193], v[16:19]
	s_setprio 0
	s_barrier
	s_add_u32 s22, s26, 0x20000
	s_addc_u32 s23, s27, 0
	s_add_i32 s50, s51, s37
	s_mov_b32 m0, s50
	s_nop 0
	global_load_lds_dwordx4 v48, s[22:23]
	s_add_i32 m0, s50, 0x2000
	s_nop 0
	global_load_lds_dwordx4 v130, s[22:23]
	s_waitcnt vmcnt(6)
	s_barrier
	s_setprio 1
	v_mfma_f32_16x16x32_bf16 v[44:47], v[198:201], v[162:165], v[44:47]
	v_mfma_f32_16x16x32_bf16 v[40:43], v[206:209], v[162:165], v[40:43]
	v_mfma_f32_16x16x32_bf16 v[28:31], v[198:201], v[170:173], v[28:31]
	v_mfma_f32_16x16x32_bf16 v[24:27], v[206:209], v[170:173], v[24:27]
	v_mfma_f32_16x16x32_bf16 v[12:15], v[198:201], v[178:181], v[12:15]
	v_mfma_f32_16x16x32_bf16 v[8:11], v[206:209], v[178:181], v[8:11]
	v_mfma_f32_16x16x32_bf16 v[4:7], v[198:201], v[186:189], v[4:7]
	v_mfma_f32_16x16x32_bf16 v[0:3], v[206:209], v[186:189], v[0:3]
	v_mfma_f32_16x16x32_bf16 v[44:47], v[202:205], v[166:169], v[44:47]
	v_mfma_f32_16x16x32_bf16 v[40:43], v[210:213], v[166:169], v[40:43]
	v_mfma_f32_16x16x32_bf16 v[28:31], v[202:205], v[174:177], v[28:31]
	v_mfma_f32_16x16x32_bf16 v[24:27], v[210:213], v[174:177], v[24:27]
	v_mfma_f32_16x16x32_bf16 v[12:15], v[202:205], v[182:185], v[12:15]
	v_mfma_f32_16x16x32_bf16 v[8:11], v[210:213], v[182:185], v[8:11]
	v_mfma_f32_16x16x32_bf16 v[4:7], v[202:205], v[190:193], v[4:7]
	v_mfma_f32_16x16x32_bf16 v[0:3], v[210:213], v[190:193], v[0:3]
	s_setprio 0
	s_add_i32 s50, 0, 0x18000
	s_barrier
	ds_read_b128 v[146:149], v131 offset:32768
	ds_read_b128 v[150:153], v131 offset:33792
	ds_read_b128 v[154:157], v131 offset:34816
	ds_read_b128 v[158:161], v131 offset:35840
	s_add_u32 s22, s28, 0x30000
	s_addc_u32 s23, s29, 0
	s_mov_b32 m0, s40
	ds_read_b128 v[162:165], v144 offset:32768
	ds_read_b128 v[166:169], v144 offset:33792
	ds_read_b128 v[170:173], v144 offset:34816
	ds_read_b128 v[174:177], v144 offset:35840
	ds_read_b128 v[178:181], v144 offset:36864
	ds_read_b128 v[182:185], v144 offset:37888
	ds_read_b128 v[186:189], v144 offset:38912
	ds_read_b128 v[190:193], v144 offset:39936
	global_load_lds_dwordx4 v134, s[22:23]
	s_mov_b32 m0, s41
	s_nop 0
	global_load_lds_dwordx4 v132, s[22:23]
	s_waitcnt lgkmcnt(8)
	s_barrier
	s_waitcnt lgkmcnt(0)
	s_setprio 1
	s_waitcnt lgkmcnt(0)
	v_mfma_f32_16x16x32_bf16 v[126:129], v[146:149], v[162:165], v[126:129]
	v_mfma_f32_16x16x32_bf16 v[122:125], v[154:157], v[162:165], v[122:125]
	v_mfma_f32_16x16x32_bf16 v[118:121], v[146:149], v[170:173], v[118:121]
	v_mfma_f32_16x16x32_bf16 v[114:117], v[154:157], v[170:173], v[114:117]
	v_mfma_f32_16x16x32_bf16 v[106:109], v[146:149], v[178:181], v[106:109]
	v_mfma_f32_16x16x32_bf16 v[98:101], v[154:157], v[178:181], v[98:101]
	v_mfma_f32_16x16x32_bf16 v[90:93], v[146:149], v[186:189], v[90:93]
	v_mfma_f32_16x16x32_bf16 v[82:85], v[154:157], v[186:189], v[82:85]
	v_mfma_f32_16x16x32_bf16 v[126:129], v[150:153], v[166:169], v[126:129]
	v_mfma_f32_16x16x32_bf16 v[122:125], v[158:161], v[166:169], v[122:125]
	v_mfma_f32_16x16x32_bf16 v[118:121], v[150:153], v[174:177], v[118:121]
	v_mfma_f32_16x16x32_bf16 v[114:117], v[158:161], v[174:177], v[114:117]
	v_mfma_f32_16x16x32_bf16 v[106:109], v[150:153], v[182:185], v[106:109]
	v_mfma_f32_16x16x32_bf16 v[98:101], v[158:161], v[182:185], v[98:101]
	v_mfma_f32_16x16x32_bf16 v[90:93], v[150:153], v[190:193], v[90:93]
	v_mfma_f32_16x16x32_bf16 v[82:85], v[158:161], v[190:193], v[82:85]
	s_setprio 0
	s_barrier
	s_add_i32 s28, 0, 0x1c000
	s_add_i32 s22, s50, s37
	s_add_u32 s52, s26, s66
	s_addc_u32 s53, s27, s67
	s_mov_b32 m0, s22
	ds_read_b128 v[198:201], v131 offset:49152
	ds_read_b128 v[202:205], v131 offset:50176
	ds_read_b128 v[206:209], v131 offset:51200
	ds_read_b128 v[210:213], v131 offset:52224
	global_load_lds_dwordx4 v48, s[52:53]
	s_add_i32 m0, s22, 0x2000
	s_nop 0
	global_load_lds_dwordx4 v130, s[52:53]
	s_barrier
	s_waitcnt lgkmcnt(0)
	s_setprio 1
	s_waitcnt lgkmcnt(0)
	v_mfma_f32_16x16x32_bf16 v[110:113], v[198:201], v[162:165], v[110:113]
	v_mfma_f32_16x16x32_bf16 v[102:105], v[206:209], v[162:165], v[102:105]
	v_mfma_f32_16x16x32_bf16 v[94:97], v[198:201], v[170:173], v[94:97]
	v_mfma_f32_16x16x32_bf16 v[86:89], v[206:209], v[170:173], v[86:89]
	v_mfma_f32_16x16x32_bf16 v[78:81], v[198:201], v[178:181], v[78:81]
	v_mfma_f32_16x16x32_bf16 v[74:77], v[206:209], v[178:181], v[74:77]
	v_mfma_f32_16x16x32_bf16 v[70:73], v[198:201], v[186:189], v[70:73]
	v_mfma_f32_16x16x32_bf16 v[66:69], v[206:209], v[186:189], v[66:69]
	v_mfma_f32_16x16x32_bf16 v[110:113], v[202:205], v[166:169], v[110:113]
	v_mfma_f32_16x16x32_bf16 v[102:105], v[210:213], v[166:169], v[102:105]
	v_mfma_f32_16x16x32_bf16 v[94:97], v[202:205], v[174:177], v[94:97]
	v_mfma_f32_16x16x32_bf16 v[86:89], v[210:213], v[174:177], v[86:89]
	v_mfma_f32_16x16x32_bf16 v[78:81], v[202:205], v[182:185], v[78:81]
	v_mfma_f32_16x16x32_bf16 v[74:77], v[210:213], v[182:185], v[74:77]
	v_mfma_f32_16x16x32_bf16 v[70:73], v[202:205], v[190:193], v[70:73]
	v_mfma_f32_16x16x32_bf16 v[66:69], v[210:213], v[190:193], v[66:69]
	s_setprio 0
	s_mov_b32 m0, s42
	s_barrier
	ds_read_b128 v[162:165], v144 offset:49152
	ds_read_b128 v[166:169], v144 offset:50176
	ds_read_b128 v[170:173], v144 offset:51200
	ds_read_b128 v[174:177], v144 offset:52224
	ds_read_b128 v[178:181], v144 offset:53248
	ds_read_b128 v[182:185], v144 offset:54272
	ds_read_b128 v[186:189], v144 offset:55296
	ds_read_b128 v[190:193], v144 offset:56320
	global_load_lds_dwordx4 v134, s[58:59]
	s_mov_b32 m0, s43
	s_nop 0
	global_load_lds_dwordx4 v132, s[58:59]
	s_barrier
	s_waitcnt lgkmcnt(0)
	s_setprio 1
	s_waitcnt lgkmcnt(0)
	v_mfma_f32_16x16x32_bf16 v[62:65], v[146:149], v[162:165], v[62:65]
	v_mfma_f32_16x16x32_bf16 v[58:61], v[154:157], v[162:165], v[58:61]
	v_mfma_f32_16x16x32_bf16 v[54:57], v[146:149], v[170:173], v[54:57]
	v_mfma_f32_16x16x32_bf16 v[50:53], v[154:157], v[170:173], v[50:53]
	v_mfma_f32_16x16x32_bf16 v[36:39], v[146:149], v[178:181], v[36:39]
	v_mfma_f32_16x16x32_bf16 v[32:35], v[154:157], v[178:181], v[32:35]
	v_mfma_f32_16x16x32_bf16 v[20:23], v[146:149], v[186:189], v[20:23]
	v_mfma_f32_16x16x32_bf16 v[16:19], v[154:157], v[186:189], v[16:19]
	v_mfma_f32_16x16x32_bf16 v[62:65], v[150:153], v[166:169], v[62:65]
	v_mfma_f32_16x16x32_bf16 v[58:61], v[158:161], v[166:169], v[58:61]
	v_mfma_f32_16x16x32_bf16 v[54:57], v[150:153], v[174:177], v[54:57]
	v_mfma_f32_16x16x32_bf16 v[50:53], v[158:161], v[174:177], v[50:53]
	v_mfma_f32_16x16x32_bf16 v[36:39], v[150:153], v[182:185], v[36:39]
	v_mfma_f32_16x16x32_bf16 v[32:35], v[158:161], v[182:185], v[32:35]
	v_mfma_f32_16x16x32_bf16 v[20:23], v[150:153], v[190:193], v[20:23]
	v_mfma_f32_16x16x32_bf16 v[16:19], v[158:161], v[190:193], v[16:19]
	s_setprio 0
	s_barrier
	s_add_u32 s22, s26, 0x20080
	s_addc_u32 s23, s27, 0
	s_add_i32 s26, s28, s37
	s_mov_b32 m0, s26
	s_nop 0
	global_load_lds_dwordx4 v48, s[22:23]
	s_add_i32 m0, s26, 0x2000
	s_nop 0
	global_load_lds_dwordx4 v130, s[22:23]
	s_waitcnt vmcnt(6)
	s_barrier
	s_setprio 1
	v_mfma_f32_16x16x32_bf16 v[44:47], v[198:201], v[162:165], v[44:47]
	v_mfma_f32_16x16x32_bf16 v[40:43], v[206:209], v[162:165], v[40:43]
	v_mfma_f32_16x16x32_bf16 v[28:31], v[198:201], v[170:173], v[28:31]
	v_mfma_f32_16x16x32_bf16 v[24:27], v[206:209], v[170:173], v[24:27]
	v_mfma_f32_16x16x32_bf16 v[12:15], v[198:201], v[178:181], v[12:15]
	v_mfma_f32_16x16x32_bf16 v[8:11], v[206:209], v[178:181], v[8:11]
	v_mfma_f32_16x16x32_bf16 v[4:7], v[198:201], v[186:189], v[4:7]
	v_mfma_f32_16x16x32_bf16 v[0:3], v[206:209], v[186:189], v[0:3]
	v_mfma_f32_16x16x32_bf16 v[44:47], v[202:205], v[166:169], v[44:47]
	v_mfma_f32_16x16x32_bf16 v[40:43], v[210:213], v[166:169], v[40:43]
	v_mfma_f32_16x16x32_bf16 v[28:31], v[202:205], v[174:177], v[28:31]
	v_mfma_f32_16x16x32_bf16 v[24:27], v[210:213], v[174:177], v[24:27]
	v_mfma_f32_16x16x32_bf16 v[12:15], v[202:205], v[182:185], v[12:15]
	v_mfma_f32_16x16x32_bf16 v[8:11], v[210:213], v[182:185], v[8:11]
	v_mfma_f32_16x16x32_bf16 v[4:7], v[202:205], v[190:193], v[4:7]
	v_mfma_f32_16x16x32_bf16 v[0:3], v[210:213], v[190:193], v[0:3]
	s_setprio 0
	s_add_i32 s49, s49, 2
	s_add_u32 s5, s5, 0x100
	s_addc_u32 s48, s48, 0
	s_cmp_gt_u32 s49, 5
	s_mov_b64 s[22:23], s[24:25]
	s_barrier
	s_cbranch_scc0 .LBB0_641
	v_lshl_add_u32 v146, s47, 8, v142
	v_mov_b32_e32 v145, 0x240000
	v_ashrrev_i32_e32 v147, 31, v146
	v_mad_i64_i32 v[148:149], s[22:23], s46, v145, v[136:137]
	v_lshlrev_b64 v[150:151], 10, v[146:147]
	v_lshl_add_u64 v[150:151], v[148:149], 0, v[150:151]
	global_store_dwordx4 v[150:151], v[126:129], off
	global_store_dwordx4 v[150:151], v[122:125], off offset:64
	global_store_dwordx4 v[150:151], v[110:113], off offset:512
	global_store_dwordx4 v[150:151], v[102:105], off offset:576
	s_mov_b32 s5, 0x20000
	s_mov_b64 s[22:23], 0x20000
	v_or_b32_e32 v102, 16, v146
	v_ashrrev_i32_e32 v103, 31, v102
	v_lshlrev_b64 v[102:103], 10, v[102:103]
	v_lshl_add_u64 v[102:103], v[148:149], 0, v[102:103]
	global_store_dwordx4 v[102:103], v[118:121], off
	global_store_dwordx4 v[102:103], v[114:117], off offset:64
	global_store_dwordx4 v[102:103], v[94:97], off offset:512
	global_store_dwordx4 v[102:103], v[86:89], off offset:576
	s_mov_b32 s46, s4
	s_mov_b32 s47, s45
	v_or_b32_e32 v86, 32, v146
	v_ashrrev_i32_e32 v87, 31, v86
	v_lshlrev_b64 v[86:87], 10, v[86:87]
	v_lshl_add_u64 v[86:87], v[148:149], 0, v[86:87]
	global_store_dwordx4 v[86:87], v[106:109], off
	global_store_dwordx4 v[86:87], v[98:101], off offset:64
	global_store_dwordx4 v[86:87], v[78:81], off offset:512
	global_store_dwordx4 v[86:87], v[74:77], off offset:576
	s_mov_b64 s[24:25], s[20:21]
	s_nop 0
	v_or_b32_e32 v74, 48, v146
	v_ashrrev_i32_e32 v75, 31, v74
	v_lshlrev_b64 v[74:75], 10, v[74:75]
	v_lshl_add_u64 v[74:75], v[148:149], 0, v[74:75]
	global_store_dwordx4 v[74:75], v[90:93], off
	global_store_dwordx4 v[74:75], v[82:85], off offset:64
	global_store_dwordx4 v[74:75], v[70:73], off offset:512
	global_store_dwordx4 v[74:75], v[66:69], off offset:576
	s_nop 1
	v_add_co_u32_e32 v68, vcc, s5, v150
	s_mov_b32 s5, 0x24000
	s_nop 0
	v_addc_co_u32_e32 v69, vcc, 0, v151, vcc
	v_lshl_add_u64 v[66:67], v[150:151], 0, s[22:23]
	global_store_dwordx4 v[68:69], v[62:65], off
	global_store_dwordx4 v[66:67], v[58:61], off offset:64
	global_store_dwordx4 v[66:67], v[44:47], off offset:512
	global_store_dwordx4 v[66:67], v[40:43], off offset:576
	s_mov_b64 s[22:23], 0x24000
	s_nop 0
	v_add_co_u32_e32 v42, vcc, s5, v150
	s_mov_b32 s5, 0x28000
	s_nop 0
	v_addc_co_u32_e32 v43, vcc, 0, v151, vcc
	v_lshl_add_u64 v[40:41], v[150:151], 0, s[22:23]
	global_store_dwordx4 v[42:43], v[54:57], off
	global_store_dwordx4 v[40:41], v[50:53], off offset:64
	global_store_dwordx4 v[40:41], v[28:31], off offset:512
	global_store_dwordx4 v[40:41], v[24:27], off offset:576
	s_mov_b64 s[22:23], 0x28000
	s_nop 0
	v_add_co_u32_e32 v26, vcc, s5, v150
	v_lshl_add_u64 v[24:25], v[150:151], 0, s[22:23]
	s_nop 0
	v_addc_co_u32_e32 v27, vcc, 0, v151, vcc
	global_store_dwordx4 v[26:27], v[36:39], off
	global_store_dwordx4 v[24:25], v[32:35], off offset:64
	global_store_dwordx4 v[24:25], v[12:15], off offset:512
	global_store_dwordx4 v[24:25], v[8:11], off offset:576
	s_mov_b64 s[22:23], 0x2c000
	s_nop 0
	v_add_co_u32_e32 v10, vcc, 0x2c000, v150
	v_lshl_add_u64 v[8:9], v[150:151], 0, s[22:23]
	s_nop 0
	v_addc_co_u32_e32 v11, vcc, 0, v151, vcc
	s_and_b64 vcc, exec, s[0:1]
	s_mov_b64 s[22:23], s[18:19]
	global_store_dwordx4 v[10:11], v[20:23], off
	global_store_dwordx4 v[8:9], v[16:19], off offset:64
	global_store_dwordx4 v[8:9], v[4:7], off offset:512
	global_store_dwordx4 v[8:9], v[0:3], off offset:576
	s_cbranch_vccz .LBB0_638
	s_waitcnt vmcnt(0)
	s_cmpk_gt_u32 s30, 0xff
	s_cbranch_scc1 .LBB0_645
	s_barrier

.LBB0_822:
	s_add_u32 s12, s10, 0x100
	s_addc_u32 s13, s11, 0
	s_add_i32 s42, 0, 0x10000
	ds_read_b128 v[142:145], v131
	ds_read_b128 v[150:153], v131 offset:1024
	ds_read_b128 v[154:157], v131 offset:2048
	ds_read_b128 v[158:161], v131 offset:3072
	s_cmp_eq_u32 s41, 8
	s_cselect_b32 s17, s5, s13
	s_cselect_b32 s16, s4, s12
	s_cselect_b32 s15, s7, s40
	s_cselect_b32 s14, s6, s39
	v_lshl_add_u64 v[198:199], s[10:11], 0, v[138:139]
	s_add_i32 m0, s24, 0xc000
	ds_read_b128 v[162:165], v149
	ds_read_b128 v[166:169], v149 offset:1024
	ds_read_b128 v[170:173], v149 offset:2048
	ds_read_b128 v[174:177], v149 offset:3072
	ds_read_b128 v[178:181], v149 offset:4096
	ds_read_b128 v[182:185], v149 offset:5120
	ds_read_b128 v[186:189], v149 offset:6144
	ds_read_b128 v[190:193], v149 offset:7168
	global_load_lds_dwordx4 v[198:199], off
	v_lshl_add_u64 v[198:199], s[10:11], 0, v[140:141]
	s_add_i32 m0, s24, 0xe000
	s_nop 0
	global_load_lds_dwordx4 v[198:199], off
	s_waitcnt lgkmcnt(8)
	s_barrier
	s_waitcnt lgkmcnt(0)
	s_setprio 1
	s_waitcnt lgkmcnt(0)
	v_mfma_f32_16x16x32_bf16 v[126:129], v[142:145], v[162:165], v[126:129]
	v_mfma_f32_16x16x32_bf16 v[122:125], v[154:157], v[162:165], v[122:125]
	v_mfma_f32_16x16x32_bf16 v[110:113], v[142:145], v[170:173], v[110:113]
	v_mfma_f32_16x16x32_bf16 v[106:109], v[154:157], v[170:173], v[106:109]
	v_mfma_f32_16x16x32_bf16 v[94:97], v[142:145], v[178:181], v[94:97]
	v_mfma_f32_16x16x32_bf16 v[90:93], v[154:157], v[178:181], v[90:93]
	v_mfma_f32_16x16x32_bf16 v[78:81], v[142:145], v[186:189], v[78:81]
	v_mfma_f32_16x16x32_bf16 v[74:77], v[154:157], v[186:189], v[74:77]
	v_mfma_f32_16x16x32_bf16 v[126:129], v[150:153], v[166:169], v[126:129]
	v_mfma_f32_16x16x32_bf16 v[122:125], v[158:161], v[166:169], v[122:125]
	v_mfma_f32_16x16x32_bf16 v[110:113], v[150:153], v[174:177], v[110:113]
	v_mfma_f32_16x16x32_bf16 v[106:109], v[158:161], v[174:177], v[106:109]
	v_mfma_f32_16x16x32_bf16 v[94:97], v[150:153], v[182:185], v[94:97]
	v_mfma_f32_16x16x32_bf16 v[90:93], v[158:161], v[182:185], v[90:93]
	v_mfma_f32_16x16x32_bf16 v[78:81], v[150:153], v[190:193], v[78:81]
	v_mfma_f32_16x16x32_bf16 v[74:77], v[158:161], v[190:193], v[74:77]
	s_setprio 0
	s_barrier
	s_add_i32 s43, 0, 0x14000
	s_add_i32 s10, s42, s23
	s_mov_b32 m0, s10
	ds_read_b128 v[198:201], v131 offset:16384
	ds_read_b128 v[202:205], v131 offset:17408
	ds_read_b128 v[206:209], v131 offset:18432
	ds_read_b128 v[210:213], v131 offset:19456
	global_load_lds_dwordx4 v134, s[14:15]
	s_add_i32 m0, s10, 0x2000
	s_nop 0
	global_load_lds_dwordx4 v130, s[14:15]
	s_barrier
	s_waitcnt lgkmcnt(0)
	s_setprio 1
	s_waitcnt lgkmcnt(0)
	v_mfma_f32_16x16x32_bf16 v[118:121], v[198:201], v[162:165], v[118:121]
	v_mfma_f32_16x16x32_bf16 v[114:117], v[206:209], v[162:165], v[114:117]
	v_mfma_f32_16x16x32_bf16 v[102:105], v[198:201], v[170:173], v[102:105]
	v_mfma_f32_16x16x32_bf16 v[98:101], v[206:209], v[170:173], v[98:101]
	v_mfma_f32_16x16x32_bf16 v[86:89], v[198:201], v[178:181], v[86:89]
	v_mfma_f32_16x16x32_bf16 v[82:85], v[206:209], v[178:181], v[82:85]
	v_mfma_f32_16x16x32_bf16 v[70:73], v[198:201], v[186:189], v[70:73]
	v_mfma_f32_16x16x32_bf16 v[66:69], v[206:209], v[186:189], v[66:69]
	v_mfma_f32_16x16x32_bf16 v[118:121], v[202:205], v[166:169], v[118:121]
	v_mfma_f32_16x16x32_bf16 v[114:117], v[210:213], v[166:169], v[114:117]
	v_mfma_f32_16x16x32_bf16 v[102:105], v[202:205], v[174:177], v[102:105]
	v_mfma_f32_16x16x32_bf16 v[98:101], v[210:213], v[174:177], v[98:101]
	v_mfma_f32_16x16x32_bf16 v[86:89], v[202:205], v[182:185], v[86:89]
	v_mfma_f32_16x16x32_bf16 v[82:85], v[210:213], v[182:185], v[82:85]
	v_mfma_f32_16x16x32_bf16 v[70:73], v[202:205], v[190:193], v[70:73]
	v_mfma_f32_16x16x32_bf16 v[66:69], v[210:213], v[190:193], v[66:69]
	s_setprio 0
	s_mov_b32 m0, s24
	s_add_u32 s84, s16, s66
	s_addc_u32 s85, s17, s67
	s_barrier
	ds_read_b128 v[162:165], v149 offset:16384
	ds_read_b128 v[166:169], v149 offset:17408
	ds_read_b128 v[170:173], v149 offset:18432
	ds_read_b128 v[174:177], v149 offset:19456
	ds_read_b128 v[178:181], v149 offset:20480
	ds_read_b128 v[182:185], v149 offset:21504
	ds_read_b128 v[186:189], v149 offset:22528
	ds_read_b128 v[190:193], v149 offset:23552
	global_load_lds_dwordx4 v136, s[16:17]
	s_mov_b32 m0, s25
	s_nop 0
	global_load_lds_dwordx4 v132, s[16:17]
	s_barrier
	s_waitcnt lgkmcnt(0)
	s_setprio 1
	s_waitcnt lgkmcnt(0)
	v_mfma_f32_16x16x32_bf16 v[62:65], v[142:145], v[162:165], v[62:65]
	v_mfma_f32_16x16x32_bf16 v[58:61], v[154:157], v[162:165], v[58:61]
	v_mfma_f32_16x16x32_bf16 v[44:47], v[142:145], v[170:173], v[44:47]
	v_mfma_f32_16x16x32_bf16 v[40:43], v[154:157], v[170:173], v[40:43]
	v_mfma_f32_16x16x32_bf16 v[28:31], v[142:145], v[178:181], v[28:31]
	v_mfma_f32_16x16x32_bf16 v[24:27], v[154:157], v[178:181], v[24:27]
	v_mfma_f32_16x16x32_bf16 v[12:15], v[142:145], v[186:189], v[12:15]
	v_mfma_f32_16x16x32_bf16 v[8:11], v[154:157], v[186:189], v[8:11]
	v_mfma_f32_16x16x32_bf16 v[62:65], v[150:153], v[166:169], v[62:65]
	v_mfma_f32_16x16x32_bf16 v[58:61], v[158:161], v[166:169], v[58:61]
	v_mfma_f32_16x16x32_bf16 v[44:47], v[150:153], v[174:177], v[44:47]
	v_mfma_f32_16x16x32_bf16 v[40:43], v[158:161], v[174:177], v[40:43]
	v_mfma_f32_16x16x32_bf16 v[28:31], v[150:153], v[182:185], v[28:31]
	v_mfma_f32_16x16x32_bf16 v[24:27], v[158:161], v[182:185], v[24:27]
	v_mfma_f32_16x16x32_bf16 v[12:15], v[150:153], v[190:193], v[12:15]
	v_mfma_f32_16x16x32_bf16 v[8:11], v[158:161], v[190:193], v[8:11]
	s_setprio 0
	s_barrier
	s_add_u32 s10, s14, 0x30000
	s_addc_u32 s11, s15, 0
	s_add_i32 s42, s43, s23
	s_mov_b32 m0, s42
	s_nop 0
	global_load_lds_dwordx4 v134, s[10:11]
	s_add_i32 m0, s42, 0x2000
	s_nop 0
	global_load_lds_dwordx4 v130, s[10:11]
	s_waitcnt vmcnt(6)
	s_barrier
	s_setprio 1
	v_mfma_f32_16x16x32_bf16 v[54:57], v[198:201], v[162:165], v[54:57]
	v_mfma_f32_16x16x32_bf16 v[50:53], v[206:209], v[162:165], v[50:53]
	v_mfma_f32_16x16x32_bf16 v[36:39], v[198:201], v[170:173], v[36:39]
	v_mfma_f32_16x16x32_bf16 v[32:35], v[206:209], v[170:173], v[32:35]
	v_mfma_f32_16x16x32_bf16 v[20:23], v[198:201], v[178:181], v[20:23]
	v_mfma_f32_16x16x32_bf16 v[16:19], v[206:209], v[178:181], v[16:19]
	v_mfma_f32_16x16x32_bf16 v[4:7], v[198:201], v[186:189], v[4:7]
	v_mfma_f32_16x16x32_bf16 v[0:3], v[206:209], v[186:189], v[0:3]
	v_mfma_f32_16x16x32_bf16 v[54:57], v[202:205], v[166:169], v[54:57]
	v_mfma_f32_16x16x32_bf16 v[50:53], v[210:213], v[166:169], v[50:53]
	v_mfma_f32_16x16x32_bf16 v[36:39], v[202:205], v[174:177], v[36:39]
	v_mfma_f32_16x16x32_bf16 v[32:35], v[210:213], v[174:177], v[32:35]
	v_mfma_f32_16x16x32_bf16 v[20:23], v[202:205], v[182:185], v[20:23]
	v_mfma_f32_16x16x32_bf16 v[16:19], v[210:213], v[182:185], v[16:19]
	v_mfma_f32_16x16x32_bf16 v[4:7], v[202:205], v[190:193], v[4:7]
	v_mfma_f32_16x16x32_bf16 v[0:3], v[210:213], v[190:193], v[0:3]
	s_setprio 0
	s_add_i32 s42, 0, 0x18000
	s_barrier
	ds_read_b128 v[142:145], v131 offset:32768
	ds_read_b128 v[150:153], v131 offset:33792
	ds_read_b128 v[154:157], v131 offset:34816
	ds_read_b128 v[158:161], v131 offset:35840
	s_add_u32 s10, s16, 0x30000
	s_addc_u32 s11, s17, 0
	s_mov_b32 m0, s26
	ds_read_b128 v[162:165], v149 offset:32768
	ds_read_b128 v[166:169], v149 offset:33792
	ds_read_b128 v[170:173], v149 offset:34816
	ds_read_b128 v[174:177], v149 offset:35840
	ds_read_b128 v[178:181], v149 offset:36864
	ds_read_b128 v[182:185], v149 offset:37888
	ds_read_b128 v[186:189], v149 offset:38912
	ds_read_b128 v[190:193], v149 offset:39936
	global_load_lds_dwordx4 v136, s[10:11]
	s_mov_b32 m0, s27
	s_nop 0
	global_load_lds_dwordx4 v132, s[10:11]
	s_waitcnt lgkmcnt(8)
	s_barrier
	s_waitcnt lgkmcnt(0)
	s_setprio 1
	s_waitcnt lgkmcnt(0)
	v_mfma_f32_16x16x32_bf16 v[126:129], v[142:145], v[162:165], v[126:129]
	v_mfma_f32_16x16x32_bf16 v[122:125], v[154:157], v[162:165], v[122:125]
	v_mfma_f32_16x16x32_bf16 v[110:113], v[142:145], v[170:173], v[110:113]
	v_mfma_f32_16x16x32_bf16 v[106:109], v[154:157], v[170:173], v[106:109]
	v_mfma_f32_16x16x32_bf16 v[94:97], v[142:145], v[178:181], v[94:97]
	v_mfma_f32_16x16x32_bf16 v[90:93], v[154:157], v[178:181], v[90:93]
	v_mfma_f32_16x16x32_bf16 v[78:81], v[142:145], v[186:189], v[78:81]
	v_mfma_f32_16x16x32_bf16 v[74:77], v[154:157], v[186:189], v[74:77]
	v_mfma_f32_16x16x32_bf16 v[126:129], v[150:153], v[166:169], v[126:129]
	v_mfma_f32_16x16x32_bf16 v[122:125], v[158:161], v[166:169], v[122:125]
	v_mfma_f32_16x16x32_bf16 v[110:113], v[150:153], v[174:177], v[110:113]
	v_mfma_f32_16x16x32_bf16 v[106:109], v[158:161], v[174:177], v[106:109]
	v_mfma_f32_16x16x32_bf16 v[94:97], v[150:153], v[182:185], v[94:97]
	v_mfma_f32_16x16x32_bf16 v[90:93], v[158:161], v[182:185], v[90:93]
	v_mfma_f32_16x16x32_bf16 v[78:81], v[150:153], v[190:193], v[78:81]
	v_mfma_f32_16x16x32_bf16 v[74:77], v[158:161], v[190:193], v[74:77]
	s_setprio 0
	s_barrier
	s_add_i32 s16, 0, 0x1c000
	s_add_i32 s10, s42, s23
	s_add_u32 s72, s14, s66
	s_addc_u32 s73, s15, s67
	s_mov_b32 m0, s10
	ds_read_b128 v[198:201], v131 offset:49152
	ds_read_b128 v[202:205], v131 offset:50176
	ds_read_b128 v[206:209], v131 offset:51200
	ds_read_b128 v[210:213], v131 offset:52224
	global_load_lds_dwordx4 v134, s[72:73]
	s_add_i32 m0, s10, 0x2000
	s_nop 0
	global_load_lds_dwordx4 v130, s[72:73]
	s_barrier
	s_waitcnt lgkmcnt(0)
	s_setprio 1
	s_waitcnt lgkmcnt(0)
	v_mfma_f32_16x16x32_bf16 v[118:121], v[198:201], v[162:165], v[118:121]
	v_mfma_f32_16x16x32_bf16 v[114:117], v[206:209], v[162:165], v[114:117]
	v_mfma_f32_16x16x32_bf16 v[102:105], v[198:201], v[170:173], v[102:105]
	v_mfma_f32_16x16x32_bf16 v[98:101], v[206:209], v[170:173], v[98:101]
	v_mfma_f32_16x16x32_bf16 v[86:89], v[198:201], v[178:181], v[86:89]
	v_mfma_f32_16x16x32_bf16 v[82:85], v[206:209], v[178:181], v[82:85]
	v_mfma_f32_16x16x32_bf16 v[70:73], v[198:201], v[186:189], v[70:73]
	v_mfma_f32_16x16x32_bf16 v[66:69], v[206:209], v[186:189], v[66:69]
	v_mfma_f32_16x16x32_bf16 v[118:121], v[202:205], v[166:169], v[118:121]
	v_mfma_f32_16x16x32_bf16 v[114:117], v[210:213], v[166:169], v[114:117]
	v_mfma_f32_16x16x32_bf16 v[102:105], v[202:205], v[174:177], v[102:105]
	v_mfma_f32_16x16x32_bf16 v[98:101], v[210:213], v[174:177], v[98:101]
	v_mfma_f32_16x16x32_bf16 v[86:89], v[202:205], v[182:185], v[86:89]
	v_mfma_f32_16x16x32_bf16 v[82:85], v[210:213], v[182:185], v[82:85]
	v_mfma_f32_16x16x32_bf16 v[70:73], v[202:205], v[190:193], v[70:73]
	v_mfma_f32_16x16x32_bf16 v[66:69], v[210:213], v[190:193], v[66:69]
	s_setprio 0
	s_mov_b32 m0, s28
	s_barrier
	ds_read_b128 v[162:165], v149 offset:49152
	ds_read_b128 v[166:169], v149 offset:50176
	ds_read_b128 v[170:173], v149 offset:51200
	ds_read_b128 v[174:177], v149 offset:52224
	ds_read_b128 v[178:181], v149 offset:53248
	ds_read_b128 v[182:185], v149 offset:54272
	ds_read_b128 v[186:189], v149 offset:55296
	ds_read_b128 v[190:193], v149 offset:56320
	global_load_lds_dwordx4 v136, s[84:85]
	s_mov_b32 m0, s29
	s_nop 0
	global_load_lds_dwordx4 v132, s[84:85]
	s_barrier
	s_waitcnt lgkmcnt(0)
	s_setprio 1
	s_waitcnt lgkmcnt(0)
	v_mfma_f32_16x16x32_bf16 v[62:65], v[142:145], v[162:165], v[62:65]
	v_mfma_f32_16x16x32_bf16 v[58:61], v[154:157], v[162:165], v[58:61]
	v_mfma_f32_16x16x32_bf16 v[44:47], v[142:145], v[170:173], v[44:47]
	v_mfma_f32_16x16x32_bf16 v[40:43], v[154:157], v[170:173], v[40:43]
	v_mfma_f32_16x16x32_bf16 v[28:31], v[142:145], v[178:181], v[28:31]
	v_mfma_f32_16x16x32_bf16 v[24:27], v[154:157], v[178:181], v[24:27]
	v_mfma_f32_16x16x32_bf16 v[12:15], v[142:145], v[186:189], v[12:15]
	v_mfma_f32_16x16x32_bf16 v[8:11], v[154:157], v[186:189], v[8:11]
	v_mfma_f32_16x16x32_bf16 v[62:65], v[150:153], v[166:169], v[62:65]
	v_mfma_f32_16x16x32_bf16 v[58:61], v[158:161], v[166:169], v[58:61]
	v_mfma_f32_16x16x32_bf16 v[44:47], v[150:153], v[174:177], v[44:47]
	v_mfma_f32_16x16x32_bf16 v[40:43], v[158:161], v[174:177], v[40:43]
	v_mfma_f32_16x16x32_bf16 v[28:31], v[150:153], v[182:185], v[28:31]
	v_mfma_f32_16x16x32_bf16 v[24:27], v[158:161], v[182:185], v[24:27]
	v_mfma_f32_16x16x32_bf16 v[12:15], v[150:153], v[190:193], v[12:15]
	v_mfma_f32_16x16x32_bf16 v[8:11], v[158:161], v[190:193], v[8:11]
	s_setprio 0
	s_barrier
	s_add_u32 s10, s14, 0x30080
	s_addc_u32 s11, s15, 0
	s_add_i32 s14, s16, s23
	s_mov_b32 m0, s14
	s_nop 0
	global_load_lds_dwordx4 v134, s[10:11]
	s_add_i32 m0, s14, 0x2000
	s_nop 0
	global_load_lds_dwordx4 v130, s[10:11]
	s_waitcnt vmcnt(6)
	s_barrier
	s_setprio 1
	v_mfma_f32_16x16x32_bf16 v[54:57], v[198:201], v[162:165], v[54:57]
	v_mfma_f32_16x16x32_bf16 v[50:53], v[206:209], v[162:165], v[50:53]
	v_mfma_f32_16x16x32_bf16 v[36:39], v[198:201], v[170:173], v[36:39]
	v_mfma_f32_16x16x32_bf16 v[32:35], v[206:209], v[170:173], v[32:35]
	v_mfma_f32_16x16x32_bf16 v[20:23], v[198:201], v[178:181], v[20:23]
	v_mfma_f32_16x16x32_bf16 v[16:19], v[206:209], v[178:181], v[16:19]
	v_mfma_f32_16x16x32_bf16 v[4:7], v[198:201], v[186:189], v[4:7]
	v_mfma_f32_16x16x32_bf16 v[0:3], v[206:209], v[186:189], v[0:3]
	v_mfma_f32_16x16x32_bf16 v[54:57], v[202:205], v[166:169], v[54:57]
	v_mfma_f32_16x16x32_bf16 v[50:53], v[210:213], v[166:169], v[50:53]
	v_mfma_f32_16x16x32_bf16 v[36:39], v[202:205], v[174:177], v[36:39]
	v_mfma_f32_16x16x32_bf16 v[32:35], v[210:213], v[174:177], v[32:35]
	v_mfma_f32_16x16x32_bf16 v[20:23], v[202:205], v[182:185], v[20:23]
	v_mfma_f32_16x16x32_bf16 v[16:19], v[210:213], v[182:185], v[16:19]
	v_mfma_f32_16x16x32_bf16 v[4:7], v[202:205], v[190:193], v[4:7]
	v_mfma_f32_16x16x32_bf16 v[0:3], v[210:213], v[190:193], v[0:3]
	s_setprio 0
	s_add_i32 s41, s41, 2
	s_add_u32 s39, s39, 0x100
	s_addc_u32 s40, s40, 0
	s_cmp_gt_u32 s41, 9
	s_mov_b64 s[10:11], s[12:13]
	s_barrier
	s_cbranch_scc0 .LBB0_822
	v_lshl_add_u32 v142, s38, 8, v146
	v_ashrrev_i32_e32 v143, 31, v142
	v_lshlrev_b64 v[144:145], 14, v[142:143]
	v_mul_f32_e32 v143, 0x3d372713, v126
	v_mul_f32_e32 v143, v126, v143
	v_fma_f32 v143, v126, v143, v126
	v_mul_f32_e32 v143, 0xbfcc422a, v143
	v_mul_f32_e32 v143, 0x3fb8aa3b, v143
	v_exp_f32_e32 v150, v143
	v_mul_f32_e32 v143, 0x3d372713, v122
	v_mul_f32_e32 v143, v122, v143
	v_fma_f32 v143, v122, v143, v122
	v_mul_f32_e32 v143, 0xbfcc422a, v143
	v_mul_f32_e32 v143, 0x3fb8aa3b, v143
	v_exp_f32_e32 v152, v143
	v_mul_f32_e32 v143, 0x3d372713, v127
	v_mul_f32_e32 v143, v127, v143
	v_fma_f32 v143, v127, v143, v127
	v_mul_f32_e32 v143, 0xbfcc422a, v143
	v_mul_f32_e32 v143, 0x3fb8aa3b, v143
	v_exp_f32_e32 v151, v143
	v_lshl_or_b32 v154, s37, 8, v148
	s_lshl_b32 s10, s36, 4
	s_ashr_i32 s11, s10, 31
	v_pk_add_f32 v[150:151], v[150:151], 1.0 op_sel_hi:[1,0]
	s_lshl_b64 s[10:11], s[10:11], 1
	s_mov_b32 s36, s31
	s_mov_b32 s37, s35
	s_mov_b32 s38, s34
	v_rcp_f32_e32 v143, v151
	s_nop 0
	v_mul_f32_e32 v143, v127, v143
	s_nop 0
	v_rcp_f32_e32 v127, v150
	s_nop 0
	v_mul_f32_e32 v150, v126, v127
	v_mul_f32_e32 v126, 0x3d372713, v123
	v_mul_f32_e32 v126, v123, v126
	v_fma_f32 v126, v123, v126, v123
	v_mul_f32_e32 v126, 0xbfcc422a, v126
	v_mul_f32_e32 v126, 0x3fb8aa3b, v126
	v_exp_f32_e32 v153, v126
	v_cvt_pk_bf16_f32 v150, v150, v143
	v_pk_add_f32 v[126:127], v[152:153], 1.0 op_sel_hi:[1,0]
	s_nop 0
	s_nop 0
	v_rcp_f32_e32 v151, v127
	s_nop 0
	v_mul_f32_e32 v152, v123, v151
	s_nop 0
	v_rcp_f32_e32 v123, v126
	s_nop 0
	v_mul_f32_e32 v153, v122, v123
	v_mul_f32_e32 v123, 0x3d372713, v124
	v_mul_f32_e32 v123, v124, v123
	v_fma_f32 v123, v124, v123, v124
	v_mul_f32_e32 v123, 0xbfcc422a, v123
	v_mul_f32_e32 v123, 0x3fb8aa3b, v123
	v_mul_f32_e32 v122, 0x3d372713, v128
	v_exp_f32_e32 v126, v123
	v_mul_f32_e32 v123, 0x3d372713, v129
	v_mul_f32_e32 v122, v128, v122
	v_mul_f32_e32 v123, v129, v123
	v_fma_f32 v122, v128, v122, v128
	v_fma_f32 v123, v129, v123, v129
	v_mul_f32_e32 v122, 0xbfcc422a, v122
	v_mul_f32_e32 v123, 0xbfcc422a, v123
	v_mul_f32_e32 v122, 0x3fb8aa3b, v122
	v_mul_f32_e32 v123, 0x3fb8aa3b, v123
	v_exp_f32_e32 v122, v122
	v_exp_f32_e32 v123, v123
	v_cvt_pk_bf16_f32 v152, v153, v152
	v_pk_add_f32 v[122:123], v[122:123], 1.0 op_sel_hi:[1,0]
	s_nop 0
	s_nop 0
	v_rcp_f32_e32 v127, v123
	s_nop 0
	v_mul_f32_e32 v129, v129, v127
	s_nop 0
	v_rcp_f32_e32 v123, v122
	s_nop 0
	v_mul_f32_e32 v128, v128, v123
	v_mul_f32_e32 v122, 0x3d372713, v125
	v_mul_f32_e32 v122, v125, v122
	v_fma_f32 v122, v125, v122, v125
	v_mul_f32_e32 v122, 0xbfcc422a, v122
	v_mul_f32_e32 v122, 0x3fb8aa3b, v122
	v_exp_f32_e32 v127, v122
	s_nop 0
	v_pk_add_f32 v[122:123], v[126:127], 1.0 op_sel_hi:[1,0]
	s_nop 0
	s_nop 0
	v_rcp_f32_e32 v126, v123
	s_nop 0
	v_mul_f32_e32 v123, v125, v126
	s_nop 0
	v_ashrrev_i32_e32 v126, 4, v154
	v_ashrrev_i32_e32 v127, 31, v126
	v_rcp_f32_e32 v125, v122
	s_nop 0
	v_mul_f32_e32 v122, v124, v125
	v_lshlrev_b64 v[124:125], 9, v[126:127]
	v_mul_f32_e32 v127, 0x3d372713, v118
	v_cvt_pk_bf16_f32 v153, v122, v123
	v_lshl_add_u64 v[122:123], s[0:1], 0, v[144:145]
	v_mul_f32_e32 v127, v118, v127
	v_cvt_pk_bf16_f32 v151, v128, v129
	v_lshl_add_u64 v[128:129], v[122:123], 0, v[124:125]
	v_fma_f32 v127, v118, v127, v118
	v_lshl_add_u64 v[128:129], v[128:129], 0, s[10:11]
	v_mul_f32_e32 v127, 0xbfcc422a, v127
	v_lshl_add_u64 v[128:129], v[128:129], 0, v[48:49]
	v_mul_f32_e32 v127, 0x3fb8aa3b, v127
	global_store_dwordx4 v[128:129], v[150:153], off
	v_exp_f32_e32 v128, v127
	v_mul_f32_e32 v127, 0x3d372713, v114
	v_mul_f32_e32 v127, v114, v127
	v_fma_f32 v127, v114, v127, v114
	v_mul_f32_e32 v127, 0xbfcc422a, v127
	v_mul_f32_e32 v127, 0x3fb8aa3b, v127
	v_exp_f32_e32 v144, v127
	v_mul_f32_e32 v127, 0x3d372713, v119
	v_mul_f32_e32 v127, v119, v127
	v_fma_f32 v127, v119, v127, v119
	v_mul_f32_e32 v127, 0xbfcc422a, v127
	v_mul_f32_e32 v127, 0x3fb8aa3b, v127
	v_exp_f32_e32 v129, v127
	s_nop 0
	v_pk_add_f32 v[128:129], v[128:129], 1.0 op_sel_hi:[1,0]
	s_nop 0
	s_nop 0
	v_rcp_f32_e32 v127, v129
	s_nop 0
	v_mul_f32_e32 v127, v119, v127
	s_nop 0
	v_rcp_f32_e32 v119, v128
	s_nop 0
	v_mul_f32_e32 v128, v118, v119
	v_mul_f32_e32 v118, 0x3d372713, v115
	v_mul_f32_e32 v118, v115, v118
	v_fma_f32 v118, v115, v118, v115
	v_mul_f32_e32 v118, 0xbfcc422a, v118
	v_mul_f32_e32 v118, 0x3fb8aa3b, v118
	v_exp_f32_e32 v145, v118
	s_nop 0
	v_pk_add_f32 v[118:119], v[144:145], 1.0 op_sel_hi:[1,0]
	s_nop 0
	s_nop 0
	v_rcp_f32_e32 v129, v119
	s_nop 0
	v_mul_f32_e32 v129, v115, v129
	s_nop 0
	v_rcp_f32_e32 v115, v118
	s_nop 0
	v_mul_f32_e32 v143, v114, v115
	v_mul_f32_e32 v115, 0x3d372713, v116
	v_mul_f32_e32 v115, v116, v115
	v_fma_f32 v115, v116, v115, v116
	v_mul_f32_e32 v115, 0xbfcc422a, v115
	v_mul_f32_e32 v115, 0x3fb8aa3b, v115
	v_mul_f32_e32 v114, 0x3d372713, v120
	v_exp_f32_e32 v118, v115
	v_mul_f32_e32 v115, 0x3d372713, v121
	v_mul_f32_e32 v114, v120, v114
	v_mul_f32_e32 v115, v121, v115
	v_fma_f32 v114, v120, v114, v120
	v_fma_f32 v115, v121, v115, v121
	v_mul_f32_e32 v114, 0xbfcc422a, v114
	v_mul_f32_e32 v115, 0xbfcc422a, v115
	v_mul_f32_e32 v114, 0x3fb8aa3b, v114
	v_mul_f32_e32 v115, 0x3fb8aa3b, v115
	v_exp_f32_e32 v114, v114
	v_exp_f32_e32 v115, v115
	s_nop 0
	v_pk_add_f32 v[114:115], v[114:115], 1.0 op_sel_hi:[1,0]
	s_nop 0
	s_nop 0
	v_rcp_f32_e32 v119, v115
	s_nop 0
	v_mul_f32_e32 v121, v121, v119
	s_nop 0
	v_rcp_f32_e32 v115, v114
	s_nop 0
	v_mul_f32_e32 v120, v120, v115
	v_mul_f32_e32 v114, 0x3d372713, v117
	v_mul_f32_e32 v114, v117, v114
	v_fma_f32 v114, v117, v114, v117
	v_mul_f32_e32 v114, 0xbfcc422a, v114
	v_mul_f32_e32 v114, 0x3fb8aa3b, v114
	v_exp_f32_e32 v119, v114
	s_nop 0
	v_pk_add_f32 v[114:115], v[118:119], 1.0 op_sel_hi:[1,0]
	s_nop 0
	s_nop 0
	v_rcp_f32_e32 v118, v115
	s_nop 0
	v_mul_f32_e32 v115, v117, v118
	s_nop 0
	v_rcp_f32_e32 v117, v114
	s_nop 0
	v_mul_f32_e32 v119, v116, v117
	v_or_b32_e32 v114, 8, v126
	v_cvt_pk_bf16_f32 v119, v119, v115
	v_ashrrev_i32_e32 v115, 31, v114
	v_lshlrev_b64 v[114:115], 9, v[114:115]
	v_cvt_pk_bf16_f32 v117, v120, v121
	v_lshl_add_u64 v[120:121], v[122:123], 0, v[114:115]
	v_lshl_add_u64 v[120:121], v[120:121], 0, s[10:11]
	v_cvt_pk_bf16_f32 v116, v128, v127
	v_cvt_pk_bf16_f32 v118, v143, v129
	v_lshl_add_u64 v[120:121], v[120:121], 0, v[48:49]
	global_store_dwordx4 v[120:121], v[116:119], off
	s_nop 1
	v_mul_f32_e32 v119, 0x3d372713, v106
	v_mul_f32_e32 v119, v106, v119
	v_fma_f32 v119, v106, v119, v106
	v_mul_f32_e32 v119, 0xbfcc422a, v119
	v_mul_f32_e32 v119, 0x3fb8aa3b, v119
	v_mul_f32_e32 v118, 0x3d372713, v110
	v_exp_f32_e32 v120, v119
	v_mul_f32_e32 v119, 0x3d372713, v111
	v_mul_f32_e32 v118, v110, v118
	v_mul_f32_e32 v119, v111, v119
	v_fma_f32 v118, v110, v118, v110
	v_fma_f32 v119, v111, v119, v111
	v_mul_f32_e32 v118, 0xbfcc422a, v118
	v_mul_f32_e32 v119, 0xbfcc422a, v119
	v_mul_f32_e32 v118, 0x3fb8aa3b, v118
	v_mul_f32_e32 v119, 0x3fb8aa3b, v119
	v_exp_f32_e32 v118, v118
	v_exp_f32_e32 v119, v119
	v_or_b32_e32 v116, 16, v142
	v_ashrrev_i32_e32 v117, 31, v116
	v_lshlrev_b64 v[116:117], 14, v[116:117]
	v_pk_add_f32 v[118:119], v[118:119], 1.0 op_sel_hi:[1,0]
	s_nop 0
	s_nop 0
	v_rcp_f32_e32 v121, v119
	s_nop 0
	v_mul_f32_e32 v119, v111, v121
	s_nop 0
	v_rcp_f32_e32 v111, v118
	s_nop 0
	v_mul_f32_e32 v118, v110, v111
	v_mul_f32_e32 v110, 0x3d372713, v107
	v_mul_f32_e32 v110, v107, v110
	v_fma_f32 v110, v107, v110, v107
	v_mul_f32_e32 v110, 0xbfcc422a, v110
	v_mul_f32_e32 v110, 0x3fb8aa3b, v110
	v_exp_f32_e32 v121, v110
	s_nop 0
	v_pk_add_f32 v[110:111], v[120:121], 1.0 op_sel_hi:[1,0]
	s_nop 0
	s_nop 0
	v_rcp_f32_e32 v120, v111
	s_nop 0
	v_mul_f32_e32 v120, v107, v120
	s_nop 0
	v_rcp_f32_e32 v107, v110
	s_nop 0
	v_mul_f32_e32 v121, v106, v107
	v_mul_f32_e32 v107, 0x3d372713, v108
	v_mul_f32_e32 v107, v108, v107
	v_fma_f32 v107, v108, v107, v108
	v_mul_f32_e32 v107, 0xbfcc422a, v107
	v_mul_f32_e32 v107, 0x3fb8aa3b, v107
	v_mul_f32_e32 v106, 0x3d372713, v112
	v_exp_f32_e32 v110, v107
	v_mul_f32_e32 v107, 0x3d372713, v113
	v_mul_f32_e32 v106, v112, v106
	v_mul_f32_e32 v107, v113, v107
	v_fma_f32 v106, v112, v106, v112
	v_fma_f32 v107, v113, v107, v113
	v_mul_f32_e32 v106, 0xbfcc422a, v106
	v_mul_f32_e32 v107, 0xbfcc422a, v107
	v_mul_f32_e32 v106, 0x3fb8aa3b, v106
	v_mul_f32_e32 v107, 0x3fb8aa3b, v107
	v_exp_f32_e32 v106, v106
	v_exp_f32_e32 v107, v107
	s_nop 0
	v_pk_add_f32 v[106:107], v[106:107], 1.0 op_sel_hi:[1,0]
	s_nop 0
	s_nop 0
	v_rcp_f32_e32 v111, v107
	s_nop 0
	v_mul_f32_e32 v113, v113, v111
	s_nop 0
	v_rcp_f32_e32 v107, v106
	s_nop 0
	v_mul_f32_e32 v112, v112, v107
	v_mul_f32_e32 v106, 0x3d372713, v109
	v_mul_f32_e32 v106, v109, v106
	v_fma_f32 v106, v109, v106, v109
	v_mul_f32_e32 v106, 0xbfcc422a, v106
	v_mul_f32_e32 v106, 0x3fb8aa3b, v106
	v_exp_f32_e32 v111, v106
	s_nop 0
	v_pk_add_f32 v[106:107], v[110:111], 1.0 op_sel_hi:[1,0]
	s_nop 0
	s_nop 0
	v_rcp_f32_e32 v110, v107
	s_nop 0
	v_mul_f32_e32 v107, v109, v110
	s_nop 0
	v_rcp_f32_e32 v109, v106
	s_nop 0
	v_mul_f32_e32 v106, v108, v109
	v_cvt_pk_bf16_f32 v111, v106, v107
	v_lshl_add_u64 v[106:107], s[0:1], 0, v[116:117]
	v_cvt_pk_bf16_f32 v109, v112, v113
	v_lshl_add_u64 v[112:113], v[106:107], 0, v[124:125]
	v_lshl_add_u64 v[112:113], v[112:113], 0, s[10:11]
	v_cvt_pk_bf16_f32 v108, v118, v119
	v_cvt_pk_bf16_f32 v110, v121, v120
	v_lshl_add_u64 v[112:113], v[112:113], 0, v[48:49]
	global_store_dwordx4 v[112:113], v[108:111], off
	s_nop 1
	v_mul_f32_e32 v109, 0x3d372713, v98
	v_mul_f32_e32 v109, v98, v109
	v_fma_f32 v109, v98, v109, v98
	v_mul_f32_e32 v109, 0xbfcc422a, v109
	v_mul_f32_e32 v109, 0x3fb8aa3b, v109
	v_mul_f32_e32 v108, 0x3d372713, v102
	v_exp_f32_e32 v110, v109
	v_mul_f32_e32 v109, 0x3d372713, v103
	v_mul_f32_e32 v108, v102, v108
	v_mul_f32_e32 v109, v103, v109
	v_fma_f32 v108, v102, v108, v102
	v_fma_f32 v109, v103, v109, v103
	v_mul_f32_e32 v108, 0xbfcc422a, v108
	v_mul_f32_e32 v109, 0xbfcc422a, v109
	v_mul_f32_e32 v108, 0x3fb8aa3b, v108
	v_mul_f32_e32 v109, 0x3fb8aa3b, v109
	v_exp_f32_e32 v108, v108
	v_exp_f32_e32 v109, v109
	s_nop 0
	v_pk_add_f32 v[108:109], v[108:109], 1.0 op_sel_hi:[1,0]
	s_nop 0
	s_nop 0
	v_rcp_f32_e32 v111, v109
	s_nop 0
	v_mul_f32_e32 v109, v103, v111
	s_nop 0
	v_rcp_f32_e32 v103, v108
	s_nop 0
	v_mul_f32_e32 v108, v102, v103
	v_mul_f32_e32 v102, 0x3d372713, v99
	v_mul_f32_e32 v102, v99, v102
	v_fma_f32 v102, v99, v102, v99
	v_mul_f32_e32 v102, 0xbfcc422a, v102
	v_mul_f32_e32 v102, 0x3fb8aa3b, v102
	v_exp_f32_e32 v111, v102
	s_nop 0
	v_pk_add_f32 v[102:103], v[110:111], 1.0 op_sel_hi:[1,0]
	s_nop 0
	s_nop 0
	v_rcp_f32_e32 v110, v103
	s_nop 0
	v_mul_f32_e32 v110, v99, v110
	s_nop 0
	v_rcp_f32_e32 v99, v102
	s_nop 0
	v_mul_f32_e32 v111, v98, v99
	v_mul_f32_e32 v99, 0x3d372713, v100
	v_mul_f32_e32 v99, v100, v99
	v_fma_f32 v99, v100, v99, v100
	v_mul_f32_e32 v99, 0xbfcc422a, v99
	v_mul_f32_e32 v99, 0x3fb8aa3b, v99
	v_mul_f32_e32 v98, 0x3d372713, v104
	v_exp_f32_e32 v102, v99
	v_mul_f32_e32 v99, 0x3d372713, v105
	v_mul_f32_e32 v98, v104, v98
	v_mul_f32_e32 v99, v105, v99
	v_fma_f32 v98, v104, v98, v104
	v_fma_f32 v99, v105, v99, v105
	v_mul_f32_e32 v98, 0xbfcc422a, v98
	v_mul_f32_e32 v99, 0xbfcc422a, v99
	v_mul_f32_e32 v98, 0x3fb8aa3b, v98
	v_mul_f32_e32 v99, 0x3fb8aa3b, v99
	v_exp_f32_e32 v98, v98
	v_exp_f32_e32 v99, v99
	s_nop 0
	v_pk_add_f32 v[98:99], v[98:99], 1.0 op_sel_hi:[1,0]
	s_nop 0
	s_nop 0
	v_rcp_f32_e32 v103, v99
	s_nop 0
	v_mul_f32_e32 v105, v105, v103
	s_nop 0
	v_rcp_f32_e32 v99, v98
	s_nop 0
	v_mul_f32_e32 v104, v104, v99
	v_mul_f32_e32 v98, 0x3d372713, v101
	v_mul_f32_e32 v98, v101, v98
	v_fma_f32 v98, v101, v98, v101
	v_mul_f32_e32 v98, 0xbfcc422a, v98
	v_mul_f32_e32 v98, 0x3fb8aa3b, v98
	v_exp_f32_e32 v103, v98
	s_nop 0
	v_pk_add_f32 v[98:99], v[102:103], 1.0 op_sel_hi:[1,0]
	s_nop 0
	s_nop 0
	v_rcp_f32_e32 v102, v99
	s_nop 0
	v_mul_f32_e32 v101, v101, v102
	s_nop 0
	v_rcp_f32_e32 v99, v98
	s_nop 0
	v_mul_f32_e32 v102, v100, v99
	v_cvt_pk_bf16_f32 v101, v102, v101
	v_lshl_add_u64 v[102:103], v[106:107], 0, v[114:115]
	v_lshl_add_u64 v[102:103], v[102:103], 0, s[10:11]
	v_cvt_pk_bf16_f32 v98, v108, v109
	v_cvt_pk_bf16_f32 v99, v104, v105
	v_cvt_pk_bf16_f32 v100, v111, v110
	v_lshl_add_u64 v[102:103], v[102:103], 0, v[48:49]
	global_store_dwordx4 v[102:103], v[98:101], off
	s_nop 1
	v_mul_f32_e32 v101, 0x3d372713, v90
	v_mul_f32_e32 v101, v90, v101
	v_fma_f32 v101, v90, v101, v90
	v_mul_f32_e32 v101, 0xbfcc422a, v101
	v_mul_f32_e32 v101, 0x3fb8aa3b, v101
	v_mul_f32_e32 v100, 0x3d372713, v94
	v_exp_f32_e32 v102, v101
	v_mul_f32_e32 v101, 0x3d372713, v95
	v_mul_f32_e32 v100, v94, v100
	v_mul_f32_e32 v101, v95, v101
	v_fma_f32 v100, v94, v100, v94
	v_fma_f32 v101, v95, v101, v95
	v_mul_f32_e32 v100, 0xbfcc422a, v100
	v_mul_f32_e32 v101, 0xbfcc422a, v101
	v_mul_f32_e32 v100, 0x3fb8aa3b, v100
	v_mul_f32_e32 v101, 0x3fb8aa3b, v101
	v_exp_f32_e32 v100, v100
	v_exp_f32_e32 v101, v101
	v_or_b32_e32 v98, 32, v142
	v_ashrrev_i32_e32 v99, 31, v98
	v_lshlrev_b64 v[98:99], 14, v[98:99]
	v_pk_add_f32 v[100:101], v[100:101], 1.0 op_sel_hi:[1,0]
	s_nop 0
	s_nop 0
	v_rcp_f32_e32 v103, v101
	s_nop 0
	v_mul_f32_e32 v101, v95, v103
	s_nop 0
	v_rcp_f32_e32 v95, v100
	s_nop 0
	v_mul_f32_e32 v100, v94, v95
	v_mul_f32_e32 v94, 0x3d372713, v91
	v_mul_f32_e32 v94, v91, v94
	v_fma_f32 v94, v91, v94, v91
	v_mul_f32_e32 v94, 0xbfcc422a, v94
	v_mul_f32_e32 v94, 0x3fb8aa3b, v94
	v_exp_f32_e32 v103, v94
	s_nop 0
	v_pk_add_f32 v[94:95], v[102:103], 1.0 op_sel_hi:[1,0]
	s_nop 0
	s_nop 0
	v_rcp_f32_e32 v102, v95
	s_nop 0
	v_mul_f32_e32 v102, v91, v102
	s_nop 0
	v_rcp_f32_e32 v91, v94
	s_nop 0
	v_mul_f32_e32 v103, v90, v91
	v_mul_f32_e32 v91, 0x3d372713, v92
	v_mul_f32_e32 v91, v92, v91
	v_fma_f32 v91, v92, v91, v92
	v_mul_f32_e32 v91, 0xbfcc422a, v91
	v_mul_f32_e32 v91, 0x3fb8aa3b, v91
	v_mul_f32_e32 v90, 0x3d372713, v96
	v_exp_f32_e32 v94, v91
	v_mul_f32_e32 v91, 0x3d372713, v97
	v_mul_f32_e32 v90, v96, v90
	v_mul_f32_e32 v91, v97, v91
	v_fma_f32 v90, v96, v90, v96
	v_fma_f32 v91, v97, v91, v97
	v_mul_f32_e32 v90, 0xbfcc422a, v90
	v_mul_f32_e32 v91, 0xbfcc422a, v91
	v_mul_f32_e32 v90, 0x3fb8aa3b, v90
	v_mul_f32_e32 v91, 0x3fb8aa3b, v91
	v_exp_f32_e32 v90, v90
	v_exp_f32_e32 v91, v91
	s_nop 0
	v_pk_add_f32 v[90:91], v[90:91], 1.0 op_sel_hi:[1,0]
	s_nop 0
	s_nop 0
	v_rcp_f32_e32 v95, v91
	s_nop 0
	v_mul_f32_e32 v97, v97, v95
	s_nop 0
	v_rcp_f32_e32 v91, v90
	s_nop 0
	v_mul_f32_e32 v96, v96, v91
	v_mul_f32_e32 v90, 0x3d372713, v93
	v_mul_f32_e32 v90, v93, v90
	v_fma_f32 v90, v93, v90, v93
	v_mul_f32_e32 v90, 0xbfcc422a, v90
	v_mul_f32_e32 v90, 0x3fb8aa3b, v90
	v_exp_f32_e32 v95, v90
	s_nop 0
	v_pk_add_f32 v[90:91], v[94:95], 1.0 op_sel_hi:[1,0]
	s_nop 0
	s_nop 0
	v_rcp_f32_e32 v94, v91
	s_nop 0
	v_mul_f32_e32 v91, v93, v94
	s_nop 0
	v_rcp_f32_e32 v93, v90
	s_nop 0
	v_mul_f32_e32 v90, v92, v93
	v_cvt_pk_bf16_f32 v95, v90, v91
	v_lshl_add_u64 v[90:91], s[0:1], 0, v[98:99]
	v_cvt_pk_bf16_f32 v93, v96, v97
	v_lshl_add_u64 v[96:97], v[90:91], 0, v[124:125]
	v_lshl_add_u64 v[96:97], v[96:97], 0, s[10:11]
	v_cvt_pk_bf16_f32 v92, v100, v101
	v_cvt_pk_bf16_f32 v94, v103, v102
	v_lshl_add_u64 v[96:97], v[96:97], 0, v[48:49]
	global_store_dwordx4 v[96:97], v[92:95], off
	s_nop 1
	v_mul_f32_e32 v93, 0x3d372713, v82
	v_mul_f32_e32 v93, v82, v93
	v_fma_f32 v93, v82, v93, v82
	v_mul_f32_e32 v93, 0xbfcc422a, v93
	v_mul_f32_e32 v93, 0x3fb8aa3b, v93
	v_mul_f32_e32 v92, 0x3d372713, v86
	v_exp_f32_e32 v94, v93
	v_mul_f32_e32 v93, 0x3d372713, v87
	v_mul_f32_e32 v92, v86, v92
	v_mul_f32_e32 v93, v87, v93
	v_fma_f32 v92, v86, v92, v86
	v_fma_f32 v93, v87, v93, v87
	v_mul_f32_e32 v92, 0xbfcc422a, v92
	v_mul_f32_e32 v93, 0xbfcc422a, v93
	v_mul_f32_e32 v92, 0x3fb8aa3b, v92
	v_mul_f32_e32 v93, 0x3fb8aa3b, v93
	v_exp_f32_e32 v92, v92
	v_exp_f32_e32 v93, v93
	s_nop 0
	v_pk_add_f32 v[92:93], v[92:93], 1.0 op_sel_hi:[1,0]
	s_nop 0
	s_nop 0
	v_rcp_f32_e32 v95, v93
	s_nop 0
	v_mul_f32_e32 v93, v87, v95
	s_nop 0
	v_rcp_f32_e32 v87, v92
	s_nop 0
	v_mul_f32_e32 v92, v86, v87
	v_mul_f32_e32 v86, 0x3d372713, v83
	v_mul_f32_e32 v86, v83, v86
	v_fma_f32 v86, v83, v86, v83
	v_mul_f32_e32 v86, 0xbfcc422a, v86
	v_mul_f32_e32 v86, 0x3fb8aa3b, v86
	v_exp_f32_e32 v95, v86
	s_nop 0
	v_pk_add_f32 v[86:87], v[94:95], 1.0 op_sel_hi:[1,0]
	s_nop 0
	s_nop 0
	v_rcp_f32_e32 v94, v87
	s_nop 0
	v_mul_f32_e32 v94, v83, v94
	s_nop 0
	v_rcp_f32_e32 v83, v86
	s_nop 0
	v_mul_f32_e32 v95, v82, v83
	v_mul_f32_e32 v83, 0x3d372713, v84
	v_mul_f32_e32 v83, v84, v83
	v_fma_f32 v83, v84, v83, v84
	v_mul_f32_e32 v83, 0xbfcc422a, v83
	v_mul_f32_e32 v83, 0x3fb8aa3b, v83
	v_mul_f32_e32 v82, 0x3d372713, v88
	v_exp_f32_e32 v86, v83
	v_mul_f32_e32 v83, 0x3d372713, v89
	v_mul_f32_e32 v82, v88, v82
	v_mul_f32_e32 v83, v89, v83
	v_fma_f32 v82, v88, v82, v88
	v_fma_f32 v83, v89, v83, v89
	v_mul_f32_e32 v82, 0xbfcc422a, v82
	v_mul_f32_e32 v83, 0xbfcc422a, v83
	v_mul_f32_e32 v82, 0x3fb8aa3b, v82
	v_mul_f32_e32 v83, 0x3fb8aa3b, v83
	v_exp_f32_e32 v82, v82
	v_exp_f32_e32 v83, v83
	s_nop 0
	v_pk_add_f32 v[82:83], v[82:83], 1.0 op_sel_hi:[1,0]
	s_nop 0
	s_nop 0
	v_rcp_f32_e32 v87, v83
	s_nop 0
	v_mul_f32_e32 v89, v89, v87
	s_nop 0
	v_rcp_f32_e32 v83, v82
	s_nop 0
	v_mul_f32_e32 v88, v88, v83
	v_mul_f32_e32 v82, 0x3d372713, v85
	v_mul_f32_e32 v82, v85, v82
	v_fma_f32 v82, v85, v82, v85
	v_mul_f32_e32 v82, 0xbfcc422a, v82
	v_mul_f32_e32 v82, 0x3fb8aa3b, v82
	v_exp_f32_e32 v87, v82
	s_nop 0
	v_pk_add_f32 v[82:83], v[86:87], 1.0 op_sel_hi:[1,0]
	s_nop 0
	s_nop 0
	v_rcp_f32_e32 v86, v83
	s_nop 0
	v_mul_f32_e32 v85, v85, v86
	s_nop 0
	v_rcp_f32_e32 v83, v82
	s_nop 0
	v_mul_f32_e32 v86, v84, v83
	v_cvt_pk_bf16_f32 v85, v86, v85
	v_lshl_add_u64 v[86:87], v[90:91], 0, v[114:115]
	v_lshl_add_u64 v[86:87], v[86:87], 0, s[10:11]
	v_cvt_pk_bf16_f32 v82, v92, v93
	v_cvt_pk_bf16_f32 v83, v88, v89
	v_cvt_pk_bf16_f32 v84, v95, v94
	v_lshl_add_u64 v[86:87], v[86:87], 0, v[48:49]
	global_store_dwordx4 v[86:87], v[82:85], off
	s_nop 1
	v_mul_f32_e32 v85, 0x3d372713, v74
	v_mul_f32_e32 v85, v74, v85
	v_fma_f32 v85, v74, v85, v74
	v_mul_f32_e32 v85, 0xbfcc422a, v85
	v_mul_f32_e32 v85, 0x3fb8aa3b, v85
	v_mul_f32_e32 v84, 0x3d372713, v78
	v_exp_f32_e32 v86, v85
	v_mul_f32_e32 v85, 0x3d372713, v79
	v_mul_f32_e32 v84, v78, v84
	v_mul_f32_e32 v85, v79, v85
	v_fma_f32 v84, v78, v84, v78
	v_fma_f32 v85, v79, v85, v79
	v_mul_f32_e32 v84, 0xbfcc422a, v84
	v_mul_f32_e32 v85, 0xbfcc422a, v85
	v_mul_f32_e32 v84, 0x3fb8aa3b, v84
	v_mul_f32_e32 v85, 0x3fb8aa3b, v85
	v_exp_f32_e32 v84, v84
	v_exp_f32_e32 v85, v85
	v_or_b32_e32 v82, 48, v142
	v_ashrrev_i32_e32 v83, 31, v82
	v_lshlrev_b64 v[82:83], 14, v[82:83]
	v_pk_add_f32 v[84:85], v[84:85], 1.0 op_sel_hi:[1,0]
	s_nop 0
	s_nop 0
	v_rcp_f32_e32 v87, v85
	s_nop 0
	v_mul_f32_e32 v85, v79, v87
	s_nop 0
	v_rcp_f32_e32 v79, v84
	s_nop 0
	v_mul_f32_e32 v84, v78, v79
	v_mul_f32_e32 v78, 0x3d372713, v75
	v_mul_f32_e32 v78, v75, v78
	v_fma_f32 v78, v75, v78, v75
	v_mul_f32_e32 v78, 0xbfcc422a, v78
	v_mul_f32_e32 v78, 0x3fb8aa3b, v78
	v_exp_f32_e32 v87, v78
	s_nop 0
	v_pk_add_f32 v[78:79], v[86:87], 1.0 op_sel_hi:[1,0]
	s_nop 0
	s_nop 0
	v_rcp_f32_e32 v86, v79
	s_nop 0
	v_mul_f32_e32 v86, v75, v86
	s_nop 0
	v_rcp_f32_e32 v75, v78
	s_nop 0
	v_mul_f32_e32 v87, v74, v75
	v_mul_f32_e32 v75, 0x3d372713, v76
	v_mul_f32_e32 v75, v76, v75
	v_fma_f32 v75, v76, v75, v76
	v_mul_f32_e32 v75, 0xbfcc422a, v75
	v_mul_f32_e32 v75, 0x3fb8aa3b, v75
	v_mul_f32_e32 v74, 0x3d372713, v80
	v_exp_f32_e32 v78, v75
	v_mul_f32_e32 v75, 0x3d372713, v81
	v_mul_f32_e32 v74, v80, v74
	v_mul_f32_e32 v75, v81, v75
	v_fma_f32 v74, v80, v74, v80
	v_fma_f32 v75, v81, v75, v81
	v_mul_f32_e32 v74, 0xbfcc422a, v74
	v_mul_f32_e32 v75, 0xbfcc422a, v75
	v_mul_f32_e32 v74, 0x3fb8aa3b, v74
	v_mul_f32_e32 v75, 0x3fb8aa3b, v75
	v_exp_f32_e32 v74, v74
	v_exp_f32_e32 v75, v75
	s_nop 0
	v_pk_add_f32 v[74:75], v[74:75], 1.0 op_sel_hi:[1,0]
	s_nop 0
	s_nop 0
	v_rcp_f32_e32 v79, v75
	s_nop 0
	v_mul_f32_e32 v81, v81, v79
	s_nop 0
	v_rcp_f32_e32 v75, v74
	s_nop 0
	v_mul_f32_e32 v80, v80, v75
	v_mul_f32_e32 v74, 0x3d372713, v77
	v_mul_f32_e32 v74, v77, v74
	v_fma_f32 v74, v77, v74, v77
	v_mul_f32_e32 v74, 0xbfcc422a, v74
	v_mul_f32_e32 v74, 0x3fb8aa3b, v74
	v_exp_f32_e32 v79, v74
	s_nop 0
	v_pk_add_f32 v[74:75], v[78:79], 1.0 op_sel_hi:[1,0]
	s_nop 0
	s_nop 0
	v_rcp_f32_e32 v78, v75
	s_nop 0
	v_mul_f32_e32 v75, v77, v78
	s_nop 0
	v_rcp_f32_e32 v77, v74
	s_nop 0
	v_mul_f32_e32 v74, v76, v77
	v_cvt_pk_bf16_f32 v79, v74, v75
	v_lshl_add_u64 v[74:75], s[0:1], 0, v[82:83]
	v_cvt_pk_bf16_f32 v77, v80, v81
	v_lshl_add_u64 v[80:81], v[74:75], 0, v[124:125]
	v_lshl_add_u64 v[80:81], v[80:81], 0, s[10:11]
	v_cvt_pk_bf16_f32 v76, v84, v85
	v_cvt_pk_bf16_f32 v78, v87, v86
	v_lshl_add_u64 v[80:81], v[80:81], 0, v[48:49]
	global_store_dwordx4 v[80:81], v[76:79], off
	s_nop 1
	v_mul_f32_e32 v77, 0x3d372713, v66
	v_mul_f32_e32 v77, v66, v77
	v_fma_f32 v77, v66, v77, v66
	v_mul_f32_e32 v77, 0xbfcc422a, v77
	v_mul_f32_e32 v77, 0x3fb8aa3b, v77
	v_mul_f32_e32 v76, 0x3d372713, v70
	v_exp_f32_e32 v78, v77
	v_mul_f32_e32 v77, 0x3d372713, v71
	v_mul_f32_e32 v76, v70, v76
	v_mul_f32_e32 v77, v71, v77
	v_fma_f32 v76, v70, v76, v70
	v_fma_f32 v77, v71, v77, v71
	v_mul_f32_e32 v76, 0xbfcc422a, v76
	v_mul_f32_e32 v77, 0xbfcc422a, v77
	v_mul_f32_e32 v76, 0x3fb8aa3b, v76
	v_mul_f32_e32 v77, 0x3fb8aa3b, v77
	v_exp_f32_e32 v76, v76
	v_exp_f32_e32 v77, v77
	s_nop 0
	v_pk_add_f32 v[76:77], v[76:77], 1.0 op_sel_hi:[1,0]
	s_nop 0
	s_nop 0
	v_rcp_f32_e32 v79, v77
	s_nop 0
	v_mul_f32_e32 v77, v71, v79
	s_nop 0
	v_rcp_f32_e32 v71, v76
	s_nop 0
	v_mul_f32_e32 v76, v70, v71
	v_mul_f32_e32 v70, 0x3d372713, v67
	v_mul_f32_e32 v70, v67, v70
	v_fma_f32 v70, v67, v70, v67
	v_mul_f32_e32 v70, 0xbfcc422a, v70
	v_mul_f32_e32 v70, 0x3fb8aa3b, v70
	v_exp_f32_e32 v79, v70
	s_nop 0
	v_pk_add_f32 v[70:71], v[78:79], 1.0 op_sel_hi:[1,0]
	s_nop 0
	s_nop 0
	v_rcp_f32_e32 v78, v71
	s_nop 0
	v_mul_f32_e32 v78, v67, v78
	s_nop 0
	v_rcp_f32_e32 v67, v70
	s_nop 0
	v_mul_f32_e32 v79, v66, v67
	v_mul_f32_e32 v67, 0x3d372713, v68
	v_mul_f32_e32 v67, v68, v67
	v_fma_f32 v67, v68, v67, v68
	v_mul_f32_e32 v67, 0xbfcc422a, v67
	v_mul_f32_e32 v67, 0x3fb8aa3b, v67
	v_mul_f32_e32 v66, 0x3d372713, v72
	v_exp_f32_e32 v70, v67
	v_mul_f32_e32 v67, 0x3d372713, v73
	v_mul_f32_e32 v66, v72, v66
	v_mul_f32_e32 v67, v73, v67
	v_fma_f32 v66, v72, v66, v72
	v_fma_f32 v67, v73, v67, v73
	v_mul_f32_e32 v66, 0xbfcc422a, v66
	v_mul_f32_e32 v67, 0xbfcc422a, v67
	v_mul_f32_e32 v66, 0x3fb8aa3b, v66
	v_mul_f32_e32 v67, 0x3fb8aa3b, v67
	v_exp_f32_e32 v66, v66
	v_exp_f32_e32 v67, v67
	s_nop 0
	v_pk_add_f32 v[66:67], v[66:67], 1.0 op_sel_hi:[1,0]
	s_nop 0
	s_nop 0
	v_rcp_f32_e32 v71, v67
	s_nop 0
	v_mul_f32_e32 v73, v73, v71
	s_nop 0
	v_rcp_f32_e32 v67, v66
	s_nop 0
	v_mul_f32_e32 v72, v72, v67
	v_mul_f32_e32 v66, 0x3d372713, v69
	v_mul_f32_e32 v66, v69, v66
	v_fma_f32 v66, v69, v66, v69
	v_mul_f32_e32 v66, 0xbfcc422a, v66
	v_mul_f32_e32 v66, 0x3fb8aa3b, v66
	v_exp_f32_e32 v71, v66
	s_nop 0
	v_pk_add_f32 v[66:67], v[70:71], 1.0 op_sel_hi:[1,0]
	s_nop 0
	s_nop 0
	v_rcp_f32_e32 v70, v67
	s_nop 0
	v_mul_f32_e32 v69, v69, v70
	s_nop 0
	v_rcp_f32_e32 v67, v66
	s_nop 0
	v_mul_f32_e32 v70, v68, v67
	v_cvt_pk_bf16_f32 v69, v70, v69
	v_lshl_add_u64 v[70:71], v[74:75], 0, v[114:115]
	v_lshl_add_u64 v[70:71], v[70:71], 0, s[10:11]
	v_cvt_pk_bf16_f32 v66, v76, v77
	v_cvt_pk_bf16_f32 v67, v72, v73
	v_cvt_pk_bf16_f32 v68, v79, v78
	v_lshl_add_u64 v[70:71], v[70:71], 0, v[48:49]
	global_store_dwordx4 v[70:71], v[66:69], off
	s_nop 1
	v_mul_f32_e32 v67, 0x3d372713, v58
	v_mul_f32_e32 v67, v58, v67
	v_fma_f32 v67, v58, v67, v58
	v_mul_f32_e32 v67, 0xbfcc422a, v67
	v_mul_f32_e32 v67, 0x3fb8aa3b, v67
	v_mul_f32_e32 v66, 0x3d372713, v62
	v_exp_f32_e32 v68, v67
	v_mul_f32_e32 v67, 0x3d372713, v63
	v_mul_f32_e32 v66, v62, v66
	v_mul_f32_e32 v67, v63, v67
	v_fma_f32 v66, v62, v66, v62
	v_fma_f32 v67, v63, v67, v63
	v_mul_f32_e32 v66, 0xbfcc422a, v66
	v_mul_f32_e32 v67, 0xbfcc422a, v67
	v_mul_f32_e32 v66, 0x3fb8aa3b, v66
	v_mul_f32_e32 v67, 0x3fb8aa3b, v67
	v_exp_f32_e32 v66, v66
	v_exp_f32_e32 v67, v67
	s_nop 0
	v_pk_add_f32 v[66:67], v[66:67], 1.0 op_sel_hi:[1,0]
	s_nop 0
	s_nop 0
	v_rcp_f32_e32 v69, v67
	s_nop 0
	v_mul_f32_e32 v67, v63, v69
	s_nop 0
	v_rcp_f32_e32 v63, v66
	s_nop 0
	v_mul_f32_e32 v66, v62, v63
	v_mul_f32_e32 v62, 0x3d372713, v59
	v_mul_f32_e32 v62, v59, v62
	v_fma_f32 v62, v59, v62, v59
	v_mul_f32_e32 v62, 0xbfcc422a, v62
	v_mul_f32_e32 v62, 0x3fb8aa3b, v62
	v_exp_f32_e32 v69, v62
	s_nop 0
	v_pk_add_f32 v[62:63], v[68:69], 1.0 op_sel_hi:[1,0]
	s_nop 0
	s_nop 0
	v_rcp_f32_e32 v68, v63
	s_nop 0
	v_mul_f32_e32 v68, v59, v68
	s_nop 0
	v_rcp_f32_e32 v59, v62
	s_nop 0
	v_mul_f32_e32 v69, v58, v59
	v_mul_f32_e32 v59, 0x3d372713, v60
	v_mul_f32_e32 v59, v60, v59
	v_fma_f32 v59, v60, v59, v60
	v_mul_f32_e32 v59, 0xbfcc422a, v59
	v_mul_f32_e32 v59, 0x3fb8aa3b, v59
	v_mul_f32_e32 v58, 0x3d372713, v64
	v_exp_f32_e32 v62, v59
	v_mul_f32_e32 v59, 0x3d372713, v65
	v_mul_f32_e32 v58, v64, v58
	v_mul_f32_e32 v59, v65, v59
	v_fma_f32 v58, v64, v58, v64
	v_fma_f32 v59, v65, v59, v65
	v_mul_f32_e32 v58, 0xbfcc422a, v58
	v_mul_f32_e32 v59, 0xbfcc422a, v59
	v_mul_f32_e32 v58, 0x3fb8aa3b, v58
	v_mul_f32_e32 v59, 0x3fb8aa3b, v59
	v_exp_f32_e32 v58, v58
	v_exp_f32_e32 v59, v59
	s_nop 0
	v_pk_add_f32 v[58:59], v[58:59], 1.0 op_sel_hi:[1,0]
	s_nop 0
	s_nop 0
	v_rcp_f32_e32 v63, v59
	s_nop 0
	v_mul_f32_e32 v65, v65, v63
	s_nop 0
	v_rcp_f32_e32 v59, v58
	s_nop 0
	v_mul_f32_e32 v64, v64, v59
	v_mul_f32_e32 v58, 0x3d372713, v61
	v_mul_f32_e32 v58, v61, v58
	v_fma_f32 v58, v61, v58, v61
	v_mul_f32_e32 v58, 0xbfcc422a, v58
	v_mul_f32_e32 v58, 0x3fb8aa3b, v58
	v_exp_f32_e32 v63, v58
	s_nop 0
	v_pk_add_f32 v[58:59], v[62:63], 1.0 op_sel_hi:[1,0]
	s_nop 0
	s_nop 0
	v_rcp_f32_e32 v62, v59
	s_nop 0
	v_mul_f32_e32 v59, v61, v62
	s_mov_b64 s[12:13], 0x200000
	v_rcp_f32_e32 v61, v58
	s_nop 0
	v_mul_f32_e32 v58, v60, v61
	v_cvt_pk_bf16_f32 v63, v58, v59
	v_lshl_add_u64 v[58:59], v[122:123], 0, s[12:13]
	v_cvt_pk_bf16_f32 v61, v64, v65
	v_lshl_add_u64 v[64:65], v[58:59], 0, v[124:125]
	v_lshl_add_u64 v[64:65], v[64:65], 0, s[10:11]
	v_cvt_pk_bf16_f32 v60, v66, v67
	v_cvt_pk_bf16_f32 v62, v69, v68
	v_lshl_add_u64 v[64:65], v[64:65], 0, v[48:49]
	global_store_dwordx4 v[64:65], v[60:63], off
	s_nop 1
	v_mul_f32_e32 v61, 0x3d372713, v50
	v_mul_f32_e32 v61, v50, v61
	v_fma_f32 v61, v50, v61, v50
	v_mul_f32_e32 v61, 0xbfcc422a, v61
	v_mul_f32_e32 v61, 0x3fb8aa3b, v61
	v_mul_f32_e32 v60, 0x3d372713, v54
	v_exp_f32_e32 v62, v61
	v_mul_f32_e32 v61, 0x3d372713, v55
	v_mul_f32_e32 v60, v54, v60
	v_mul_f32_e32 v61, v55, v61
	v_fma_f32 v60, v54, v60, v54
	v_fma_f32 v61, v55, v61, v55
	v_mul_f32_e32 v60, 0xbfcc422a, v60
	v_mul_f32_e32 v61, 0xbfcc422a, v61
	v_mul_f32_e32 v60, 0x3fb8aa3b, v60
	v_mul_f32_e32 v61, 0x3fb8aa3b, v61
	v_exp_f32_e32 v60, v60
	v_exp_f32_e32 v61, v61
	s_nop 0
	v_pk_add_f32 v[60:61], v[60:61], 1.0 op_sel_hi:[1,0]
	s_nop 0
	s_nop 0
	v_rcp_f32_e32 v63, v61
	s_nop 0
	v_mul_f32_e32 v61, v55, v63
	s_nop 0
	v_rcp_f32_e32 v55, v60
	s_nop 0
	v_mul_f32_e32 v60, v54, v55
	v_mul_f32_e32 v54, 0x3d372713, v51
	v_mul_f32_e32 v54, v51, v54
	v_fma_f32 v54, v51, v54, v51
	v_mul_f32_e32 v54, 0xbfcc422a, v54
	v_mul_f32_e32 v54, 0x3fb8aa3b, v54
	v_exp_f32_e32 v63, v54
	s_nop 0
	v_pk_add_f32 v[54:55], v[62:63], 1.0 op_sel_hi:[1,0]
	s_nop 0
	s_nop 0
	v_rcp_f32_e32 v62, v55
	s_nop 0
	v_mul_f32_e32 v62, v51, v62
	s_nop 0
	v_rcp_f32_e32 v51, v54
	s_nop 0
	v_mul_f32_e32 v63, v50, v51
	v_mul_f32_e32 v51, 0x3d372713, v52
	v_mul_f32_e32 v51, v52, v51
	v_fma_f32 v51, v52, v51, v52
	v_mul_f32_e32 v51, 0xbfcc422a, v51
	v_mul_f32_e32 v51, 0x3fb8aa3b, v51
	v_mul_f32_e32 v50, 0x3d372713, v56
	v_exp_f32_e32 v54, v51
	v_mul_f32_e32 v51, 0x3d372713, v57
	v_mul_f32_e32 v50, v56, v50
	v_mul_f32_e32 v51, v57, v51
	v_fma_f32 v50, v56, v50, v56
	v_fma_f32 v51, v57, v51, v57
	v_mul_f32_e32 v50, 0xbfcc422a, v50
	v_mul_f32_e32 v51, 0xbfcc422a, v51
	v_mul_f32_e32 v50, 0x3fb8aa3b, v50
	v_mul_f32_e32 v51, 0x3fb8aa3b, v51
	v_exp_f32_e32 v50, v50
	v_exp_f32_e32 v51, v51
	s_nop 0
	v_pk_add_f32 v[50:51], v[50:51], 1.0 op_sel_hi:[1,0]
	s_nop 0
	s_nop 0
	v_rcp_f32_e32 v55, v51
	s_nop 0
	v_mul_f32_e32 v57, v57, v55
	s_nop 0
	v_rcp_f32_e32 v51, v50
	s_nop 0
	v_mul_f32_e32 v56, v56, v51
	v_mul_f32_e32 v50, 0x3d372713, v53
	v_mul_f32_e32 v50, v53, v50
	v_fma_f32 v50, v53, v50, v53
	v_mul_f32_e32 v50, 0xbfcc422a, v50
	v_mul_f32_e32 v50, 0x3fb8aa3b, v50
	v_exp_f32_e32 v55, v50
	s_nop 0
	v_pk_add_f32 v[50:51], v[54:55], 1.0 op_sel_hi:[1,0]
	s_nop 0
	s_nop 0
	v_rcp_f32_e32 v54, v51
	s_nop 0
	v_mul_f32_e32 v53, v53, v54
	s_nop 0
	v_rcp_f32_e32 v51, v50
	s_nop 0
	v_mul_f32_e32 v54, v52, v51
	v_cvt_pk_bf16_f32 v53, v54, v53
	v_lshl_add_u64 v[54:55], v[58:59], 0, v[114:115]
	v_lshl_add_u64 v[54:55], v[54:55], 0, s[10:11]
	v_cvt_pk_bf16_f32 v50, v60, v61
	v_cvt_pk_bf16_f32 v51, v56, v57
	v_cvt_pk_bf16_f32 v52, v63, v62
	v_lshl_add_u64 v[54:55], v[54:55], 0, v[48:49]
	global_store_dwordx4 v[54:55], v[50:53], off
	s_nop 1
	v_mul_f32_e32 v51, 0x3d372713, v40
	v_mul_f32_e32 v51, v40, v51
	v_fma_f32 v51, v40, v51, v40
	v_mul_f32_e32 v51, 0xbfcc422a, v51
	v_mul_f32_e32 v51, 0x3fb8aa3b, v51
	v_mul_f32_e32 v50, 0x3d372713, v44
	v_exp_f32_e32 v52, v51
	v_mul_f32_e32 v51, 0x3d372713, v45
	v_mul_f32_e32 v50, v44, v50
	v_mul_f32_e32 v51, v45, v51
	v_fma_f32 v50, v44, v50, v44
	v_fma_f32 v51, v45, v51, v45
	v_mul_f32_e32 v50, 0xbfcc422a, v50
	v_mul_f32_e32 v51, 0xbfcc422a, v51
	v_mul_f32_e32 v50, 0x3fb8aa3b, v50
	v_mul_f32_e32 v51, 0x3fb8aa3b, v51
	v_exp_f32_e32 v50, v50
	v_exp_f32_e32 v51, v51
	s_nop 0
	v_pk_add_f32 v[50:51], v[50:51], 1.0 op_sel_hi:[1,0]
	s_nop 0
	s_nop 0
	v_rcp_f32_e32 v53, v51
	s_nop 0
	v_mul_f32_e32 v51, v45, v53
	s_nop 0
	v_rcp_f32_e32 v45, v50
	s_nop 0
	v_mul_f32_e32 v50, v44, v45
	v_mul_f32_e32 v44, 0x3d372713, v41
	v_mul_f32_e32 v44, v41, v44
	v_fma_f32 v44, v41, v44, v41
	v_mul_f32_e32 v44, 0xbfcc422a, v44
	v_mul_f32_e32 v44, 0x3fb8aa3b, v44
	v_exp_f32_e32 v53, v44
	s_nop 0
	v_pk_add_f32 v[44:45], v[52:53], 1.0 op_sel_hi:[1,0]
	s_nop 0
	s_nop 0
	v_rcp_f32_e32 v52, v45
	s_nop 0
	v_mul_f32_e32 v52, v41, v52
	s_nop 0
	v_rcp_f32_e32 v41, v44
	s_nop 0
	v_mul_f32_e32 v53, v40, v41
	v_mul_f32_e32 v41, 0x3d372713, v42
	v_mul_f32_e32 v41, v42, v41
	v_fma_f32 v41, v42, v41, v42
	v_mul_f32_e32 v41, 0xbfcc422a, v41
	v_mul_f32_e32 v41, 0x3fb8aa3b, v41
	v_mul_f32_e32 v40, 0x3d372713, v46
	v_exp_f32_e32 v44, v41
	v_mul_f32_e32 v41, 0x3d372713, v47
	v_mul_f32_e32 v40, v46, v40
	v_mul_f32_e32 v41, v47, v41
	v_fma_f32 v40, v46, v40, v46
	v_fma_f32 v41, v47, v41, v47
	v_mul_f32_e32 v40, 0xbfcc422a, v40
	v_mul_f32_e32 v41, 0xbfcc422a, v41
	v_mul_f32_e32 v40, 0x3fb8aa3b, v40
	v_mul_f32_e32 v41, 0x3fb8aa3b, v41
	v_exp_f32_e32 v40, v40
	v_exp_f32_e32 v41, v41
	s_nop 0
	v_pk_add_f32 v[40:41], v[40:41], 1.0 op_sel_hi:[1,0]
	s_nop 0
	s_nop 0
	v_rcp_f32_e32 v45, v41
	s_nop 0
	v_mul_f32_e32 v47, v47, v45
	s_nop 0
	v_rcp_f32_e32 v41, v40
	s_nop 0
	v_mul_f32_e32 v46, v46, v41
	v_mul_f32_e32 v40, 0x3d372713, v43
	v_mul_f32_e32 v40, v43, v40
	v_fma_f32 v40, v43, v40, v43
	v_mul_f32_e32 v40, 0xbfcc422a, v40
	v_mul_f32_e32 v40, 0x3fb8aa3b, v40
	v_exp_f32_e32 v45, v40
	s_nop 0
	v_pk_add_f32 v[40:41], v[44:45], 1.0 op_sel_hi:[1,0]
	s_nop 0
	s_nop 0
	v_rcp_f32_e32 v44, v41
	s_nop 0
	v_mul_f32_e32 v41, v43, v44
	s_mov_b64 s[12:13], 0x240000
	v_rcp_f32_e32 v43, v40
	s_nop 0
	v_mul_f32_e32 v40, v42, v43
	v_cvt_pk_bf16_f32 v45, v40, v41
	v_lshl_add_u64 v[40:41], v[122:123], 0, s[12:13]
	v_cvt_pk_bf16_f32 v43, v46, v47
	v_lshl_add_u64 v[46:47], v[40:41], 0, v[124:125]
	v_lshl_add_u64 v[46:47], v[46:47], 0, s[10:11]
	v_cvt_pk_bf16_f32 v42, v50, v51
	v_cvt_pk_bf16_f32 v44, v53, v52
	v_lshl_add_u64 v[46:47], v[46:47], 0, v[48:49]
	global_store_dwordx4 v[46:47], v[42:45], off
	s_nop 1
	v_mul_f32_e32 v43, 0x3d372713, v32
	v_mul_f32_e32 v43, v32, v43
	v_fma_f32 v43, v32, v43, v32
	v_mul_f32_e32 v43, 0xbfcc422a, v43
	v_mul_f32_e32 v43, 0x3fb8aa3b, v43
	v_mul_f32_e32 v42, 0x3d372713, v36
	v_exp_f32_e32 v44, v43
	v_mul_f32_e32 v43, 0x3d372713, v37
	v_mul_f32_e32 v42, v36, v42
	v_mul_f32_e32 v43, v37, v43
	v_fma_f32 v42, v36, v42, v36
	v_fma_f32 v43, v37, v43, v37
	v_mul_f32_e32 v42, 0xbfcc422a, v42
	v_mul_f32_e32 v43, 0xbfcc422a, v43
	v_mul_f32_e32 v42, 0x3fb8aa3b, v42
	v_mul_f32_e32 v43, 0x3fb8aa3b, v43
	v_exp_f32_e32 v42, v42
	v_exp_f32_e32 v43, v43
	s_nop 0
	v_pk_add_f32 v[42:43], v[42:43], 1.0 op_sel_hi:[1,0]
	s_nop 0
	s_nop 0
	v_rcp_f32_e32 v45, v43
	s_nop 0
	v_mul_f32_e32 v43, v37, v45
	s_nop 0
	v_rcp_f32_e32 v37, v42
	s_nop 0
	v_mul_f32_e32 v42, v36, v37
	v_mul_f32_e32 v36, 0x3d372713, v33
	v_mul_f32_e32 v36, v33, v36
	v_fma_f32 v36, v33, v36, v33
	v_mul_f32_e32 v36, 0xbfcc422a, v36
	v_mul_f32_e32 v36, 0x3fb8aa3b, v36
	v_exp_f32_e32 v45, v36
	s_nop 0
	v_pk_add_f32 v[36:37], v[44:45], 1.0 op_sel_hi:[1,0]
	s_nop 0
	s_nop 0
	v_rcp_f32_e32 v44, v37
	s_nop 0
	v_mul_f32_e32 v44, v33, v44
	s_nop 0
	v_rcp_f32_e32 v33, v36
	s_nop 0
	v_mul_f32_e32 v45, v32, v33
	v_mul_f32_e32 v33, 0x3d372713, v34
	v_mul_f32_e32 v33, v34, v33
	v_fma_f32 v33, v34, v33, v34
	v_mul_f32_e32 v33, 0xbfcc422a, v33
	v_mul_f32_e32 v33, 0x3fb8aa3b, v33
	v_mul_f32_e32 v32, 0x3d372713, v38
	v_exp_f32_e32 v36, v33
	v_mul_f32_e32 v33, 0x3d372713, v39
	v_mul_f32_e32 v32, v38, v32
	v_mul_f32_e32 v33, v39, v33
	v_fma_f32 v32, v38, v32, v38
	v_fma_f32 v33, v39, v33, v39
	v_mul_f32_e32 v32, 0xbfcc422a, v32
	v_mul_f32_e32 v33, 0xbfcc422a, v33
	v_mul_f32_e32 v32, 0x3fb8aa3b, v32
	v_mul_f32_e32 v33, 0x3fb8aa3b, v33
	v_exp_f32_e32 v32, v32
	v_exp_f32_e32 v33, v33
	s_nop 0
	v_pk_add_f32 v[32:33], v[32:33], 1.0 op_sel_hi:[1,0]
	s_nop 0
	s_nop 0
	v_rcp_f32_e32 v37, v33
	s_nop 0
	v_mul_f32_e32 v39, v39, v37
	s_nop 0
	v_rcp_f32_e32 v33, v32
	s_nop 0
	v_mul_f32_e32 v38, v38, v33
	v_mul_f32_e32 v32, 0x3d372713, v35
	v_mul_f32_e32 v32, v35, v32
	v_fma_f32 v32, v35, v32, v35
	v_mul_f32_e32 v32, 0xbfcc422a, v32
	v_mul_f32_e32 v32, 0x3fb8aa3b, v32
	v_exp_f32_e32 v37, v32
	s_nop 0
	v_pk_add_f32 v[32:33], v[36:37], 1.0 op_sel_hi:[1,0]
	s_nop 0
	s_nop 0
	v_rcp_f32_e32 v36, v33
	s_nop 0
	v_mul_f32_e32 v35, v35, v36
	s_nop 0
	v_rcp_f32_e32 v33, v32
	s_nop 0
	v_mul_f32_e32 v36, v34, v33
	v_cvt_pk_bf16_f32 v35, v36, v35
	v_lshl_add_u64 v[36:37], v[40:41], 0, v[114:115]
	v_lshl_add_u64 v[36:37], v[36:37], 0, s[10:11]
	v_cvt_pk_bf16_f32 v32, v42, v43
	v_cvt_pk_bf16_f32 v33, v38, v39
	v_cvt_pk_bf16_f32 v34, v45, v44
	v_lshl_add_u64 v[36:37], v[36:37], 0, v[48:49]
	global_store_dwordx4 v[36:37], v[32:35], off
	s_nop 1
	v_mul_f32_e32 v33, 0x3d372713, v24
	v_mul_f32_e32 v33, v24, v33
	v_fma_f32 v33, v24, v33, v24
	v_mul_f32_e32 v33, 0xbfcc422a, v33
	v_mul_f32_e32 v33, 0x3fb8aa3b, v33
	v_mul_f32_e32 v32, 0x3d372713, v28
	v_exp_f32_e32 v34, v33
	v_mul_f32_e32 v33, 0x3d372713, v29
	v_mul_f32_e32 v32, v28, v32
	v_mul_f32_e32 v33, v29, v33
	v_fma_f32 v32, v28, v32, v28
	v_fma_f32 v33, v29, v33, v29
	v_mul_f32_e32 v32, 0xbfcc422a, v32
	v_mul_f32_e32 v33, 0xbfcc422a, v33
	v_mul_f32_e32 v32, 0x3fb8aa3b, v32
	v_mul_f32_e32 v33, 0x3fb8aa3b, v33
	v_exp_f32_e32 v32, v32
	v_exp_f32_e32 v33, v33
	s_nop 0
	v_pk_add_f32 v[32:33], v[32:33], 1.0 op_sel_hi:[1,0]
	s_nop 0
	s_nop 0
	v_rcp_f32_e32 v35, v33
	s_nop 0
	v_mul_f32_e32 v33, v29, v35
	s_nop 0
	v_rcp_f32_e32 v29, v32
	s_nop 0
	v_mul_f32_e32 v32, v28, v29
	v_mul_f32_e32 v28, 0x3d372713, v25
	v_mul_f32_e32 v28, v25, v28
	v_fma_f32 v28, v25, v28, v25
	v_mul_f32_e32 v28, 0xbfcc422a, v28
	v_mul_f32_e32 v28, 0x3fb8aa3b, v28
	v_exp_f32_e32 v35, v28
	s_nop 0
	v_pk_add_f32 v[28:29], v[34:35], 1.0 op_sel_hi:[1,0]
	s_nop 0
	s_nop 0
	v_rcp_f32_e32 v34, v29
	s_nop 0
	v_mul_f32_e32 v34, v25, v34
	s_nop 0
	v_rcp_f32_e32 v25, v28
	s_nop 0
	v_mul_f32_e32 v35, v24, v25
	v_mul_f32_e32 v25, 0x3d372713, v26
	v_mul_f32_e32 v25, v26, v25
	v_fma_f32 v25, v26, v25, v26
	v_mul_f32_e32 v25, 0xbfcc422a, v25
	v_mul_f32_e32 v25, 0x3fb8aa3b, v25
	v_mul_f32_e32 v24, 0x3d372713, v30
	v_exp_f32_e32 v28, v25
	v_mul_f32_e32 v25, 0x3d372713, v31
	v_mul_f32_e32 v24, v30, v24
	v_mul_f32_e32 v25, v31, v25
	v_fma_f32 v24, v30, v24, v30
	v_fma_f32 v25, v31, v25, v31
	v_mul_f32_e32 v24, 0xbfcc422a, v24
	v_mul_f32_e32 v25, 0xbfcc422a, v25
	v_mul_f32_e32 v24, 0x3fb8aa3b, v24
	v_mul_f32_e32 v25, 0x3fb8aa3b, v25
	v_exp_f32_e32 v24, v24
	v_exp_f32_e32 v25, v25
	s_nop 0
	v_pk_add_f32 v[24:25], v[24:25], 1.0 op_sel_hi:[1,0]
	s_nop 0
	s_nop 0
	v_rcp_f32_e32 v29, v25
	s_nop 0
	v_mul_f32_e32 v31, v31, v29
	s_nop 0
	v_rcp_f32_e32 v25, v24
	s_nop 0
	v_mul_f32_e32 v30, v30, v25
	v_mul_f32_e32 v24, 0x3d372713, v27
	v_mul_f32_e32 v24, v27, v24
	v_fma_f32 v24, v27, v24, v27
	v_mul_f32_e32 v24, 0xbfcc422a, v24
	v_mul_f32_e32 v24, 0x3fb8aa3b, v24
	v_exp_f32_e32 v29, v24
	s_nop 0
	v_pk_add_f32 v[24:25], v[28:29], 1.0 op_sel_hi:[1,0]
	s_nop 0
	s_nop 0
	v_rcp_f32_e32 v28, v25
	s_nop 0
	v_mul_f32_e32 v25, v27, v28
	s_mov_b64 s[12:13], 0x280000
	v_rcp_f32_e32 v27, v24
	s_nop 0
	v_mul_f32_e32 v24, v26, v27
	v_cvt_pk_bf16_f32 v29, v24, v25
	v_lshl_add_u64 v[24:25], v[122:123], 0, s[12:13]
	v_cvt_pk_bf16_f32 v27, v30, v31
	v_lshl_add_u64 v[30:31], v[24:25], 0, v[124:125]
	v_lshl_add_u64 v[30:31], v[30:31], 0, s[10:11]
	v_cvt_pk_bf16_f32 v26, v32, v33
	v_cvt_pk_bf16_f32 v28, v35, v34
	v_lshl_add_u64 v[30:31], v[30:31], 0, v[48:49]
	global_store_dwordx4 v[30:31], v[26:29], off
	s_nop 1
	v_mul_f32_e32 v27, 0x3d372713, v16
	v_mul_f32_e32 v27, v16, v27
	v_fma_f32 v27, v16, v27, v16
	v_mul_f32_e32 v27, 0xbfcc422a, v27
	v_mul_f32_e32 v27, 0x3fb8aa3b, v27
	v_mul_f32_e32 v26, 0x3d372713, v20
	v_exp_f32_e32 v28, v27
	v_mul_f32_e32 v27, 0x3d372713, v21
	v_mul_f32_e32 v26, v20, v26
	v_mul_f32_e32 v27, v21, v27
	v_fma_f32 v26, v20, v26, v20
	v_fma_f32 v27, v21, v27, v21
	v_mul_f32_e32 v26, 0xbfcc422a, v26
	v_mul_f32_e32 v27, 0xbfcc422a, v27
	v_mul_f32_e32 v26, 0x3fb8aa3b, v26
	v_mul_f32_e32 v27, 0x3fb8aa3b, v27
	v_exp_f32_e32 v26, v26
	v_exp_f32_e32 v27, v27
	s_nop 0
	v_pk_add_f32 v[26:27], v[26:27], 1.0 op_sel_hi:[1,0]
	s_nop 0
	s_nop 0
	v_rcp_f32_e32 v29, v27
	s_nop 0
	v_mul_f32_e32 v27, v21, v29
	s_nop 0
	v_rcp_f32_e32 v21, v26
	s_nop 0
	v_mul_f32_e32 v26, v20, v21
	v_mul_f32_e32 v20, 0x3d372713, v17
	v_mul_f32_e32 v20, v17, v20
	v_fma_f32 v20, v17, v20, v17
	v_mul_f32_e32 v20, 0xbfcc422a, v20
	v_mul_f32_e32 v20, 0x3fb8aa3b, v20
	v_exp_f32_e32 v29, v20
	s_nop 0
	v_pk_add_f32 v[20:21], v[28:29], 1.0 op_sel_hi:[1,0]
	s_nop 0
	s_nop 0
	v_rcp_f32_e32 v28, v21
	s_nop 0
	v_mul_f32_e32 v28, v17, v28
	s_nop 0
	v_rcp_f32_e32 v17, v20
	s_nop 0
	v_mul_f32_e32 v29, v16, v17
	v_mul_f32_e32 v17, 0x3d372713, v18
	v_mul_f32_e32 v17, v18, v17
	v_fma_f32 v17, v18, v17, v18
	v_mul_f32_e32 v17, 0xbfcc422a, v17
	v_mul_f32_e32 v17, 0x3fb8aa3b, v17
	v_mul_f32_e32 v16, 0x3d372713, v22
	v_exp_f32_e32 v20, v17
	v_mul_f32_e32 v17, 0x3d372713, v23
	v_mul_f32_e32 v16, v22, v16
	v_mul_f32_e32 v17, v23, v17
	v_fma_f32 v16, v22, v16, v22
	v_fma_f32 v17, v23, v17, v23
	v_mul_f32_e32 v16, 0xbfcc422a, v16
	v_mul_f32_e32 v17, 0xbfcc422a, v17
	v_mul_f32_e32 v16, 0x3fb8aa3b, v16
	v_mul_f32_e32 v17, 0x3fb8aa3b, v17
	v_exp_f32_e32 v16, v16
	v_exp_f32_e32 v17, v17
	s_nop 0
	v_pk_add_f32 v[16:17], v[16:17], 1.0 op_sel_hi:[1,0]
	s_nop 0
	s_nop 0
	v_rcp_f32_e32 v21, v17
	s_nop 0
	v_mul_f32_e32 v23, v23, v21
	s_nop 0
	v_rcp_f32_e32 v17, v16
	s_nop 0
	v_mul_f32_e32 v22, v22, v17
	v_mul_f32_e32 v16, 0x3d372713, v19
	v_mul_f32_e32 v16, v19, v16
	v_fma_f32 v16, v19, v16, v19
	v_mul_f32_e32 v16, 0xbfcc422a, v16
	v_mul_f32_e32 v16, 0x3fb8aa3b, v16
	v_exp_f32_e32 v21, v16
	s_nop 0
	v_pk_add_f32 v[16:17], v[20:21], 1.0 op_sel_hi:[1,0]
	s_nop 0
	s_nop 0
	v_rcp_f32_e32 v20, v17
	s_nop 0
	v_mul_f32_e32 v19, v19, v20
	s_nop 0
	v_rcp_f32_e32 v17, v16
	s_nop 0
	v_mul_f32_e32 v20, v18, v17
	v_cvt_pk_bf16_f32 v19, v20, v19
	v_lshl_add_u64 v[20:21], v[24:25], 0, v[114:115]
	v_lshl_add_u64 v[20:21], v[20:21], 0, s[10:11]
	v_cvt_pk_bf16_f32 v16, v26, v27
	v_cvt_pk_bf16_f32 v17, v22, v23
	v_cvt_pk_bf16_f32 v18, v29, v28
	v_lshl_add_u64 v[20:21], v[20:21], 0, v[48:49]
	global_store_dwordx4 v[20:21], v[16:19], off
	s_nop 1
	v_mul_f32_e32 v17, 0x3d372713, v8
	v_mul_f32_e32 v17, v8, v17
	v_fma_f32 v17, v8, v17, v8
	v_mul_f32_e32 v17, 0xbfcc422a, v17
	v_mul_f32_e32 v17, 0x3fb8aa3b, v17
	v_mul_f32_e32 v16, 0x3d372713, v12
	v_exp_f32_e32 v18, v17
	v_mul_f32_e32 v17, 0x3d372713, v13
	v_mul_f32_e32 v16, v12, v16
	v_mul_f32_e32 v17, v13, v17
	v_fma_f32 v16, v12, v16, v12
	v_fma_f32 v17, v13, v17, v13
	v_mul_f32_e32 v16, 0xbfcc422a, v16
	v_mul_f32_e32 v17, 0xbfcc422a, v17
	v_mul_f32_e32 v16, 0x3fb8aa3b, v16
	v_mul_f32_e32 v17, 0x3fb8aa3b, v17
	v_exp_f32_e32 v16, v16
	v_exp_f32_e32 v17, v17
	s_nop 0
	v_pk_add_f32 v[16:17], v[16:17], 1.0 op_sel_hi:[1,0]
	s_nop 0
	s_nop 0
	v_rcp_f32_e32 v19, v17
	s_nop 0
	v_mul_f32_e32 v17, v13, v19
	s_nop 0
	v_rcp_f32_e32 v13, v16
	s_nop 0
	v_mul_f32_e32 v16, v12, v13
	v_mul_f32_e32 v12, 0x3d372713, v9
	v_mul_f32_e32 v12, v9, v12
	v_fma_f32 v12, v9, v12, v9
	v_mul_f32_e32 v12, 0xbfcc422a, v12
	v_mul_f32_e32 v12, 0x3fb8aa3b, v12
	v_exp_f32_e32 v19, v12
	s_nop 0
	v_pk_add_f32 v[12:13], v[18:19], 1.0 op_sel_hi:[1,0]
	s_nop 0
	s_nop 0
	v_rcp_f32_e32 v18, v13
	s_nop 0
	v_mul_f32_e32 v18, v9, v18
	s_nop 0
	v_rcp_f32_e32 v9, v12
	s_nop 0
	v_mul_f32_e32 v19, v8, v9
	v_mul_f32_e32 v9, 0x3d372713, v10
	v_mul_f32_e32 v9, v10, v9
	v_fma_f32 v9, v10, v9, v10
	v_mul_f32_e32 v9, 0xbfcc422a, v9
	v_mul_f32_e32 v9, 0x3fb8aa3b, v9
	v_mul_f32_e32 v8, 0x3d372713, v14
	v_exp_f32_e32 v12, v9
	v_mul_f32_e32 v9, 0x3d372713, v15
	v_mul_f32_e32 v8, v14, v8
	v_mul_f32_e32 v9, v15, v9
	v_fma_f32 v8, v14, v8, v14
	v_fma_f32 v9, v15, v9, v15
	v_mul_f32_e32 v8, 0xbfcc422a, v8
	v_mul_f32_e32 v9, 0xbfcc422a, v9
	v_mul_f32_e32 v8, 0x3fb8aa3b, v8
	v_mul_f32_e32 v9, 0x3fb8aa3b, v9
	v_exp_f32_e32 v8, v8
	v_exp_f32_e32 v9, v9
	s_nop 0
	v_pk_add_f32 v[8:9], v[8:9], 1.0 op_sel_hi:[1,0]
	s_nop 0
	s_nop 0
	v_rcp_f32_e32 v13, v9
	s_nop 0
	v_mul_f32_e32 v15, v15, v13
	s_nop 0
	v_rcp_f32_e32 v9, v8
	s_nop 0
	v_mul_f32_e32 v14, v14, v9
	v_mul_f32_e32 v8, 0x3d372713, v11
	v_mul_f32_e32 v8, v11, v8
	v_fma_f32 v8, v11, v8, v11
	v_mul_f32_e32 v8, 0xbfcc422a, v8
	v_mul_f32_e32 v8, 0x3fb8aa3b, v8
	v_exp_f32_e32 v13, v8
	s_nop 0
	v_pk_add_f32 v[8:9], v[12:13], 1.0 op_sel_hi:[1,0]
	s_nop 0
	s_nop 0
	v_rcp_f32_e32 v12, v9
	s_nop 0
	v_mul_f32_e32 v9, v11, v12
	s_mov_b64 s[12:13], 0x2c0000
	v_rcp_f32_e32 v11, v8
	s_nop 0
	v_mul_f32_e32 v8, v10, v11
	v_cvt_pk_bf16_f32 v13, v8, v9
	v_lshl_add_u64 v[8:9], v[122:123], 0, s[12:13]
	v_cvt_pk_bf16_f32 v11, v14, v15
	v_lshl_add_u64 v[14:15], v[8:9], 0, v[124:125]
	v_lshl_add_u64 v[14:15], v[14:15], 0, s[10:11]
	v_cvt_pk_bf16_f32 v10, v16, v17
	v_cvt_pk_bf16_f32 v12, v19, v18
	v_lshl_add_u64 v[14:15], v[14:15], 0, v[48:49]
	global_store_dwordx4 v[14:15], v[10:13], off
	s_nop 1
	v_mul_f32_e32 v11, 0x3d372713, v0
	v_mul_f32_e32 v11, v0, v11
	v_fma_f32 v11, v0, v11, v0
	v_mul_f32_e32 v11, 0xbfcc422a, v11
	v_mul_f32_e32 v11, 0x3fb8aa3b, v11
	v_mul_f32_e32 v10, 0x3d372713, v4
	v_exp_f32_e32 v12, v11
	v_mul_f32_e32 v11, 0x3d372713, v5
	v_mul_f32_e32 v10, v4, v10
	v_mul_f32_e32 v11, v5, v11
	v_fma_f32 v10, v4, v10, v4
	v_fma_f32 v11, v5, v11, v5
	v_mul_f32_e32 v10, 0xbfcc422a, v10
	v_mul_f32_e32 v11, 0xbfcc422a, v11
	v_mul_f32_e32 v10, 0x3fb8aa3b, v10
	v_mul_f32_e32 v11, 0x3fb8aa3b, v11
	v_exp_f32_e32 v10, v10
	v_exp_f32_e32 v11, v11
	s_nop 0
	v_pk_add_f32 v[10:11], v[10:11], 1.0 op_sel_hi:[1,0]
	s_nop 0
	s_nop 0
	v_rcp_f32_e32 v13, v11
	s_nop 0
	v_mul_f32_e32 v11, v5, v13
	s_nop 0
	v_rcp_f32_e32 v5, v10
	s_nop 0
	v_mul_f32_e32 v10, v4, v5
	v_mul_f32_e32 v4, 0x3d372713, v1
	v_mul_f32_e32 v4, v1, v4
	v_fma_f32 v4, v1, v4, v1
	v_mul_f32_e32 v4, 0xbfcc422a, v4
	v_mul_f32_e32 v4, 0x3fb8aa3b, v4
	v_exp_f32_e32 v13, v4
	s_nop 0
	v_pk_add_f32 v[4:5], v[12:13], 1.0 op_sel_hi:[1,0]
	s_nop 0
	s_nop 0
	v_rcp_f32_e32 v12, v5
	s_nop 0
	v_mul_f32_e32 v12, v1, v12
	s_nop 0
	v_rcp_f32_e32 v1, v4
	s_nop 0
	v_mul_f32_e32 v13, v0, v1
	v_mul_f32_e32 v1, 0x3d372713, v2
	v_mul_f32_e32 v1, v2, v1
	v_fma_f32 v1, v2, v1, v2
	v_mul_f32_e32 v1, 0xbfcc422a, v1
	v_mul_f32_e32 v1, 0x3fb8aa3b, v1
	v_mul_f32_e32 v0, 0x3d372713, v6
	v_exp_f32_e32 v4, v1
	v_mul_f32_e32 v1, 0x3d372713, v7
	v_mul_f32_e32 v0, v6, v0
	v_mul_f32_e32 v1, v7, v1
	v_fma_f32 v0, v6, v0, v6
	v_fma_f32 v1, v7, v1, v7
	v_mul_f32_e32 v0, 0xbfcc422a, v0
	v_mul_f32_e32 v1, 0xbfcc422a, v1
	v_mul_f32_e32 v0, 0x3fb8aa3b, v0
	v_mul_f32_e32 v1, 0x3fb8aa3b, v1
	v_exp_f32_e32 v0, v0
	v_exp_f32_e32 v1, v1
	s_nop 0
	v_pk_add_f32 v[0:1], v[0:1], 1.0 op_sel_hi:[1,0]
	s_nop 0
	s_nop 0
	v_rcp_f32_e32 v5, v1
	s_nop 0
	v_mul_f32_e32 v7, v7, v5
	s_nop 0
	v_rcp_f32_e32 v1, v0
	s_nop 0
	v_mul_f32_e32 v6, v6, v1
	v_mul_f32_e32 v0, 0x3d372713, v3
	v_mul_f32_e32 v0, v3, v0
	v_fma_f32 v0, v3, v0, v3
	v_mul_f32_e32 v0, 0xbfcc422a, v0
	v_mul_f32_e32 v0, 0x3fb8aa3b, v0
	v_exp_f32_e32 v5, v0
	s_nop 0
	v_pk_add_f32 v[0:1], v[4:5], 1.0 op_sel_hi:[1,0]
	s_nop 0
	s_nop 0
	v_rcp_f32_e32 v4, v1
	s_nop 0
	v_mul_f32_e32 v3, v3, v4
	s_mov_b64 s[12:13], s[6:7]
	v_rcp_f32_e32 v1, v0
	s_nop 0
	v_mul_f32_e32 v4, v2, v1
	v_cvt_pk_bf16_f32 v3, v4, v3
	v_lshl_add_u64 v[4:5], v[8:9], 0, v[114:115]
	v_lshl_add_u64 v[4:5], v[4:5], 0, s[10:11]
	v_cvt_pk_bf16_f32 v0, v10, v11
	v_cvt_pk_bf16_f32 v1, v6, v7
	v_cvt_pk_bf16_f32 v2, v13, v12
	v_lshl_add_u64 v[4:5], v[4:5], 0, v[48:49]
	s_and_b64 vcc, exec, s[8:9]
	s_mov_b64 s[10:11], s[4:5]
	global_store_dwordx4 v[4:5], v[0:3], off
	s_cbranch_vccz .LBB0_819
	s_waitcnt vmcnt(0)
	s_cmpk_gt_u32 s18, 0xff
	s_cbranch_scc1 .LBB0_826
	s_barrier

.LBB0_1056:
	s_add_i32 s56, s28, 2
	s_add_u32 s29, s24, 0xfffc0080
	s_addc_u32 s30, s25, -1
	s_add_i32 s57, 0, 0x10000
	ds_read_b128 v[130:133], v203
	ds_read_b128 v[134:137], v203 offset:1024
	ds_read_b128 v[138:141], v203 offset:2048
	ds_read_b128 v[142:145], v203 offset:3072
	s_cmp_eq_u32 s17, s28
	s_cselect_b32 s28, s22, s19
	s_cselect_b32 s31, s21, s30
	s_cselect_b32 s30, s20, s29
	s_cselect_b32 s29, s23, s27
	s_add_i32 m0, s39, 0xc000
	ds_read_b128 v[146:149], v217
	ds_read_b128 v[150:153], v217 offset:1024
	ds_read_b128 v[154:157], v217 offset:2048
	ds_read_b128 v[158:161], v217 offset:3072
	ds_read_b128 v[162:165], v217 offset:4096
	ds_read_b128 v[166:169], v217 offset:5120
	ds_read_b128 v[170:173], v217 offset:6144
	ds_read_b128 v[174:177], v217 offset:7168
	global_load_lds_dwordx4 v204, s[24:25]
	s_add_i32 m0, s39, 0xe000
	s_nop 0
	global_load_lds_dwordx4 v206, s[24:25]
	s_waitcnt lgkmcnt(8)
	s_barrier
	s_waitcnt lgkmcnt(0)
	s_setprio 1
	s_waitcnt lgkmcnt(0)
	v_mfma_f32_16x16x32_bf16 v[126:129], v[130:133], v[146:149], v[126:129]
	v_mfma_f32_16x16x32_bf16 v[122:125], v[138:141], v[146:149], v[122:125]
	v_mfma_f32_16x16x32_bf16 v[118:121], v[130:133], v[154:157], v[118:121]
	v_mfma_f32_16x16x32_bf16 v[114:117], v[138:141], v[154:157], v[114:117]
	v_mfma_f32_16x16x32_bf16 v[102:105], v[130:133], v[162:165], v[102:105]
	v_mfma_f32_16x16x32_bf16 v[98:101], v[138:141], v[162:165], v[98:101]
	v_mfma_f32_16x16x32_bf16 v[86:89], v[130:133], v[170:173], v[86:89]
	v_mfma_f32_16x16x32_bf16 v[82:85], v[138:141], v[170:173], v[82:85]
	v_mfma_f32_16x16x32_bf16 v[126:129], v[134:137], v[150:153], v[126:129]
	v_mfma_f32_16x16x32_bf16 v[122:125], v[142:145], v[150:153], v[122:125]
	v_mfma_f32_16x16x32_bf16 v[118:121], v[134:137], v[158:161], v[118:121]
	v_mfma_f32_16x16x32_bf16 v[114:117], v[142:145], v[158:161], v[114:117]
	v_mfma_f32_16x16x32_bf16 v[102:105], v[134:137], v[166:169], v[102:105]
	v_mfma_f32_16x16x32_bf16 v[98:101], v[142:145], v[166:169], v[98:101]
	v_mfma_f32_16x16x32_bf16 v[86:89], v[134:137], v[174:177], v[86:89]
	v_mfma_f32_16x16x32_bf16 v[82:85], v[142:145], v[174:177], v[82:85]
	s_setprio 0
	s_barrier
	s_add_i32 s60, 0, 0x14000
	s_add_i32 s57, s57, s38
	s_mov_b32 m0, s57
	ds_read_b128 v[178:181], v203 offset:16384
	ds_read_b128 v[182:185], v203 offset:17408
	ds_read_b128 v[186:189], v203 offset:18432
	ds_read_b128 v[190:193], v203 offset:19456
	global_load_lds_dwordx4 v48, s[28:29]
	s_add_i32 m0, s57, 0x2000
	s_nop 0
	global_load_lds_dwordx4 v202, s[28:29]
	s_barrier
	s_waitcnt lgkmcnt(0)
	s_setprio 1
	s_waitcnt lgkmcnt(0)
	v_mfma_f32_16x16x32_bf16 v[110:113], v[178:181], v[146:149], v[110:113]
	v_mfma_f32_16x16x32_bf16 v[106:109], v[186:189], v[146:149], v[106:109]
	v_mfma_f32_16x16x32_bf16 v[94:97], v[178:181], v[154:157], v[94:97]
	v_mfma_f32_16x16x32_bf16 v[90:93], v[186:189], v[154:157], v[90:93]
	v_mfma_f32_16x16x32_bf16 v[78:81], v[178:181], v[162:165], v[78:81]
	v_mfma_f32_16x16x32_bf16 v[74:77], v[186:189], v[162:165], v[74:77]
	v_mfma_f32_16x16x32_bf16 v[70:73], v[178:181], v[170:173], v[70:73]
	v_mfma_f32_16x16x32_bf16 v[66:69], v[186:189], v[170:173], v[66:69]
	v_mfma_f32_16x16x32_bf16 v[110:113], v[182:185], v[150:153], v[110:113]
	v_mfma_f32_16x16x32_bf16 v[106:109], v[190:193], v[150:153], v[106:109]
	v_mfma_f32_16x16x32_bf16 v[94:97], v[182:185], v[158:161], v[94:97]
	v_mfma_f32_16x16x32_bf16 v[90:93], v[190:193], v[158:161], v[90:93]
	v_mfma_f32_16x16x32_bf16 v[78:81], v[182:185], v[166:169], v[78:81]
	v_mfma_f32_16x16x32_bf16 v[74:77], v[190:193], v[166:169], v[74:77]
	v_mfma_f32_16x16x32_bf16 v[70:73], v[182:185], v[174:177], v[70:73]
	v_mfma_f32_16x16x32_bf16 v[66:69], v[190:193], v[174:177], v[66:69]
	s_setprio 0
	s_mov_b32 m0, s39
	s_add_u32 s84, s30, s66
	s_addc_u32 s85, s31, s67
	s_barrier
	ds_read_b128 v[146:149], v217 offset:16384
	ds_read_b128 v[150:153], v217 offset:17408
	ds_read_b128 v[154:157], v217 offset:18432
	ds_read_b128 v[158:161], v217 offset:19456
	ds_read_b128 v[162:165], v217 offset:20480
	ds_read_b128 v[166:169], v217 offset:21504
	ds_read_b128 v[170:173], v217 offset:22528
	ds_read_b128 v[174:177], v217 offset:23552
	global_load_lds_dwordx4 v198, s[30:31]
	s_mov_b32 m0, s40
	s_nop 0
	global_load_lds_dwordx4 v200, s[30:31]
	s_barrier
	s_waitcnt lgkmcnt(0)
	s_setprio 1
	s_waitcnt lgkmcnt(0)
	v_mfma_f32_16x16x32_bf16 v[62:65], v[130:133], v[146:149], v[62:65]
	v_mfma_f32_16x16x32_bf16 v[58:61], v[138:141], v[146:149], v[58:61]
	v_mfma_f32_16x16x32_bf16 v[54:57], v[130:133], v[154:157], v[54:57]
	v_mfma_f32_16x16x32_bf16 v[50:53], v[138:141], v[154:157], v[50:53]
	v_mfma_f32_16x16x32_bf16 v[36:39], v[130:133], v[162:165], v[36:39]
	v_mfma_f32_16x16x32_bf16 v[32:35], v[138:141], v[162:165], v[32:35]
	v_mfma_f32_16x16x32_bf16 v[20:23], v[130:133], v[170:173], v[20:23]
	v_mfma_f32_16x16x32_bf16 v[16:19], v[138:141], v[170:173], v[16:19]
	v_mfma_f32_16x16x32_bf16 v[62:65], v[134:137], v[150:153], v[62:65]
	v_mfma_f32_16x16x32_bf16 v[58:61], v[142:145], v[150:153], v[58:61]
	v_mfma_f32_16x16x32_bf16 v[54:57], v[134:137], v[158:161], v[54:57]
	v_mfma_f32_16x16x32_bf16 v[50:53], v[142:145], v[158:161], v[50:53]
	v_mfma_f32_16x16x32_bf16 v[36:39], v[134:137], v[166:169], v[36:39]
	v_mfma_f32_16x16x32_bf16 v[32:35], v[142:145], v[166:169], v[32:35]
	v_mfma_f32_16x16x32_bf16 v[20:23], v[134:137], v[174:177], v[20:23]
	v_mfma_f32_16x16x32_bf16 v[16:19], v[142:145], v[174:177], v[16:19]
	s_setprio 0
	s_barrier
	s_add_u32 s58, s28, 0x40000
	s_addc_u32 s59, s29, 0
	s_add_i32 s57, s60, s38
	s_mov_b32 m0, s57
	s_nop 0
	global_load_lds_dwordx4 v48, s[58:59]
	s_add_i32 m0, s57, 0x2000
	s_nop 0
	global_load_lds_dwordx4 v202, s[58:59]
	s_waitcnt vmcnt(6)
	s_barrier
	s_setprio 1
	v_mfma_f32_16x16x32_bf16 v[44:47], v[178:181], v[146:149], v[44:47]
	v_mfma_f32_16x16x32_bf16 v[40:43], v[186:189], v[146:149], v[40:43]
	v_mfma_f32_16x16x32_bf16 v[28:31], v[178:181], v[154:157], v[28:31]
	v_mfma_f32_16x16x32_bf16 v[24:27], v[186:189], v[154:157], v[24:27]
	v_mfma_f32_16x16x32_bf16 v[12:15], v[178:181], v[162:165], v[12:15]
	v_mfma_f32_16x16x32_bf16 v[8:11], v[186:189], v[162:165], v[8:11]
	v_mfma_f32_16x16x32_bf16 v[4:7], v[178:181], v[170:173], v[4:7]
	v_mfma_f32_16x16x32_bf16 v[0:3], v[186:189], v[170:173], v[0:3]
	v_mfma_f32_16x16x32_bf16 v[44:47], v[182:185], v[150:153], v[44:47]
	v_mfma_f32_16x16x32_bf16 v[40:43], v[190:193], v[150:153], v[40:43]
	v_mfma_f32_16x16x32_bf16 v[28:31], v[182:185], v[158:161], v[28:31]
	v_mfma_f32_16x16x32_bf16 v[24:27], v[190:193], v[158:161], v[24:27]
	v_mfma_f32_16x16x32_bf16 v[12:15], v[182:185], v[166:169], v[12:15]
	v_mfma_f32_16x16x32_bf16 v[8:11], v[190:193], v[166:169], v[8:11]
	v_mfma_f32_16x16x32_bf16 v[4:7], v[182:185], v[174:177], v[4:7]
	v_mfma_f32_16x16x32_bf16 v[0:3], v[190:193], v[174:177], v[0:3]
	s_setprio 0
	s_add_i32 s57, 0, 0x18000
	s_barrier
	ds_read_b128 v[130:133], v203 offset:32768
	ds_read_b128 v[134:137], v203 offset:33792
	ds_read_b128 v[138:141], v203 offset:34816
	ds_read_b128 v[142:145], v203 offset:35840
	s_add_u32 s30, s30, 0x40000
	s_addc_u32 s31, s31, 0
	s_mov_b32 m0, s41
	ds_read_b128 v[146:149], v217 offset:32768
	ds_read_b128 v[150:153], v217 offset:33792
	ds_read_b128 v[154:157], v217 offset:34816
	ds_read_b128 v[158:161], v217 offset:35840
	ds_read_b128 v[162:165], v217 offset:36864
	ds_read_b128 v[166:169], v217 offset:37888
	ds_read_b128 v[170:173], v217 offset:38912
	ds_read_b128 v[174:177], v217 offset:39936
	global_load_lds_dwordx4 v198, s[30:31]
	s_mov_b32 m0, s42
	s_nop 0
	global_load_lds_dwordx4 v200, s[30:31]
	s_waitcnt lgkmcnt(8)
	s_barrier
	s_waitcnt lgkmcnt(0)
	s_setprio 1
	s_waitcnt lgkmcnt(0)
	v_mfma_f32_16x16x32_bf16 v[126:129], v[130:133], v[146:149], v[126:129]
	v_mfma_f32_16x16x32_bf16 v[122:125], v[138:141], v[146:149], v[122:125]
	v_mfma_f32_16x16x32_bf16 v[118:121], v[130:133], v[154:157], v[118:121]
	v_mfma_f32_16x16x32_bf16 v[114:117], v[138:141], v[154:157], v[114:117]
	v_mfma_f32_16x16x32_bf16 v[102:105], v[130:133], v[162:165], v[102:105]
	v_mfma_f32_16x16x32_bf16 v[98:101], v[138:141], v[162:165], v[98:101]
	v_mfma_f32_16x16x32_bf16 v[86:89], v[130:133], v[170:173], v[86:89]
	v_mfma_f32_16x16x32_bf16 v[82:85], v[138:141], v[170:173], v[82:85]
	v_mfma_f32_16x16x32_bf16 v[126:129], v[134:137], v[150:153], v[126:129]
	v_mfma_f32_16x16x32_bf16 v[122:125], v[142:145], v[150:153], v[122:125]
	v_mfma_f32_16x16x32_bf16 v[118:121], v[134:137], v[158:161], v[118:121]
	v_mfma_f32_16x16x32_bf16 v[114:117], v[142:145], v[158:161], v[114:117]
	v_mfma_f32_16x16x32_bf16 v[102:105], v[134:137], v[166:169], v[102:105]
	v_mfma_f32_16x16x32_bf16 v[98:101], v[142:145], v[166:169], v[98:101]
	v_mfma_f32_16x16x32_bf16 v[86:89], v[134:137], v[174:177], v[86:89]
	v_mfma_f32_16x16x32_bf16 v[82:85], v[142:145], v[174:177], v[82:85]
	s_setprio 0
	s_barrier
	s_add_i32 s30, 0, 0x1c000
	s_add_i32 s31, s57, s38
	s_add_u32 s58, s28, s66
	s_addc_u32 s59, s29, s67
	s_mov_b32 m0, s31
	ds_read_b128 v[178:181], v203 offset:49152
	ds_read_b128 v[182:185], v203 offset:50176
	ds_read_b128 v[186:189], v203 offset:51200
	ds_read_b128 v[190:193], v203 offset:52224
	global_load_lds_dwordx4 v48, s[58:59]
	s_add_i32 m0, s31, 0x2000
	s_nop 0
	global_load_lds_dwordx4 v202, s[58:59]
	s_barrier
	s_waitcnt lgkmcnt(0)
	s_setprio 1
	s_waitcnt lgkmcnt(0)
	v_mfma_f32_16x16x32_bf16 v[110:113], v[178:181], v[146:149], v[110:113]
	v_mfma_f32_16x16x32_bf16 v[106:109], v[186:189], v[146:149], v[106:109]
	v_mfma_f32_16x16x32_bf16 v[94:97], v[178:181], v[154:157], v[94:97]
	v_mfma_f32_16x16x32_bf16 v[90:93], v[186:189], v[154:157], v[90:93]
	v_mfma_f32_16x16x32_bf16 v[78:81], v[178:181], v[162:165], v[78:81]
	v_mfma_f32_16x16x32_bf16 v[74:77], v[186:189], v[162:165], v[74:77]
	v_mfma_f32_16x16x32_bf16 v[70:73], v[178:181], v[170:173], v[70:73]
	v_mfma_f32_16x16x32_bf16 v[66:69], v[186:189], v[170:173], v[66:69]
	v_mfma_f32_16x16x32_bf16 v[110:113], v[182:185], v[150:153], v[110:113]
	v_mfma_f32_16x16x32_bf16 v[106:109], v[190:193], v[150:153], v[106:109]
	v_mfma_f32_16x16x32_bf16 v[94:97], v[182:185], v[158:161], v[94:97]
	v_mfma_f32_16x16x32_bf16 v[90:93], v[190:193], v[158:161], v[90:93]
	v_mfma_f32_16x16x32_bf16 v[78:81], v[182:185], v[166:169], v[78:81]
	v_mfma_f32_16x16x32_bf16 v[74:77], v[190:193], v[166:169], v[74:77]
	v_mfma_f32_16x16x32_bf16 v[70:73], v[182:185], v[174:177], v[70:73]
	v_mfma_f32_16x16x32_bf16 v[66:69], v[190:193], v[174:177], v[66:69]
	s_setprio 0
	s_mov_b32 m0, s49
	s_barrier
	ds_read_b128 v[146:149], v217 offset:49152
	ds_read_b128 v[150:153], v217 offset:50176
	ds_read_b128 v[154:157], v217 offset:51200
	ds_read_b128 v[158:161], v217 offset:52224
	ds_read_b128 v[162:165], v217 offset:53248
	ds_read_b128 v[166:169], v217 offset:54272
	ds_read_b128 v[170:173], v217 offset:55296
	ds_read_b128 v[174:177], v217 offset:56320
	global_load_lds_dwordx4 v198, s[84:85]
	s_mov_b32 m0, s50
	s_nop 0
	global_load_lds_dwordx4 v200, s[84:85]
	s_barrier
	s_waitcnt lgkmcnt(0)
	s_setprio 1
	s_waitcnt lgkmcnt(0)
	v_mfma_f32_16x16x32_bf16 v[62:65], v[130:133], v[146:149], v[62:65]
	v_mfma_f32_16x16x32_bf16 v[58:61], v[138:141], v[146:149], v[58:61]
	v_mfma_f32_16x16x32_bf16 v[54:57], v[130:133], v[154:157], v[54:57]
	v_mfma_f32_16x16x32_bf16 v[50:53], v[138:141], v[154:157], v[50:53]
	v_mfma_f32_16x16x32_bf16 v[36:39], v[130:133], v[162:165], v[36:39]
	v_mfma_f32_16x16x32_bf16 v[32:35], v[138:141], v[162:165], v[32:35]
	v_mfma_f32_16x16x32_bf16 v[20:23], v[130:133], v[170:173], v[20:23]
	v_mfma_f32_16x16x32_bf16 v[16:19], v[138:141], v[170:173], v[16:19]
	v_mfma_f32_16x16x32_bf16 v[62:65], v[134:137], v[150:153], v[62:65]
	v_mfma_f32_16x16x32_bf16 v[58:61], v[142:145], v[150:153], v[58:61]
	v_mfma_f32_16x16x32_bf16 v[54:57], v[134:137], v[158:161], v[54:57]
	v_mfma_f32_16x16x32_bf16 v[50:53], v[142:145], v[158:161], v[50:53]
	v_mfma_f32_16x16x32_bf16 v[36:39], v[134:137], v[166:169], v[36:39]
	v_mfma_f32_16x16x32_bf16 v[32:35], v[142:145], v[166:169], v[32:35]
	v_mfma_f32_16x16x32_bf16 v[20:23], v[134:137], v[174:177], v[20:23]
	v_mfma_f32_16x16x32_bf16 v[16:19], v[142:145], v[174:177], v[16:19]
	s_setprio 0
	s_barrier
	s_add_u32 s28, s28, 0x40080
	s_addc_u32 s29, s29, 0
	s_add_i32 s30, s30, s38
	s_mov_b32 m0, s30
	s_nop 0
	global_load_lds_dwordx4 v48, s[28:29]
	s_add_i32 m0, s30, 0x2000
	s_nop 0
	global_load_lds_dwordx4 v202, s[28:29]
	s_waitcnt vmcnt(6)
	s_barrier
	s_setprio 1
	v_mfma_f32_16x16x32_bf16 v[44:47], v[178:181], v[146:149], v[44:47]
	v_mfma_f32_16x16x32_bf16 v[40:43], v[186:189], v[146:149], v[40:43]
	v_mfma_f32_16x16x32_bf16 v[28:31], v[178:181], v[154:157], v[28:31]
	v_mfma_f32_16x16x32_bf16 v[24:27], v[186:189], v[154:157], v[24:27]
	v_mfma_f32_16x16x32_bf16 v[12:15], v[178:181], v[162:165], v[12:15]
	v_mfma_f32_16x16x32_bf16 v[8:11], v[186:189], v[162:165], v[8:11]
	v_mfma_f32_16x16x32_bf16 v[4:7], v[178:181], v[170:173], v[4:7]
	v_mfma_f32_16x16x32_bf16 v[0:3], v[186:189], v[170:173], v[0:3]
	v_mfma_f32_16x16x32_bf16 v[44:47], v[182:185], v[150:153], v[44:47]
	v_mfma_f32_16x16x32_bf16 v[40:43], v[190:193], v[150:153], v[40:43]
	v_mfma_f32_16x16x32_bf16 v[28:31], v[182:185], v[158:161], v[28:31]
	v_mfma_f32_16x16x32_bf16 v[24:27], v[190:193], v[158:161], v[24:27]
	v_mfma_f32_16x16x32_bf16 v[12:15], v[182:185], v[166:169], v[12:15]
	v_mfma_f32_16x16x32_bf16 v[8:11], v[190:193], v[166:169], v[8:11]
	v_mfma_f32_16x16x32_bf16 v[4:7], v[182:185], v[174:177], v[4:7]
	v_mfma_f32_16x16x32_bf16 v[0:3], v[190:193], v[174:177], v[0:3]
	s_setprio 0
	s_add_u32 s24, s24, 0x100
	s_addc_u32 s25, s25, 0
	s_add_u32 s19, s19, 0x100
	s_addc_u32 s27, s27, 0
	s_cmp_ge_i32 s56, s1
	s_mov_b32 s28, s56
	s_barrier
	s_cbranch_scc0 .LBB0_1056
	v_mov_b32_e32 v130, v214
	v_mov_b32_e32 v131, v215
	s_bitcmp1_b32 s55, 0
	v_add_u32_e32 v134, s47, v130
	v_lshlrev_b32_e32 v130, 8, v134
	v_lshl_add_u32 v132, v131, 3, s48
	v_ashrrev_i32_e32 v131, 31, v130
	v_lshl_add_u64 v[130:131], v[130:131], 1, s[12:13]
	v_ashrrev_i32_e32 v133, 31, v132
	s_cselect_b64 s[28:29], -1, 0
	v_lshlrev_b32_e32 v208, 9, v215
	v_lshl_add_u32 v208, v214, 4, v208
	v_lshl_add_u32 v208, s47, 9, v208
	v_lshl_add_u32 v208, s48, 6, v208
	v_mov_b32_e32 v209, 0
	v_lshl_add_u64 v[208:209], v[208:209], 0, s[12:13]
	s_mov_b64 s[24:25], -1
	s_and_b64 vcc, exec, s[28:29]
	s_mov_b32 s57, s81
	s_cbranch_vccz .LBB0_1093
	s_mov_b64 s[24:25], 0x20000
	v_lshl_add_u64 v[130:131], v[208:209], 0, s[24:25]
	s_and_b32 s1, s55, -2
	s_mov_b64 s[24:25], 0x100
	s_cmp_lg_u32 s1, 4
	v_mov_b64_e32 v[210:211], v[130:131]
	s_cbranch_scc1 .LBB0_1060
	v_lshl_add_u32 v134, s26, 8, v134
	v_ashrrev_i32_e32 v135, 31, v134
	v_lshlrev_b64 v[134:135], 11, v[134:135]
	s_lshl_b32 s0, s0, 8
	v_lshl_add_u64 v[134:135], s[14:15], 0, v[134:135]
	s_ashr_i32 s1, s0, 31
	v_lshl_add_u64 v[134:135], s[0:1], 1, v[134:135]
	v_lshl_add_u64 v[210:211], v[132:133], 1, v[134:135]
	s_mov_b64 s[24:25], 0x400

.LBB0_1219:
	s_add_u32 s26, s24, 0xfffc0080
	s_addc_u32 s27, s25, -1
	s_add_i32 s31, 0, 0x10000
	ds_read_b128 v[130:133], v201
	ds_read_b128 v[134:137], v201 offset:1024
	ds_read_b128 v[138:141], v201 offset:2048
	ds_read_b128 v[142:145], v201 offset:3072
	s_cmp_eq_u32 s30, 12
	s_cselect_b32 s29, s19, s27
	s_cselect_b32 s28, s18, s26
	s_cselect_b32 s27, s21, s17
	s_cselect_b32 s26, s20, s15
	s_add_i32 m0, s41, 0xc000
	ds_read_b128 v[146:149], v210
	ds_read_b128 v[150:153], v210 offset:1024
	ds_read_b128 v[154:157], v210 offset:2048
	ds_read_b128 v[158:161], v210 offset:3072
	ds_read_b128 v[162:165], v210 offset:4096
	ds_read_b128 v[166:169], v210 offset:5120
	ds_read_b128 v[170:173], v210 offset:6144
	ds_read_b128 v[174:177], v210 offset:7168
	global_load_lds_dwordx4 v200, s[24:25]
	s_add_i32 m0, s41, 0xe000
	s_nop 0
	global_load_lds_dwordx4 v202, s[24:25]
	s_waitcnt lgkmcnt(8)
	s_barrier
	s_waitcnt lgkmcnt(0)
	s_setprio 1
	s_waitcnt lgkmcnt(0)
	v_mfma_f32_16x16x32_bf16 v[126:129], v[130:133], v[146:149], v[126:129]
	v_mfma_f32_16x16x32_bf16 v[122:125], v[138:141], v[146:149], v[122:125]
	v_mfma_f32_16x16x32_bf16 v[118:121], v[130:133], v[154:157], v[118:121]
	v_mfma_f32_16x16x32_bf16 v[106:109], v[138:141], v[154:157], v[106:109]
	v_mfma_f32_16x16x32_bf16 v[94:97], v[130:133], v[162:165], v[94:97]
	v_mfma_f32_16x16x32_bf16 v[90:93], v[138:141], v[162:165], v[90:93]
	v_mfma_f32_16x16x32_bf16 v[86:89], v[130:133], v[170:173], v[86:89]
	v_mfma_f32_16x16x32_bf16 v[74:77], v[138:141], v[170:173], v[74:77]
	v_mfma_f32_16x16x32_bf16 v[126:129], v[134:137], v[150:153], v[126:129]
	v_mfma_f32_16x16x32_bf16 v[122:125], v[142:145], v[150:153], v[122:125]
	v_mfma_f32_16x16x32_bf16 v[118:121], v[134:137], v[158:161], v[118:121]
	v_mfma_f32_16x16x32_bf16 v[106:109], v[142:145], v[158:161], v[106:109]
	v_mfma_f32_16x16x32_bf16 v[94:97], v[134:137], v[166:169], v[94:97]
	v_mfma_f32_16x16x32_bf16 v[90:93], v[142:145], v[166:169], v[90:93]
	v_mfma_f32_16x16x32_bf16 v[86:89], v[134:137], v[174:177], v[86:89]
	v_mfma_f32_16x16x32_bf16 v[74:77], v[142:145], v[174:177], v[74:77]
	s_setprio 0
	s_barrier
	s_add_i32 s50, 0, 0x14000
	s_add_i32 s31, s31, s40
	s_mov_b32 m0, s31
	ds_read_b128 v[178:181], v201 offset:16384
	ds_read_b128 v[182:185], v201 offset:17408
	ds_read_b128 v[186:189], v201 offset:18432
	ds_read_b128 v[204:207], v201 offset:19456
	global_load_lds_dwordx4 v48, s[26:27]
	s_add_i32 m0, s31, 0x2000
	s_nop 0
	global_load_lds_dwordx4 v190, s[26:27]
	s_barrier
	s_waitcnt lgkmcnt(0)
	s_setprio 1
	s_waitcnt lgkmcnt(0)
	v_mfma_f32_16x16x32_bf16 v[114:117], v[178:181], v[146:149], v[114:117]
	v_mfma_f32_16x16x32_bf16 v[110:113], v[186:189], v[146:149], v[110:113]
	v_mfma_f32_16x16x32_bf16 v[102:105], v[178:181], v[154:157], v[102:105]
	v_mfma_f32_16x16x32_bf16 v[98:101], v[186:189], v[154:157], v[98:101]
	v_mfma_f32_16x16x32_bf16 v[82:85], v[178:181], v[162:165], v[82:85]
	v_mfma_f32_16x16x32_bf16 v[78:81], v[186:189], v[162:165], v[78:81]
	v_mfma_f32_16x16x32_bf16 v[70:73], v[178:181], v[170:173], v[70:73]
	v_mfma_f32_16x16x32_bf16 v[66:69], v[186:189], v[170:173], v[66:69]
	v_mfma_f32_16x16x32_bf16 v[114:117], v[182:185], v[150:153], v[114:117]
	v_mfma_f32_16x16x32_bf16 v[110:113], v[204:207], v[150:153], v[110:113]
	v_mfma_f32_16x16x32_bf16 v[102:105], v[182:185], v[158:161], v[102:105]
	v_mfma_f32_16x16x32_bf16 v[98:101], v[204:207], v[158:161], v[98:101]
	v_mfma_f32_16x16x32_bf16 v[82:85], v[182:185], v[166:169], v[82:85]
	v_mfma_f32_16x16x32_bf16 v[78:81], v[204:207], v[166:169], v[78:81]
	v_mfma_f32_16x16x32_bf16 v[70:73], v[182:185], v[174:177], v[70:73]
	v_mfma_f32_16x16x32_bf16 v[66:69], v[204:207], v[174:177], v[66:69]
	s_setprio 0
	s_mov_b32 m0, s41
	s_add_u32 s58, s28, s66
	s_addc_u32 s59, s29, s67
	s_barrier
	ds_read_b128 v[146:149], v210 offset:16384
	ds_read_b128 v[150:153], v210 offset:17408
	ds_read_b128 v[154:157], v210 offset:18432
	ds_read_b128 v[158:161], v210 offset:19456
	ds_read_b128 v[162:165], v210 offset:20480
	ds_read_b128 v[166:169], v210 offset:21504
	ds_read_b128 v[170:173], v210 offset:22528
	ds_read_b128 v[174:177], v210 offset:23552
	global_load_lds_dwordx4 v48, s[28:29]
	s_mov_b32 m0, s42
	s_nop 0
	global_load_lds_dwordx4 v190, s[28:29]
	s_barrier
	s_waitcnt lgkmcnt(0)
	s_setprio 1
	s_waitcnt lgkmcnt(0)
	v_mfma_f32_16x16x32_bf16 v[62:65], v[130:133], v[146:149], v[62:65]
	v_mfma_f32_16x16x32_bf16 v[58:61], v[138:141], v[146:149], v[58:61]
	v_mfma_f32_16x16x32_bf16 v[54:57], v[130:133], v[154:157], v[54:57]
	v_mfma_f32_16x16x32_bf16 v[40:43], v[138:141], v[154:157], v[40:43]
	v_mfma_f32_16x16x32_bf16 v[36:39], v[130:133], v[162:165], v[36:39]
	v_mfma_f32_16x16x32_bf16 v[24:27], v[138:141], v[162:165], v[24:27]
	v_mfma_f32_16x16x32_bf16 v[20:23], v[130:133], v[170:173], v[20:23]
	v_mfma_f32_16x16x32_bf16 v[8:11], v[138:141], v[170:173], v[8:11]
	v_mfma_f32_16x16x32_bf16 v[62:65], v[134:137], v[150:153], v[62:65]
	v_mfma_f32_16x16x32_bf16 v[58:61], v[142:145], v[150:153], v[58:61]
	v_mfma_f32_16x16x32_bf16 v[54:57], v[134:137], v[158:161], v[54:57]
	v_mfma_f32_16x16x32_bf16 v[40:43], v[142:145], v[158:161], v[40:43]
	v_mfma_f32_16x16x32_bf16 v[36:39], v[134:137], v[166:169], v[36:39]
	v_mfma_f32_16x16x32_bf16 v[24:27], v[142:145], v[166:169], v[24:27]
	v_mfma_f32_16x16x32_bf16 v[20:23], v[134:137], v[174:177], v[20:23]
	v_mfma_f32_16x16x32_bf16 v[8:11], v[142:145], v[174:177], v[8:11]
	s_setprio 0
	s_barrier
	s_add_u32 s34, s26, 0x40000
	s_addc_u32 s35, s27, 0
	s_add_i32 s31, s50, s40
	s_mov_b32 m0, s31
	s_nop 0
	global_load_lds_dwordx4 v48, s[34:35]
	s_add_i32 m0, s31, 0x2000
	s_nop 0
	global_load_lds_dwordx4 v190, s[34:35]
	s_waitcnt vmcnt(6)
	s_barrier
	s_setprio 1
	v_mfma_f32_16x16x32_bf16 v[50:53], v[178:181], v[146:149], v[50:53]
	v_mfma_f32_16x16x32_bf16 v[44:47], v[186:189], v[146:149], v[44:47]
	v_mfma_f32_16x16x32_bf16 v[32:35], v[178:181], v[154:157], v[32:35]
	v_mfma_f32_16x16x32_bf16 v[28:31], v[186:189], v[154:157], v[28:31]
	v_mfma_f32_16x16x32_bf16 v[16:19], v[178:181], v[162:165], v[16:19]
	v_mfma_f32_16x16x32_bf16 v[12:15], v[186:189], v[162:165], v[12:15]
	v_mfma_f32_16x16x32_bf16 v[4:7], v[178:181], v[170:173], v[4:7]
	v_mfma_f32_16x16x32_bf16 v[0:3], v[186:189], v[170:173], v[0:3]
	v_mfma_f32_16x16x32_bf16 v[50:53], v[182:185], v[150:153], v[50:53]
	v_mfma_f32_16x16x32_bf16 v[44:47], v[204:207], v[150:153], v[44:47]
	v_mfma_f32_16x16x32_bf16 v[32:35], v[182:185], v[158:161], v[32:35]
	v_mfma_f32_16x16x32_bf16 v[28:31], v[204:207], v[158:161], v[28:31]
	v_mfma_f32_16x16x32_bf16 v[16:19], v[182:185], v[166:169], v[16:19]
	v_mfma_f32_16x16x32_bf16 v[12:15], v[204:207], v[166:169], v[12:15]
	v_mfma_f32_16x16x32_bf16 v[4:7], v[182:185], v[174:177], v[4:7]
	v_mfma_f32_16x16x32_bf16 v[0:3], v[204:207], v[174:177], v[0:3]
	s_setprio 0
	s_add_i32 s31, 0, 0x18000
	s_barrier
	ds_read_b128 v[130:133], v201 offset:32768
	ds_read_b128 v[134:137], v201 offset:33792
	ds_read_b128 v[138:141], v201 offset:34816
	ds_read_b128 v[142:145], v201 offset:35840
	s_add_u32 s28, s28, 0x40000
	s_addc_u32 s29, s29, 0
	s_mov_b32 m0, s43
	ds_read_b128 v[146:149], v210 offset:32768
	ds_read_b128 v[150:153], v210 offset:33792
	ds_read_b128 v[154:157], v210 offset:34816
	ds_read_b128 v[158:161], v210 offset:35840
	ds_read_b128 v[162:165], v210 offset:36864
	ds_read_b128 v[166:169], v210 offset:37888
	ds_read_b128 v[170:173], v210 offset:38912
	ds_read_b128 v[174:177], v210 offset:39936
	global_load_lds_dwordx4 v48, s[28:29]
	s_mov_b32 m0, s44
	s_nop 0
	global_load_lds_dwordx4 v190, s[28:29]
	s_waitcnt lgkmcnt(8)
	s_barrier
	s_waitcnt lgkmcnt(0)
	s_setprio 1
	s_waitcnt lgkmcnt(0)
	v_mfma_f32_16x16x32_bf16 v[126:129], v[130:133], v[146:149], v[126:129]
	v_mfma_f32_16x16x32_bf16 v[122:125], v[138:141], v[146:149], v[122:125]
	v_mfma_f32_16x16x32_bf16 v[118:121], v[130:133], v[154:157], v[118:121]
	v_mfma_f32_16x16x32_bf16 v[106:109], v[138:141], v[154:157], v[106:109]
	v_mfma_f32_16x16x32_bf16 v[94:97], v[130:133], v[162:165], v[94:97]
	v_mfma_f32_16x16x32_bf16 v[90:93], v[138:141], v[162:165], v[90:93]
	v_mfma_f32_16x16x32_bf16 v[86:89], v[130:133], v[170:173], v[86:89]
	v_mfma_f32_16x16x32_bf16 v[74:77], v[138:141], v[170:173], v[74:77]
	v_mfma_f32_16x16x32_bf16 v[126:129], v[134:137], v[150:153], v[126:129]
	v_mfma_f32_16x16x32_bf16 v[122:125], v[142:145], v[150:153], v[122:125]
	v_mfma_f32_16x16x32_bf16 v[118:121], v[134:137], v[158:161], v[118:121]
	v_mfma_f32_16x16x32_bf16 v[106:109], v[142:145], v[158:161], v[106:109]
	v_mfma_f32_16x16x32_bf16 v[94:97], v[134:137], v[166:169], v[94:97]
	v_mfma_f32_16x16x32_bf16 v[90:93], v[142:145], v[166:169], v[90:93]
	v_mfma_f32_16x16x32_bf16 v[86:89], v[134:137], v[174:177], v[86:89]
	v_mfma_f32_16x16x32_bf16 v[74:77], v[142:145], v[174:177], v[74:77]
	s_setprio 0
	s_barrier
	s_add_i32 s28, 0, 0x1c000
	s_add_i32 s29, s31, s40
	s_add_u32 s52, s26, s66
	s_addc_u32 s53, s27, s67
	s_mov_b32 m0, s29
	ds_read_b128 v[178:181], v201 offset:49152
	ds_read_b128 v[182:185], v201 offset:50176
	ds_read_b128 v[186:189], v201 offset:51200
	ds_read_b128 v[204:207], v201 offset:52224
	global_load_lds_dwordx4 v48, s[52:53]
	s_add_i32 m0, s29, 0x2000
	s_nop 0
	global_load_lds_dwordx4 v190, s[52:53]
	s_barrier
	s_waitcnt lgkmcnt(0)
	s_setprio 1
	s_waitcnt lgkmcnt(0)
	v_mfma_f32_16x16x32_bf16 v[114:117], v[178:181], v[146:149], v[114:117]
	v_mfma_f32_16x16x32_bf16 v[110:113], v[186:189], v[146:149], v[110:113]
	v_mfma_f32_16x16x32_bf16 v[102:105], v[178:181], v[154:157], v[102:105]
	v_mfma_f32_16x16x32_bf16 v[98:101], v[186:189], v[154:157], v[98:101]
	v_mfma_f32_16x16x32_bf16 v[82:85], v[178:181], v[162:165], v[82:85]
	v_mfma_f32_16x16x32_bf16 v[78:81], v[186:189], v[162:165], v[78:81]
	v_mfma_f32_16x16x32_bf16 v[70:73], v[178:181], v[170:173], v[70:73]
	v_mfma_f32_16x16x32_bf16 v[66:69], v[186:189], v[170:173], v[66:69]
	v_mfma_f32_16x16x32_bf16 v[114:117], v[182:185], v[150:153], v[114:117]
	v_mfma_f32_16x16x32_bf16 v[110:113], v[204:207], v[150:153], v[110:113]
	v_mfma_f32_16x16x32_bf16 v[102:105], v[182:185], v[158:161], v[102:105]
	v_mfma_f32_16x16x32_bf16 v[98:101], v[204:207], v[158:161], v[98:101]
	v_mfma_f32_16x16x32_bf16 v[82:85], v[182:185], v[166:169], v[82:85]
	v_mfma_f32_16x16x32_bf16 v[78:81], v[204:207], v[166:169], v[78:81]
	v_mfma_f32_16x16x32_bf16 v[70:73], v[182:185], v[174:177], v[70:73]
	v_mfma_f32_16x16x32_bf16 v[66:69], v[204:207], v[174:177], v[66:69]
	s_setprio 0
	s_mov_b32 m0, s47
	s_barrier
	ds_read_b128 v[146:149], v210 offset:49152
	ds_read_b128 v[150:153], v210 offset:50176
	ds_read_b128 v[154:157], v210 offset:51200
	ds_read_b128 v[158:161], v210 offset:52224
	ds_read_b128 v[162:165], v210 offset:53248
	ds_read_b128 v[166:169], v210 offset:54272
	ds_read_b128 v[170:173], v210 offset:55296
	ds_read_b128 v[174:177], v210 offset:56320
	global_load_lds_dwordx4 v48, s[58:59]
	s_mov_b32 m0, s48
	s_nop 0
	global_load_lds_dwordx4 v190, s[58:59]
	s_barrier
	s_waitcnt lgkmcnt(0)
	s_setprio 1
	s_waitcnt lgkmcnt(0)
	v_mfma_f32_16x16x32_bf16 v[62:65], v[130:133], v[146:149], v[62:65]
	v_mfma_f32_16x16x32_bf16 v[58:61], v[138:141], v[146:149], v[58:61]
	v_mfma_f32_16x16x32_bf16 v[54:57], v[130:133], v[154:157], v[54:57]
	v_mfma_f32_16x16x32_bf16 v[40:43], v[138:141], v[154:157], v[40:43]
	v_mfma_f32_16x16x32_bf16 v[36:39], v[130:133], v[162:165], v[36:39]
	v_mfma_f32_16x16x32_bf16 v[24:27], v[138:141], v[162:165], v[24:27]
	v_mfma_f32_16x16x32_bf16 v[20:23], v[130:133], v[170:173], v[20:23]
	v_mfma_f32_16x16x32_bf16 v[8:11], v[138:141], v[170:173], v[8:11]
	v_mfma_f32_16x16x32_bf16 v[62:65], v[134:137], v[150:153], v[62:65]
	v_mfma_f32_16x16x32_bf16 v[58:61], v[142:145], v[150:153], v[58:61]
	v_mfma_f32_16x16x32_bf16 v[54:57], v[134:137], v[158:161], v[54:57]
	v_mfma_f32_16x16x32_bf16 v[40:43], v[142:145], v[158:161], v[40:43]
	v_mfma_f32_16x16x32_bf16 v[36:39], v[134:137], v[166:169], v[36:39]
	v_mfma_f32_16x16x32_bf16 v[24:27], v[142:145], v[166:169], v[24:27]
	v_mfma_f32_16x16x32_bf16 v[20:23], v[134:137], v[174:177], v[20:23]
	v_mfma_f32_16x16x32_bf16 v[8:11], v[142:145], v[174:177], v[8:11]
	s_setprio 0
	s_barrier
	s_add_u32 s26, s26, 0x40080
	s_addc_u32 s27, s27, 0
	s_add_i32 s28, s28, s40
	s_mov_b32 m0, s28
	s_nop 0
	global_load_lds_dwordx4 v48, s[26:27]
	s_add_i32 m0, s28, 0x2000
	s_nop 0
	global_load_lds_dwordx4 v190, s[26:27]
	s_waitcnt vmcnt(6)
	s_barrier
	s_setprio 1
	v_mfma_f32_16x16x32_bf16 v[50:53], v[178:181], v[146:149], v[50:53]
	v_mfma_f32_16x16x32_bf16 v[44:47], v[186:189], v[146:149], v[44:47]
	v_mfma_f32_16x16x32_bf16 v[32:35], v[178:181], v[154:157], v[32:35]
	v_mfma_f32_16x16x32_bf16 v[28:31], v[186:189], v[154:157], v[28:31]
	v_mfma_f32_16x16x32_bf16 v[16:19], v[178:181], v[162:165], v[16:19]
	v_mfma_f32_16x16x32_bf16 v[12:15], v[186:189], v[162:165], v[12:15]
	v_mfma_f32_16x16x32_bf16 v[4:7], v[178:181], v[170:173], v[4:7]
	v_mfma_f32_16x16x32_bf16 v[0:3], v[186:189], v[170:173], v[0:3]
	v_mfma_f32_16x16x32_bf16 v[50:53], v[182:185], v[150:153], v[50:53]
	v_mfma_f32_16x16x32_bf16 v[44:47], v[204:207], v[150:153], v[44:47]
	v_mfma_f32_16x16x32_bf16 v[32:35], v[182:185], v[158:161], v[32:35]
	v_mfma_f32_16x16x32_bf16 v[28:31], v[204:207], v[158:161], v[28:31]
	v_mfma_f32_16x16x32_bf16 v[16:19], v[182:185], v[166:169], v[16:19]
	v_mfma_f32_16x16x32_bf16 v[12:15], v[204:207], v[166:169], v[12:15]
	v_mfma_f32_16x16x32_bf16 v[4:7], v[182:185], v[174:177], v[4:7]
	v_mfma_f32_16x16x32_bf16 v[0:3], v[204:207], v[174:177], v[0:3]
	s_setprio 0
	s_add_i32 s30, s30, 2
	s_add_u32 s24, s24, 0x100
	s_addc_u32 s25, s25, 0
	s_add_u32 s15, s15, 0x100
	s_addc_u32 s17, s17, 0
	s_cmp_gt_u32 s30, 13
	s_barrier
	s_cbranch_scc0 .LBB0_1219
	s_mul_hi_i32 s15, s22, 0x38e38e39
	s_lshr_b32 s17, s15, 31
	s_ashr_i32 s15, s15, 1
	s_add_i32 s24, s15, s17
	s_mul_i32 s15, s24, -9
	s_add_i32 s28, s15, s22
	s_cmp_eq_u32 s28, 0
	s_cselect_b64 s[26:27], -1, 0
	s_ashr_i32 s25, s24, 31
	s_cmp_lg_u32 s28, 0
	s_cbranch_scc0 .LBB0_1222
	s_ashr_i32 s29, s28, 31
	s_lshl_b64 s[28:29], s[28:29], 18
	s_lshl_b64 s[30:31], s[24:25], 21
	s_add_u32 s15, s28, s30
	s_addc_u32 s17, s29, s31
	s_add_u32 s28, s15, 0xfffc0000
	s_addc_u32 s29, s17, -1
	s_mov_b64 s[30:31], s[6:7]
	s_cbranch_execnz .LBB0_1215
	s_branch .LBB0_1214

.LBB0_1356:
	s_add_u32 s28, s26, 0xfffc0080
	s_addc_u32 s29, s27, -1
	s_add_i32 s46, 0, 0x10000
	ds_read_b128 v[146:149], v137
	ds_read_b128 v[150:153], v137 offset:1024
	ds_read_b128 v[154:157], v137 offset:2048
	ds_read_b128 v[158:161], v137 offset:3072
	s_cmp_eq_u32 s45, 12
	s_cselect_b32 s31, s19, s29
	s_cselect_b32 s30, s18, s28
	s_cselect_b32 s29, s21, s17
	s_cselect_b32 s28, s20, s15
	s_add_i32 m0, s23, 0xc000
	ds_read_b128 v[162:165], v145
	ds_read_b128 v[166:169], v145 offset:1024
	ds_read_b128 v[170:173], v145 offset:2048
	ds_read_b128 v[174:177], v145 offset:3072
	ds_read_b128 v[178:181], v145 offset:4096
	ds_read_b128 v[182:185], v145 offset:5120
	ds_read_b128 v[186:189], v145 offset:6144
	ds_read_b128 v[190:193], v145 offset:7168
	global_load_lds_dwordx4 v136, s[26:27]
	s_add_i32 m0, s23, 0xe000
	s_nop 0
	global_load_lds_dwordx4 v138, s[26:27]
	s_waitcnt lgkmcnt(8)
	s_barrier
	s_waitcnt lgkmcnt(0)
	s_setprio 1
	s_waitcnt lgkmcnt(0)
	v_mfma_f32_16x16x32_bf16 v[126:129], v[146:149], v[162:165], v[126:129]
	v_mfma_f32_16x16x32_bf16 v[118:121], v[154:157], v[162:165], v[118:121]
	v_mfma_f32_16x16x32_bf16 v[110:113], v[146:149], v[170:173], v[110:113]
	v_mfma_f32_16x16x32_bf16 v[102:105], v[154:157], v[170:173], v[102:105]
	v_mfma_f32_16x16x32_bf16 v[94:97], v[146:149], v[178:181], v[94:97]
	v_mfma_f32_16x16x32_bf16 v[86:89], v[154:157], v[178:181], v[86:89]
	v_mfma_f32_16x16x32_bf16 v[78:81], v[146:149], v[186:189], v[78:81]
	v_mfma_f32_16x16x32_bf16 v[70:73], v[154:157], v[186:189], v[70:73]
	v_mfma_f32_16x16x32_bf16 v[126:129], v[150:153], v[166:169], v[126:129]
	v_mfma_f32_16x16x32_bf16 v[118:121], v[158:161], v[166:169], v[118:121]
	v_mfma_f32_16x16x32_bf16 v[110:113], v[150:153], v[174:177], v[110:113]
	v_mfma_f32_16x16x32_bf16 v[102:105], v[158:161], v[174:177], v[102:105]
	v_mfma_f32_16x16x32_bf16 v[94:97], v[150:153], v[182:185], v[94:97]
	v_mfma_f32_16x16x32_bf16 v[86:89], v[158:161], v[182:185], v[86:89]
	v_mfma_f32_16x16x32_bf16 v[78:81], v[150:153], v[190:193], v[78:81]
	v_mfma_f32_16x16x32_bf16 v[70:73], v[158:161], v[190:193], v[70:73]
	s_setprio 0
	s_barrier
	s_add_i32 s48, 0, 0x14000
	s_add_i32 s46, s46, s37
	ds_read_b128 v[198:201], v137 offset:16384
	ds_read_b128 v[202:205], v137 offset:17408
	ds_read_b128 v[206:209], v137 offset:18432
	ds_read_b128 v[210:213], v137 offset:19456
	s_mov_b32 m0, s46
	global_load_lds_dwordx4 v48, s[28:29]
	s_add_i32 m0, s46, 0x2000
	s_nop 0
	global_load_lds_dwordx4 v130, s[28:29]
	s_barrier
	s_waitcnt lgkmcnt(0)
	s_setprio 1
	s_waitcnt lgkmcnt(0)
	v_mfma_f32_16x16x32_bf16 v[122:125], v[198:201], v[162:165], v[122:125]
	v_mfma_f32_16x16x32_bf16 v[114:117], v[206:209], v[162:165], v[114:117]
	v_mfma_f32_16x16x32_bf16 v[106:109], v[198:201], v[170:173], v[106:109]
	v_mfma_f32_16x16x32_bf16 v[98:101], v[206:209], v[170:173], v[98:101]
	v_mfma_f32_16x16x32_bf16 v[90:93], v[198:201], v[178:181], v[90:93]
	v_mfma_f32_16x16x32_bf16 v[82:85], v[206:209], v[178:181], v[82:85]
	v_mfma_f32_16x16x32_bf16 v[74:77], v[198:201], v[186:189], v[74:77]
	v_mfma_f32_16x16x32_bf16 v[66:69], v[206:209], v[186:189], v[66:69]
	v_mfma_f32_16x16x32_bf16 v[122:125], v[202:205], v[166:169], v[122:125]
	v_mfma_f32_16x16x32_bf16 v[114:117], v[210:213], v[166:169], v[114:117]
	v_mfma_f32_16x16x32_bf16 v[106:109], v[202:205], v[174:177], v[106:109]
	v_mfma_f32_16x16x32_bf16 v[98:101], v[210:213], v[174:177], v[98:101]
	v_mfma_f32_16x16x32_bf16 v[90:93], v[202:205], v[182:185], v[90:93]
	v_mfma_f32_16x16x32_bf16 v[82:85], v[210:213], v[182:185], v[82:85]
	v_mfma_f32_16x16x32_bf16 v[74:77], v[202:205], v[190:193], v[74:77]
	v_mfma_f32_16x16x32_bf16 v[66:69], v[210:213], v[190:193], v[66:69]
	s_setprio 0
	s_mov_b32 m0, s23
	s_add_u32 s58, s30, s66
	s_addc_u32 s59, s31, s67
	s_barrier
	ds_read_b128 v[162:165], v145 offset:16384
	ds_read_b128 v[166:169], v145 offset:17408
	ds_read_b128 v[170:173], v145 offset:18432
	ds_read_b128 v[174:177], v145 offset:19456
	ds_read_b128 v[178:181], v145 offset:20480
	ds_read_b128 v[182:185], v145 offset:21504
	ds_read_b128 v[186:189], v145 offset:22528
	ds_read_b128 v[190:193], v145 offset:23552
	global_load_lds_dwordx4 v134, s[30:31]
	s_mov_b32 m0, s25
	s_nop 0
	global_load_lds_dwordx4 v132, s[30:31]
	s_barrier
	s_waitcnt lgkmcnt(0)
	s_setprio 1
	s_waitcnt lgkmcnt(0)
	v_mfma_f32_16x16x32_bf16 v[62:65], v[146:149], v[162:165], v[62:65]
	v_mfma_f32_16x16x32_bf16 v[54:57], v[154:157], v[162:165], v[54:57]
	v_mfma_f32_16x16x32_bf16 v[44:47], v[146:149], v[170:173], v[44:47]
	v_mfma_f32_16x16x32_bf16 v[36:39], v[154:157], v[170:173], v[36:39]
	v_mfma_f32_16x16x32_bf16 v[28:31], v[146:149], v[178:181], v[28:31]
	v_mfma_f32_16x16x32_bf16 v[20:23], v[154:157], v[178:181], v[20:23]
	v_mfma_f32_16x16x32_bf16 v[12:15], v[146:149], v[186:189], v[12:15]
	v_mfma_f32_16x16x32_bf16 v[4:7], v[154:157], v[186:189], v[4:7]
	v_mfma_f32_16x16x32_bf16 v[62:65], v[150:153], v[166:169], v[62:65]
	v_mfma_f32_16x16x32_bf16 v[54:57], v[158:161], v[166:169], v[54:57]
	v_mfma_f32_16x16x32_bf16 v[44:47], v[150:153], v[174:177], v[44:47]
	v_mfma_f32_16x16x32_bf16 v[36:39], v[158:161], v[174:177], v[36:39]
	v_mfma_f32_16x16x32_bf16 v[28:31], v[150:153], v[182:185], v[28:31]
	v_mfma_f32_16x16x32_bf16 v[20:23], v[158:161], v[182:185], v[20:23]
	v_mfma_f32_16x16x32_bf16 v[12:15], v[150:153], v[190:193], v[12:15]
	v_mfma_f32_16x16x32_bf16 v[4:7], v[158:161], v[190:193], v[4:7]
	s_setprio 0
	s_barrier
	s_add_u32 s46, s28, 0x40000
	s_addc_u32 s47, s29, 0
	s_add_i32 s48, s48, s37
	s_mov_b32 m0, s48
	s_nop 0
	global_load_lds_dwordx4 v48, s[46:47]
	s_add_i32 m0, s48, 0x2000
	s_nop 0
	global_load_lds_dwordx4 v130, s[46:47]
	s_waitcnt vmcnt(6)
	s_barrier
	s_setprio 1
	v_mfma_f32_16x16x32_bf16 v[58:61], v[198:201], v[162:165], v[58:61]
	v_mfma_f32_16x16x32_bf16 v[50:53], v[206:209], v[162:165], v[50:53]
	v_mfma_f32_16x16x32_bf16 v[40:43], v[198:201], v[170:173], v[40:43]
	v_mfma_f32_16x16x32_bf16 v[32:35], v[206:209], v[170:173], v[32:35]
	v_mfma_f32_16x16x32_bf16 v[24:27], v[198:201], v[178:181], v[24:27]
	v_mfma_f32_16x16x32_bf16 v[16:19], v[206:209], v[178:181], v[16:19]
	v_mfma_f32_16x16x32_bf16 v[8:11], v[198:201], v[186:189], v[8:11]
	v_mfma_f32_16x16x32_bf16 v[0:3], v[206:209], v[186:189], v[0:3]
	v_mfma_f32_16x16x32_bf16 v[58:61], v[202:205], v[166:169], v[58:61]
	v_mfma_f32_16x16x32_bf16 v[50:53], v[210:213], v[166:169], v[50:53]
	v_mfma_f32_16x16x32_bf16 v[40:43], v[202:205], v[174:177], v[40:43]
	v_mfma_f32_16x16x32_bf16 v[32:35], v[210:213], v[174:177], v[32:35]
	v_mfma_f32_16x16x32_bf16 v[24:27], v[202:205], v[182:185], v[24:27]
	v_mfma_f32_16x16x32_bf16 v[16:19], v[210:213], v[182:185], v[16:19]
	v_mfma_f32_16x16x32_bf16 v[8:11], v[202:205], v[190:193], v[8:11]
	v_mfma_f32_16x16x32_bf16 v[0:3], v[210:213], v[190:193], v[0:3]
	s_setprio 0
	s_add_i32 s46, 0, 0x18000
	s_barrier
	ds_read_b128 v[146:149], v137 offset:32768
	ds_read_b128 v[150:153], v137 offset:33792
	ds_read_b128 v[154:157], v137 offset:34816
	ds_read_b128 v[158:161], v137 offset:35840
	s_add_u32 s30, s30, 0x40000
	s_addc_u32 s31, s31, 0
	s_mov_b32 m0, s40
	ds_read_b128 v[162:165], v145 offset:32768
	ds_read_b128 v[166:169], v145 offset:33792
	ds_read_b128 v[170:173], v145 offset:34816
	ds_read_b128 v[174:177], v145 offset:35840
	ds_read_b128 v[178:181], v145 offset:36864
	ds_read_b128 v[182:185], v145 offset:37888
	ds_read_b128 v[186:189], v145 offset:38912
	ds_read_b128 v[190:193], v145 offset:39936
	global_load_lds_dwordx4 v134, s[30:31]
	s_mov_b32 m0, s41
	s_nop 0
	global_load_lds_dwordx4 v132, s[30:31]
	s_waitcnt lgkmcnt(8)
	s_barrier
	s_waitcnt lgkmcnt(0)
	s_setprio 1
	s_waitcnt lgkmcnt(0)
	v_mfma_f32_16x16x32_bf16 v[126:129], v[146:149], v[162:165], v[126:129]
	v_mfma_f32_16x16x32_bf16 v[118:121], v[154:157], v[162:165], v[118:121]
	v_mfma_f32_16x16x32_bf16 v[110:113], v[146:149], v[170:173], v[110:113]
	v_mfma_f32_16x16x32_bf16 v[102:105], v[154:157], v[170:173], v[102:105]
	v_mfma_f32_16x16x32_bf16 v[94:97], v[146:149], v[178:181], v[94:97]
	v_mfma_f32_16x16x32_bf16 v[86:89], v[154:157], v[178:181], v[86:89]
	v_mfma_f32_16x16x32_bf16 v[78:81], v[146:149], v[186:189], v[78:81]
	v_mfma_f32_16x16x32_bf16 v[70:73], v[154:157], v[186:189], v[70:73]
	v_mfma_f32_16x16x32_bf16 v[126:129], v[150:153], v[166:169], v[126:129]
	v_mfma_f32_16x16x32_bf16 v[118:121], v[158:161], v[166:169], v[118:121]
	v_mfma_f32_16x16x32_bf16 v[110:113], v[150:153], v[174:177], v[110:113]
	v_mfma_f32_16x16x32_bf16 v[102:105], v[158:161], v[174:177], v[102:105]
	v_mfma_f32_16x16x32_bf16 v[94:97], v[150:153], v[182:185], v[94:97]
	v_mfma_f32_16x16x32_bf16 v[86:89], v[158:161], v[182:185], v[86:89]
	v_mfma_f32_16x16x32_bf16 v[78:81], v[150:153], v[190:193], v[78:81]
	v_mfma_f32_16x16x32_bf16 v[70:73], v[158:161], v[190:193], v[70:73]
	s_setprio 0
	s_barrier
	s_add_i32 s30, 0, 0x1c000
	s_add_i32 s31, s46, s37
	s_add_u32 s46, s28, s66
	s_addc_u32 s47, s29, s67
	s_mov_b32 m0, s31
	ds_read_b128 v[198:201], v137 offset:49152
	ds_read_b128 v[202:205], v137 offset:50176
	ds_read_b128 v[206:209], v137 offset:51200
	ds_read_b128 v[210:213], v137 offset:52224
	global_load_lds_dwordx4 v48, s[46:47]
	s_add_i32 m0, s31, 0x2000
	s_nop 0
	global_load_lds_dwordx4 v130, s[46:47]
	s_barrier
	s_waitcnt lgkmcnt(0)
	s_setprio 1
	s_waitcnt lgkmcnt(0)
	v_mfma_f32_16x16x32_bf16 v[122:125], v[198:201], v[162:165], v[122:125]
	v_mfma_f32_16x16x32_bf16 v[114:117], v[206:209], v[162:165], v[114:117]
	v_mfma_f32_16x16x32_bf16 v[106:109], v[198:201], v[170:173], v[106:109]
	v_mfma_f32_16x16x32_bf16 v[98:101], v[206:209], v[170:173], v[98:101]
	v_mfma_f32_16x16x32_bf16 v[90:93], v[198:201], v[178:181], v[90:93]
	v_mfma_f32_16x16x32_bf16 v[82:85], v[206:209], v[178:181], v[82:85]
	v_mfma_f32_16x16x32_bf16 v[74:77], v[198:201], v[186:189], v[74:77]
	v_mfma_f32_16x16x32_bf16 v[66:69], v[206:209], v[186:189], v[66:69]
	v_mfma_f32_16x16x32_bf16 v[122:125], v[202:205], v[166:169], v[122:125]
	v_mfma_f32_16x16x32_bf16 v[114:117], v[210:213], v[166:169], v[114:117]
	v_mfma_f32_16x16x32_bf16 v[106:109], v[202:205], v[174:177], v[106:109]
	v_mfma_f32_16x16x32_bf16 v[98:101], v[210:213], v[174:177], v[98:101]
	v_mfma_f32_16x16x32_bf16 v[90:93], v[202:205], v[182:185], v[90:93]
	v_mfma_f32_16x16x32_bf16 v[82:85], v[210:213], v[182:185], v[82:85]
	v_mfma_f32_16x16x32_bf16 v[74:77], v[202:205], v[190:193], v[74:77]
	v_mfma_f32_16x16x32_bf16 v[66:69], v[210:213], v[190:193], v[66:69]
	s_setprio 0
	s_mov_b32 m0, s42
	s_barrier
	ds_read_b128 v[162:165], v145 offset:49152
	ds_read_b128 v[166:169], v145 offset:50176
	ds_read_b128 v[170:173], v145 offset:51200
	ds_read_b128 v[174:177], v145 offset:52224
	ds_read_b128 v[178:181], v145 offset:53248
	ds_read_b128 v[182:185], v145 offset:54272
	ds_read_b128 v[186:189], v145 offset:55296
	ds_read_b128 v[190:193], v145 offset:56320
	global_load_lds_dwordx4 v134, s[58:59]
	s_mov_b32 m0, s43
	s_nop 0
	global_load_lds_dwordx4 v132, s[58:59]
	s_barrier
	s_waitcnt lgkmcnt(0)
	s_setprio 1
	s_waitcnt lgkmcnt(0)
	v_mfma_f32_16x16x32_bf16 v[62:65], v[146:149], v[162:165], v[62:65]
	v_mfma_f32_16x16x32_bf16 v[54:57], v[154:157], v[162:165], v[54:57]
	v_mfma_f32_16x16x32_bf16 v[44:47], v[146:149], v[170:173], v[44:47]
	v_mfma_f32_16x16x32_bf16 v[36:39], v[154:157], v[170:173], v[36:39]
	v_mfma_f32_16x16x32_bf16 v[28:31], v[146:149], v[178:181], v[28:31]
	v_mfma_f32_16x16x32_bf16 v[20:23], v[154:157], v[178:181], v[20:23]
	v_mfma_f32_16x16x32_bf16 v[12:15], v[146:149], v[186:189], v[12:15]
	v_mfma_f32_16x16x32_bf16 v[4:7], v[154:157], v[186:189], v[4:7]
	v_mfma_f32_16x16x32_bf16 v[62:65], v[150:153], v[166:169], v[62:65]
	v_mfma_f32_16x16x32_bf16 v[54:57], v[158:161], v[166:169], v[54:57]
	v_mfma_f32_16x16x32_bf16 v[44:47], v[150:153], v[174:177], v[44:47]
	v_mfma_f32_16x16x32_bf16 v[36:39], v[158:161], v[174:177], v[36:39]
	v_mfma_f32_16x16x32_bf16 v[28:31], v[150:153], v[182:185], v[28:31]
	v_mfma_f32_16x16x32_bf16 v[20:23], v[158:161], v[182:185], v[20:23]
	v_mfma_f32_16x16x32_bf16 v[12:15], v[150:153], v[190:193], v[12:15]
	v_mfma_f32_16x16x32_bf16 v[4:7], v[158:161], v[190:193], v[4:7]
	s_setprio 0
	s_barrier
	s_add_u32 s28, s28, 0x40080
	s_addc_u32 s29, s29, 0
	s_add_i32 s30, s30, s37
	s_mov_b32 m0, s30
	s_nop 0
	global_load_lds_dwordx4 v48, s[28:29]
	s_add_i32 m0, s30, 0x2000
	s_nop 0
	global_load_lds_dwordx4 v130, s[28:29]
	s_waitcnt vmcnt(6)
	s_barrier
	s_setprio 1
	v_mfma_f32_16x16x32_bf16 v[58:61], v[198:201], v[162:165], v[58:61]
	v_mfma_f32_16x16x32_bf16 v[50:53], v[206:209], v[162:165], v[50:53]
	v_mfma_f32_16x16x32_bf16 v[40:43], v[198:201], v[170:173], v[40:43]
	v_mfma_f32_16x16x32_bf16 v[32:35], v[206:209], v[170:173], v[32:35]
	v_mfma_f32_16x16x32_bf16 v[24:27], v[198:201], v[178:181], v[24:27]
	v_mfma_f32_16x16x32_bf16 v[16:19], v[206:209], v[178:181], v[16:19]
	v_mfma_f32_16x16x32_bf16 v[8:11], v[198:201], v[186:189], v[8:11]
	v_mfma_f32_16x16x32_bf16 v[0:3], v[206:209], v[186:189], v[0:3]
	v_mfma_f32_16x16x32_bf16 v[58:61], v[202:205], v[166:169], v[58:61]
	v_mfma_f32_16x16x32_bf16 v[50:53], v[210:213], v[166:169], v[50:53]
	v_mfma_f32_16x16x32_bf16 v[40:43], v[202:205], v[174:177], v[40:43]
	v_mfma_f32_16x16x32_bf16 v[32:35], v[210:213], v[174:177], v[32:35]
	v_mfma_f32_16x16x32_bf16 v[24:27], v[202:205], v[182:185], v[24:27]
	v_mfma_f32_16x16x32_bf16 v[16:19], v[210:213], v[182:185], v[16:19]
	v_mfma_f32_16x16x32_bf16 v[8:11], v[202:205], v[190:193], v[8:11]
	v_mfma_f32_16x16x32_bf16 v[0:3], v[210:213], v[190:193], v[0:3]
	s_setprio 0
	s_add_i32 s45, s45, 2
	s_add_u32 s26, s26, 0x100
	s_addc_u32 s27, s27, 0
	s_add_u32 s15, s15, 0x100
	s_addc_u32 s17, s17, 0
	s_cmp_gt_u32 s45, 13
	s_barrier
	s_cbranch_scc0 .LBB0_1356
	v_mul_f32_e32 v147, 0xbfb8aa3b, v126
	v_exp_f32_e32 v148, v147
	v_mul_f32_e32 v147, 0xbfb8aa3b, v118
	v_exp_f32_e32 v150, v147
	v_mul_f32_e32 v147, 0xbfb8aa3b, v127
	v_exp_f32_e32 v149, v147
	v_lshl_or_b32 v140, s22, 7, v144
	v_lshl_add_u32 v146, s24, 8, v142
	v_ashrrev_i32_e32 v141, 31, v140
	v_pk_add_f32 v[148:149], v[148:149], 1.0 op_sel_hi:[1,0]
	s_movk_i32 s15, 0x1600
	s_mov_b32 s22, s14
	s_mov_b32 s24, s16
	s_mov_b64 s[28:29], s[20:21]
	v_rcp_f32_e32 v147, v149
	s_nop 0
	v_mul_f32_e32 v127, v127, v147
	s_nop 0
	v_rcp_f32_e32 v147, v148
	s_nop 0
	v_mul_f32_e32 v126, v126, v147
	v_pk_mul_f32 v[122:123], v[122:123], v[126:127]
	v_mul_f32_e32 v126, 0xbfb8aa3b, v119
	v_exp_f32_e32 v151, v126
	s_nop 0
	v_pk_add_f32 v[126:127], v[150:151], 1.0 op_sel_hi:[1,0]
	s_nop 0
	s_nop 0
	v_rcp_f32_e32 v147, v127
	s_nop 0
	v_mul_f32_e32 v119, v119, v147
	s_nop 0
	v_rcp_f32_e32 v127, v126
	s_nop 0
	v_mul_f32_e32 v118, v118, v127
	v_pk_mul_f32 v[114:115], v[114:115], v[118:119]
	v_mul_f32_e32 v119, 0xbfb8aa3b, v120
	v_mul_f32_e32 v118, 0xbfb8aa3b, v128
	v_exp_f32_e32 v126, v119
	v_mul_f32_e32 v119, 0xbfb8aa3b, v129
	v_exp_f32_e32 v118, v118
	v_exp_f32_e32 v119, v119
	s_nop 0
	v_pk_add_f32 v[118:119], v[118:119], 1.0 op_sel_hi:[1,0]
	s_nop 0
	s_nop 0
	v_rcp_f32_e32 v127, v119
	s_nop 0
	v_mul_f32_e32 v119, v129, v127
	s_nop 0
	v_rcp_f32_e32 v127, v118
	s_nop 0
	v_mul_f32_e32 v118, v128, v127
	v_pk_mul_f32 v[124:125], v[124:125], v[118:119]
	v_mul_f32_e32 v118, 0xbfb8aa3b, v121
	v_exp_f32_e32 v127, v118
	s_nop 0
	v_pk_add_f32 v[118:119], v[126:127], 1.0 op_sel_hi:[1,0]
	s_nop 0
	s_nop 0
	v_rcp_f32_e32 v126, v119
	s_nop 0
	v_mul_f32_e32 v119, v121, v126
	s_nop 0
	v_rcp_f32_e32 v121, v118
	s_nop 0
	v_mul_f32_e32 v118, v120, v121
	v_pk_mul_f32 v[116:117], v[116:117], v[118:119]
	v_cvt_pk_bf16_f32 v120, v114, v115
	v_mov_b64_e32 v[114:115], s[12:13]
	v_cvt_pk_bf16_f32 v118, v122, v123
	v_cvt_pk_bf16_f32 v121, v116, v117
	v_mad_i64_i32 v[122:123], s[26:27], v146, s15, v[114:115]
	v_lshlrev_b64 v[116:117], 1, v[140:141]
	v_cvt_pk_bf16_f32 v119, v124, v125
	v_lshl_add_u64 v[122:123], v[122:123], 0, v[116:117]
	global_store_dwordx4 v[122:123], v[118:121], off
	s_nop 1
	v_mul_f32_e32 v119, 0xbfb8aa3b, v102
	v_mul_f32_e32 v118, 0xbfb8aa3b, v110
	v_exp_f32_e32 v120, v119
	v_mul_f32_e32 v119, 0xbfb8aa3b, v111
	v_exp_f32_e32 v118, v118
	v_exp_f32_e32 v119, v119
	s_nop 0
	v_pk_add_f32 v[118:119], v[118:119], 1.0 op_sel_hi:[1,0]
	s_nop 0
	s_nop 0
	v_rcp_f32_e32 v121, v119
	s_nop 0
	v_mul_f32_e32 v111, v111, v121
	s_nop 0
	v_rcp_f32_e32 v119, v118
	s_nop 0
	v_mul_f32_e32 v110, v110, v119
	v_pk_mul_f32 v[106:107], v[106:107], v[110:111]
	v_mul_f32_e32 v110, 0xbfb8aa3b, v103
	v_exp_f32_e32 v121, v110
	s_nop 0
	v_pk_add_f32 v[110:111], v[120:121], 1.0 op_sel_hi:[1,0]
	s_nop 0
	s_nop 0
	v_rcp_f32_e32 v118, v111
	s_nop 0
	v_mul_f32_e32 v103, v103, v118
	s_nop 0
	v_rcp_f32_e32 v111, v110
	s_nop 0
	v_mul_f32_e32 v102, v102, v111
	v_pk_mul_f32 v[102:103], v[98:99], v[102:103]
	v_mul_f32_e32 v99, 0xbfb8aa3b, v104
	v_mul_f32_e32 v98, 0xbfb8aa3b, v112
	v_exp_f32_e32 v110, v99
	v_mul_f32_e32 v99, 0xbfb8aa3b, v113
	v_exp_f32_e32 v98, v98
	v_exp_f32_e32 v99, v99
	s_nop 0
	v_pk_add_f32 v[98:99], v[98:99], 1.0 op_sel_hi:[1,0]
	s_nop 0
	s_nop 0
	v_rcp_f32_e32 v111, v99
	s_nop 0
	v_mul_f32_e32 v99, v113, v111
	s_nop 0
	v_rcp_f32_e32 v111, v98
	s_nop 0
	v_mul_f32_e32 v98, v112, v111
	v_pk_mul_f32 v[108:109], v[108:109], v[98:99]
	v_mul_f32_e32 v98, 0xbfb8aa3b, v105
	v_exp_f32_e32 v111, v98
	s_nop 0
	v_pk_add_f32 v[98:99], v[110:111], 1.0 op_sel_hi:[1,0]
	s_nop 0
	s_nop 0
	v_rcp_f32_e32 v110, v99
	s_nop 0
	v_mul_f32_e32 v99, v105, v110
	s_nop 0
	v_rcp_f32_e32 v105, v98
	s_nop 0
	v_mul_f32_e32 v98, v104, v105
	v_or_b32_e32 v110, 16, v146
	v_pk_mul_f32 v[104:105], v[100:101], v[98:99]
	v_cvt_pk_bf16_f32 v100, v102, v103
	v_mad_i64_i32 v[102:103], s[26:27], v110, s15, v[114:115]
	v_cvt_pk_bf16_f32 v98, v106, v107
	v_cvt_pk_bf16_f32 v99, v108, v109
	v_cvt_pk_bf16_f32 v101, v104, v105
	v_lshl_add_u64 v[102:103], v[102:103], 0, v[116:117]
	global_store_dwordx4 v[102:103], v[98:101], off
	s_nop 1
	v_mul_f32_e32 v99, 0xbfb8aa3b, v86
	v_mul_f32_e32 v98, 0xbfb8aa3b, v94
	v_exp_f32_e32 v100, v99
	v_mul_f32_e32 v99, 0xbfb8aa3b, v95
	v_exp_f32_e32 v98, v98
	v_exp_f32_e32 v99, v99
	s_nop 0
	v_pk_add_f32 v[98:99], v[98:99], 1.0 op_sel_hi:[1,0]
	s_nop 0
	s_nop 0
	v_rcp_f32_e32 v101, v99
	s_nop 0
	v_mul_f32_e32 v95, v95, v101
	s_nop 0
	v_rcp_f32_e32 v99, v98
	s_nop 0
	v_mul_f32_e32 v94, v94, v99
	v_pk_mul_f32 v[90:91], v[90:91], v[94:95]
	v_mul_f32_e32 v94, 0xbfb8aa3b, v87
	v_exp_f32_e32 v101, v94
	s_nop 0
	v_pk_add_f32 v[94:95], v[100:101], 1.0 op_sel_hi:[1,0]
	s_nop 0
	s_nop 0
	v_rcp_f32_e32 v98, v95
	s_nop 0
	v_mul_f32_e32 v87, v87, v98
	s_nop 0
	v_rcp_f32_e32 v95, v94
	s_nop 0
	v_mul_f32_e32 v86, v86, v95
	v_pk_mul_f32 v[86:87], v[82:83], v[86:87]
	v_mul_f32_e32 v83, 0xbfb8aa3b, v88
	v_mul_f32_e32 v82, 0xbfb8aa3b, v96
	v_exp_f32_e32 v94, v83
	v_mul_f32_e32 v83, 0xbfb8aa3b, v97
	v_exp_f32_e32 v82, v82
	v_exp_f32_e32 v83, v83
	s_nop 0
	v_pk_add_f32 v[82:83], v[82:83], 1.0 op_sel_hi:[1,0]
	s_nop 0
	s_nop 0
	v_rcp_f32_e32 v95, v83
	s_nop 0
	v_mul_f32_e32 v83, v97, v95
	s_nop 0
	v_rcp_f32_e32 v95, v82
	s_nop 0
	v_mul_f32_e32 v82, v96, v95
	v_pk_mul_f32 v[92:93], v[92:93], v[82:83]
	v_mul_f32_e32 v82, 0xbfb8aa3b, v89
	v_exp_f32_e32 v95, v82
	s_nop 0
	v_pk_add_f32 v[82:83], v[94:95], 1.0 op_sel_hi:[1,0]
	s_nop 0
	s_nop 0
	v_rcp_f32_e32 v94, v83
	s_nop 0
	v_mul_f32_e32 v83, v89, v94
	s_nop 0
	v_rcp_f32_e32 v89, v82
	s_nop 0
	v_mul_f32_e32 v82, v88, v89
	v_or_b32_e32 v94, 32, v146
	v_pk_mul_f32 v[88:89], v[84:85], v[82:83]
	v_cvt_pk_bf16_f32 v84, v86, v87
	v_mad_i64_i32 v[86:87], s[26:27], v94, s15, v[114:115]
	v_cvt_pk_bf16_f32 v82, v90, v91
	v_cvt_pk_bf16_f32 v83, v92, v93
	v_cvt_pk_bf16_f32 v85, v88, v89
	v_lshl_add_u64 v[86:87], v[86:87], 0, v[116:117]
	global_store_dwordx4 v[86:87], v[82:85], off
	s_nop 1
	v_mul_f32_e32 v83, 0xbfb8aa3b, v70
	v_mul_f32_e32 v82, 0xbfb8aa3b, v78
	v_exp_f32_e32 v84, v83
	v_mul_f32_e32 v83, 0xbfb8aa3b, v79
	v_exp_f32_e32 v82, v82
	v_exp_f32_e32 v83, v83
	s_nop 0
	v_pk_add_f32 v[82:83], v[82:83], 1.0 op_sel_hi:[1,0]
	s_nop 0
	s_nop 0
	v_rcp_f32_e32 v85, v83
	s_nop 0
	v_mul_f32_e32 v79, v79, v85
	s_nop 0
	v_rcp_f32_e32 v83, v82
	s_nop 0
	v_mul_f32_e32 v78, v78, v83
	v_pk_mul_f32 v[74:75], v[74:75], v[78:79]
	v_mul_f32_e32 v78, 0xbfb8aa3b, v71
	v_exp_f32_e32 v85, v78
	s_nop 0
	v_pk_add_f32 v[78:79], v[84:85], 1.0 op_sel_hi:[1,0]
	s_nop 0
	s_nop 0
	v_rcp_f32_e32 v82, v79
	s_nop 0
	v_mul_f32_e32 v71, v71, v82
	s_nop 0
	v_rcp_f32_e32 v79, v78
	s_nop 0
	v_mul_f32_e32 v70, v70, v79
	v_pk_mul_f32 v[70:71], v[66:67], v[70:71]
	v_mul_f32_e32 v67, 0xbfb8aa3b, v72
	v_mul_f32_e32 v66, 0xbfb8aa3b, v80
	v_exp_f32_e32 v78, v67
	v_mul_f32_e32 v67, 0xbfb8aa3b, v81
	v_exp_f32_e32 v66, v66
	v_exp_f32_e32 v67, v67
	s_nop 0
	v_pk_add_f32 v[66:67], v[66:67], 1.0 op_sel_hi:[1,0]
	s_nop 0
	s_nop 0
	v_rcp_f32_e32 v79, v67
	s_nop 0
	v_mul_f32_e32 v67, v81, v79
	s_nop 0
	v_rcp_f32_e32 v79, v66
	s_nop 0
	v_mul_f32_e32 v66, v80, v79
	v_pk_mul_f32 v[76:77], v[76:77], v[66:67]
	v_mul_f32_e32 v66, 0xbfb8aa3b, v73
	v_exp_f32_e32 v79, v66
	s_nop 0
	v_pk_add_f32 v[66:67], v[78:79], 1.0 op_sel_hi:[1,0]
	s_nop 0
	s_nop 0
	v_rcp_f32_e32 v78, v67
	s_nop 0
	v_mul_f32_e32 v67, v73, v78
	s_nop 0
	v_rcp_f32_e32 v73, v66
	s_nop 0
	v_mul_f32_e32 v66, v72, v73
	v_or_b32_e32 v78, 48, v146
	v_pk_mul_f32 v[72:73], v[68:69], v[66:67]
	v_cvt_pk_bf16_f32 v68, v70, v71
	v_mad_i64_i32 v[70:71], s[26:27], v78, s15, v[114:115]
	v_cvt_pk_bf16_f32 v66, v74, v75
	v_cvt_pk_bf16_f32 v67, v76, v77
	v_cvt_pk_bf16_f32 v69, v72, v73
	v_lshl_add_u64 v[70:71], v[70:71], 0, v[116:117]
	global_store_dwordx4 v[70:71], v[66:69], off
	v_add_u32_e32 v70, 0x80, v146
	s_nop 0
	v_mul_f32_e32 v67, 0xbfb8aa3b, v54
	v_mul_f32_e32 v66, 0xbfb8aa3b, v62
	v_exp_f32_e32 v68, v67
	v_mul_f32_e32 v67, 0xbfb8aa3b, v63
	v_exp_f32_e32 v66, v66
	v_exp_f32_e32 v67, v67
	s_nop 0
	v_pk_add_f32 v[66:67], v[66:67], 1.0 op_sel_hi:[1,0]
	s_nop 0
	s_nop 0
	v_rcp_f32_e32 v69, v67
	s_nop 0
	v_mul_f32_e32 v63, v63, v69
	s_nop 0
	v_rcp_f32_e32 v67, v66
	s_nop 0
	v_mul_f32_e32 v62, v62, v67
	v_pk_mul_f32 v[58:59], v[58:59], v[62:63]
	v_mul_f32_e32 v62, 0xbfb8aa3b, v55
	v_exp_f32_e32 v69, v62
	s_nop 0
	v_pk_add_f32 v[62:63], v[68:69], 1.0 op_sel_hi:[1,0]
	s_nop 0
	s_nop 0
	v_rcp_f32_e32 v66, v63
	s_nop 0
	v_mul_f32_e32 v55, v55, v66
	s_nop 0
	v_rcp_f32_e32 v63, v62
	s_nop 0
	v_mul_f32_e32 v54, v54, v63
	v_pk_mul_f32 v[54:55], v[50:51], v[54:55]
	v_mul_f32_e32 v51, 0xbfb8aa3b, v56
	v_mul_f32_e32 v50, 0xbfb8aa3b, v64
	v_exp_f32_e32 v62, v51
	v_mul_f32_e32 v51, 0xbfb8aa3b, v65
	v_exp_f32_e32 v50, v50
	v_exp_f32_e32 v51, v51
	s_nop 0
	v_pk_add_f32 v[50:51], v[50:51], 1.0 op_sel_hi:[1,0]
	s_nop 0
	s_nop 0
	v_rcp_f32_e32 v63, v51
	s_nop 0
	v_mul_f32_e32 v51, v65, v63
	s_nop 0
	v_rcp_f32_e32 v63, v50
	s_nop 0
	v_mul_f32_e32 v50, v64, v63
	v_pk_mul_f32 v[60:61], v[60:61], v[50:51]
	v_mul_f32_e32 v50, 0xbfb8aa3b, v57
	v_exp_f32_e32 v63, v50
	s_nop 0
	v_pk_add_f32 v[50:51], v[62:63], 1.0 op_sel_hi:[1,0]
	s_nop 0
	s_nop 0
	v_rcp_f32_e32 v62, v51
	s_nop 0
	v_mul_f32_e32 v51, v57, v62
	s_nop 0
	v_rcp_f32_e32 v57, v50
	s_nop 0
	v_mul_f32_e32 v50, v56, v57
	v_pk_mul_f32 v[56:57], v[52:53], v[50:51]
	v_cvt_pk_bf16_f32 v52, v54, v55
	v_mad_i64_i32 v[54:55], s[26:27], v70, s15, v[114:115]
	v_cvt_pk_bf16_f32 v50, v58, v59
	v_cvt_pk_bf16_f32 v51, v60, v61
	v_cvt_pk_bf16_f32 v53, v56, v57
	v_lshl_add_u64 v[54:55], v[54:55], 0, v[116:117]
	global_store_dwordx4 v[54:55], v[50:53], off
	s_nop 1
	v_mul_f32_e32 v51, 0xbfb8aa3b, v36
	v_mul_f32_e32 v50, 0xbfb8aa3b, v44
	v_exp_f32_e32 v52, v51
	v_mul_f32_e32 v51, 0xbfb8aa3b, v45
	v_exp_f32_e32 v50, v50
	v_exp_f32_e32 v51, v51
	s_nop 0
	v_pk_add_f32 v[50:51], v[50:51], 1.0 op_sel_hi:[1,0]
	s_nop 0
	s_nop 0
	v_rcp_f32_e32 v53, v51
	s_nop 0
	v_mul_f32_e32 v45, v45, v53
	s_nop 0
	v_rcp_f32_e32 v51, v50
	s_nop 0
	v_mul_f32_e32 v44, v44, v51
	v_pk_mul_f32 v[40:41], v[40:41], v[44:45]
	v_mul_f32_e32 v44, 0xbfb8aa3b, v37
	v_exp_f32_e32 v53, v44
	s_nop 0
	v_pk_add_f32 v[44:45], v[52:53], 1.0 op_sel_hi:[1,0]
	s_nop 0
	s_nop 0
	v_rcp_f32_e32 v50, v45
	s_nop 0
	v_mul_f32_e32 v37, v37, v50
	s_nop 0
	v_rcp_f32_e32 v45, v44
	s_nop 0
	v_mul_f32_e32 v36, v36, v45
	v_pk_mul_f32 v[36:37], v[32:33], v[36:37]
	v_mul_f32_e32 v33, 0xbfb8aa3b, v38
	v_mul_f32_e32 v32, 0xbfb8aa3b, v46
	v_exp_f32_e32 v44, v33
	v_mul_f32_e32 v33, 0xbfb8aa3b, v47
	v_exp_f32_e32 v32, v32
	v_exp_f32_e32 v33, v33
	s_nop 0
	v_pk_add_f32 v[32:33], v[32:33], 1.0 op_sel_hi:[1,0]
	s_nop 0
	s_nop 0
	v_rcp_f32_e32 v45, v33
	s_nop 0
	v_mul_f32_e32 v33, v47, v45
	s_nop 0
	v_rcp_f32_e32 v45, v32
	s_nop 0
	v_mul_f32_e32 v32, v46, v45
	v_pk_mul_f32 v[42:43], v[42:43], v[32:33]
	v_mul_f32_e32 v32, 0xbfb8aa3b, v39
	v_exp_f32_e32 v45, v32
	s_nop 0
	v_pk_add_f32 v[32:33], v[44:45], 1.0 op_sel_hi:[1,0]
	s_nop 0
	s_nop 0
	v_rcp_f32_e32 v44, v33
	s_nop 0
	v_mul_f32_e32 v33, v39, v44
	s_nop 0
	v_rcp_f32_e32 v39, v32
	s_nop 0
	v_mul_f32_e32 v32, v38, v39
	v_add_u32_e32 v44, 0x90, v146
	v_pk_mul_f32 v[38:39], v[34:35], v[32:33]
	v_cvt_pk_bf16_f32 v34, v36, v37
	v_mad_i64_i32 v[36:37], s[26:27], v44, s15, v[114:115]
	v_cvt_pk_bf16_f32 v32, v40, v41
	v_cvt_pk_bf16_f32 v33, v42, v43
	v_cvt_pk_bf16_f32 v35, v38, v39
	v_lshl_add_u64 v[36:37], v[36:37], 0, v[116:117]
	global_store_dwordx4 v[36:37], v[32:35], off
	s_nop 1
	v_mul_f32_e32 v33, 0xbfb8aa3b, v20
	v_mul_f32_e32 v32, 0xbfb8aa3b, v28
	v_exp_f32_e32 v34, v33
	v_mul_f32_e32 v33, 0xbfb8aa3b, v29
	v_exp_f32_e32 v32, v32
	v_exp_f32_e32 v33, v33
	s_nop 0
	v_pk_add_f32 v[32:33], v[32:33], 1.0 op_sel_hi:[1,0]
	s_nop 0
	s_nop 0
	v_rcp_f32_e32 v35, v33
	s_nop 0
	v_mul_f32_e32 v29, v29, v35
	s_nop 0
	v_rcp_f32_e32 v33, v32
	s_nop 0
	v_mul_f32_e32 v28, v28, v33
	v_pk_mul_f32 v[24:25], v[24:25], v[28:29]
	v_mul_f32_e32 v28, 0xbfb8aa3b, v21
	v_exp_f32_e32 v35, v28
	s_nop 0
	v_pk_add_f32 v[28:29], v[34:35], 1.0 op_sel_hi:[1,0]
	s_nop 0
	s_nop 0
	v_rcp_f32_e32 v32, v29
	s_nop 0
	v_mul_f32_e32 v21, v21, v32
	s_nop 0
	v_rcp_f32_e32 v29, v28
	s_nop 0
	v_mul_f32_e32 v20, v20, v29
	v_pk_mul_f32 v[20:21], v[16:17], v[20:21]
	v_mul_f32_e32 v17, 0xbfb8aa3b, v22
	v_mul_f32_e32 v16, 0xbfb8aa3b, v30
	v_exp_f32_e32 v28, v17
	v_mul_f32_e32 v17, 0xbfb8aa3b, v31
	v_exp_f32_e32 v16, v16
	v_exp_f32_e32 v17, v17
	s_nop 0
	v_pk_add_f32 v[16:17], v[16:17], 1.0 op_sel_hi:[1,0]
	s_nop 0
	s_nop 0
	v_rcp_f32_e32 v29, v17
	s_nop 0
	v_mul_f32_e32 v17, v31, v29
	s_nop 0
	v_rcp_f32_e32 v29, v16
	s_nop 0
	v_mul_f32_e32 v16, v30, v29
	v_pk_mul_f32 v[26:27], v[26:27], v[16:17]
	v_mul_f32_e32 v16, 0xbfb8aa3b, v23
	v_exp_f32_e32 v29, v16
	s_nop 0
	v_pk_add_f32 v[16:17], v[28:29], 1.0 op_sel_hi:[1,0]
	s_nop 0
	s_nop 0
	v_rcp_f32_e32 v28, v17
	s_nop 0
	v_mul_f32_e32 v17, v23, v28
	s_nop 0
	v_rcp_f32_e32 v23, v16
	s_nop 0
	v_mul_f32_e32 v16, v22, v23
	v_add_u32_e32 v28, 0xa0, v146
	v_pk_mul_f32 v[22:23], v[18:19], v[16:17]
	v_cvt_pk_bf16_f32 v18, v20, v21
	v_mad_i64_i32 v[20:21], s[26:27], v28, s15, v[114:115]
	v_cvt_pk_bf16_f32 v16, v24, v25
	v_cvt_pk_bf16_f32 v17, v26, v27
	v_cvt_pk_bf16_f32 v19, v22, v23
	v_lshl_add_u64 v[20:21], v[20:21], 0, v[116:117]
	global_store_dwordx4 v[20:21], v[16:19], off
	s_nop 1
	v_mul_f32_e32 v17, 0xbfb8aa3b, v4
	v_mul_f32_e32 v16, 0xbfb8aa3b, v12
	v_exp_f32_e32 v18, v17
	v_mul_f32_e32 v17, 0xbfb8aa3b, v13
	v_exp_f32_e32 v16, v16
	v_exp_f32_e32 v17, v17
	s_nop 0
	v_pk_add_f32 v[16:17], v[16:17], 1.0 op_sel_hi:[1,0]
	s_nop 0
	s_nop 0
	v_rcp_f32_e32 v19, v17
	s_nop 0
	v_mul_f32_e32 v13, v13, v19
	s_nop 0
	v_rcp_f32_e32 v17, v16
	s_nop 0
	v_mul_f32_e32 v12, v12, v17
	v_pk_mul_f32 v[8:9], v[8:9], v[12:13]
	v_mul_f32_e32 v12, 0xbfb8aa3b, v5
	v_exp_f32_e32 v19, v12
	s_nop 0
	v_pk_add_f32 v[12:13], v[18:19], 1.0 op_sel_hi:[1,0]
	s_nop 0
	s_nop 0
	v_rcp_f32_e32 v16, v13
	s_nop 0
	v_mul_f32_e32 v5, v5, v16
	s_nop 0
	v_rcp_f32_e32 v13, v12
	s_nop 0
	v_mul_f32_e32 v4, v4, v13
	v_pk_mul_f32 v[4:5], v[0:1], v[4:5]
	v_mul_f32_e32 v1, 0xbfb8aa3b, v6
	v_mul_f32_e32 v0, 0xbfb8aa3b, v14
	v_exp_f32_e32 v12, v1
	v_mul_f32_e32 v1, 0xbfb8aa3b, v15
	v_exp_f32_e32 v0, v0
	v_exp_f32_e32 v1, v1
	s_nop 0
	v_pk_add_f32 v[0:1], v[0:1], 1.0 op_sel_hi:[1,0]
	s_nop 0
	s_nop 0
	v_rcp_f32_e32 v13, v1
	s_nop 0
	v_mul_f32_e32 v1, v15, v13
	s_nop 0
	v_rcp_f32_e32 v13, v0
	s_nop 0
	v_mul_f32_e32 v0, v14, v13
	v_pk_mul_f32 v[10:11], v[10:11], v[0:1]
	v_mul_f32_e32 v0, 0xbfb8aa3b, v7
	v_exp_f32_e32 v13, v0
	s_nop 0
	v_pk_add_f32 v[0:1], v[12:13], 1.0 op_sel_hi:[1,0]
	s_nop 0
	s_nop 0
	v_rcp_f32_e32 v12, v1
	s_nop 0
	v_mul_f32_e32 v1, v7, v12
	s_nop 0
	v_rcp_f32_e32 v7, v0
	s_nop 0
	v_mul_f32_e32 v0, v6, v7
	v_add_u32_e32 v12, 0xb0, v146
	v_pk_mul_f32 v[6:7], v[2:3], v[0:1]
	v_cvt_pk_bf16_f32 v2, v4, v5
	v_mad_i64_i32 v[4:5], s[26:27], v12, s15, v[114:115]
	v_cvt_pk_bf16_f32 v0, v8, v9
	v_cvt_pk_bf16_f32 v1, v10, v11
	v_cvt_pk_bf16_f32 v3, v6, v7
	v_lshl_add_u64 v[4:5], v[4:5], 0, v[116:117]
	s_and_b64 vcc, exec, s[0:1]
	s_mov_b64 s[26:27], s[18:19]
	global_store_dwordx4 v[4:5], v[0:3], off
	s_cbranch_vccz .LBB0_1353
	s_waitcnt vmcnt(0)
	s_cmpk_gt_u32 s5, 0xff
	s_cbranch_scc1 .LBB0_1360
	s_barrier

.LBB0_1421:
	s_add_u32 s18, s16, 0x100
	s_addc_u32 s19, s17, 0
	s_add_i32 s47, 0, 0x10000
	ds_read_b128 v[130:133], v202
	ds_read_b128 v[134:137], v202 offset:1024
	ds_read_b128 v[138:141], v202 offset:2048
	ds_read_b128 v[142:145], v202 offset:3072
	s_cmp_eq_u32 s46, 40
	s_cselect_b32 s23, s11, s19
	s_cselect_b32 s22, s10, s18
	s_cselect_b32 s21, s13, s45
	s_cselect_b32 s20, s12, s44
	v_lshl_add_u64 v[188:189], s[16:17], 0, v[152:153]
	s_add_i32 m0, s31, 0xc000
	ds_read_b128 v[156:159], v206
	ds_read_b128 v[160:163], v206 offset:1024
	ds_read_b128 v[164:167], v206 offset:2048
	ds_read_b128 v[168:171], v206 offset:3072
	ds_read_b128 v[172:175], v206 offset:4096
	ds_read_b128 v[176:179], v206 offset:5120
	ds_read_b128 v[180:183], v206 offset:6144
	ds_read_b128 v[184:187], v206 offset:7168
	global_load_lds_dwordx4 v[188:189], off
	v_lshl_add_u64 v[188:189], s[16:17], 0, v[154:155]
	s_add_i32 m0, s31, 0xe000
	s_nop 0
	global_load_lds_dwordx4 v[188:189], off
	s_waitcnt lgkmcnt(8)
	s_barrier
	s_waitcnt lgkmcnt(0)
	s_setprio 1
	s_waitcnt lgkmcnt(0)
	v_mfma_f32_16x16x32_bf16 v[126:129], v[130:133], v[156:159], v[126:129]
	v_mfma_f32_16x16x32_bf16 v[122:125], v[138:141], v[156:159], v[122:125]
	v_mfma_f32_16x16x32_bf16 v[114:117], v[130:133], v[164:167], v[114:117]
	v_mfma_f32_16x16x32_bf16 v[106:109], v[138:141], v[164:167], v[106:109]
	v_mfma_f32_16x16x32_bf16 v[98:101], v[130:133], v[172:175], v[98:101]
	v_mfma_f32_16x16x32_bf16 v[90:93], v[138:141], v[172:175], v[90:93]
	v_mfma_f32_16x16x32_bf16 v[82:85], v[130:133], v[180:183], v[82:85]
	v_mfma_f32_16x16x32_bf16 v[74:77], v[138:141], v[180:183], v[74:77]
	v_mfma_f32_16x16x32_bf16 v[126:129], v[134:137], v[160:163], v[126:129]
	v_mfma_f32_16x16x32_bf16 v[122:125], v[142:145], v[160:163], v[122:125]
	v_mfma_f32_16x16x32_bf16 v[114:117], v[134:137], v[168:171], v[114:117]
	v_mfma_f32_16x16x32_bf16 v[106:109], v[142:145], v[168:171], v[106:109]
	v_mfma_f32_16x16x32_bf16 v[98:101], v[134:137], v[176:179], v[98:101]
	v_mfma_f32_16x16x32_bf16 v[90:93], v[142:145], v[176:179], v[90:93]
	v_mfma_f32_16x16x32_bf16 v[82:85], v[134:137], v[184:187], v[82:85]
	v_mfma_f32_16x16x32_bf16 v[74:77], v[142:145], v[184:187], v[74:77]
	s_setprio 0
	s_barrier
	s_add_i32 s48, 0, 0x14000
	s_add_i32 s16, s47, s25
	ds_read_b128 v[188:191], v202 offset:16384
	ds_read_b128 v[198:201], v202 offset:17408
	ds_read_b128 v[208:211], v202 offset:18432
	ds_read_b128 v[212:215], v202 offset:19456
	s_mov_b32 m0, s16
	global_load_lds_dwordx4 v48, s[20:21]
	s_add_i32 m0, s16, 0x2000
	s_nop 0
	global_load_lds_dwordx4 v146, s[20:21]
	s_barrier
	s_waitcnt lgkmcnt(0)
	s_setprio 1
	s_waitcnt lgkmcnt(0)
	v_mfma_f32_16x16x32_bf16 v[118:121], v[188:191], v[156:159], v[118:121]
	v_mfma_f32_16x16x32_bf16 v[110:113], v[208:211], v[156:159], v[110:113]
	v_mfma_f32_16x16x32_bf16 v[102:105], v[188:191], v[164:167], v[102:105]
	v_mfma_f32_16x16x32_bf16 v[94:97], v[208:211], v[164:167], v[94:97]
	v_mfma_f32_16x16x32_bf16 v[86:89], v[188:191], v[172:175], v[86:89]
	v_mfma_f32_16x16x32_bf16 v[78:81], v[208:211], v[172:175], v[78:81]
	v_mfma_f32_16x16x32_bf16 v[70:73], v[188:191], v[180:183], v[70:73]
	v_mfma_f32_16x16x32_bf16 v[66:69], v[208:211], v[180:183], v[66:69]
	v_mfma_f32_16x16x32_bf16 v[118:121], v[198:201], v[160:163], v[118:121]
	v_mfma_f32_16x16x32_bf16 v[110:113], v[212:215], v[160:163], v[110:113]
	v_mfma_f32_16x16x32_bf16 v[102:105], v[198:201], v[168:171], v[102:105]
	v_mfma_f32_16x16x32_bf16 v[94:97], v[212:215], v[168:171], v[94:97]
	v_mfma_f32_16x16x32_bf16 v[86:89], v[198:201], v[176:179], v[86:89]
	v_mfma_f32_16x16x32_bf16 v[78:81], v[212:215], v[176:179], v[78:81]
	v_mfma_f32_16x16x32_bf16 v[70:73], v[198:201], v[184:187], v[70:73]
	v_mfma_f32_16x16x32_bf16 v[66:69], v[212:215], v[184:187], v[66:69]
	s_setprio 0
	s_mov_b32 m0, s31
	s_add_u32 s58, s22, s66
	s_addc_u32 s59, s23, s67
	s_barrier
	ds_read_b128 v[156:159], v206 offset:16384
	ds_read_b128 v[160:163], v206 offset:17408
	ds_read_b128 v[164:167], v206 offset:18432
	ds_read_b128 v[168:171], v206 offset:19456
	ds_read_b128 v[172:175], v206 offset:20480
	ds_read_b128 v[176:179], v206 offset:21504
	ds_read_b128 v[180:183], v206 offset:22528
	ds_read_b128 v[184:187], v206 offset:23552
	global_load_lds_dwordx4 v48, s[22:23]
	s_mov_b32 m0, s34
	s_nop 0
	global_load_lds_dwordx4 v146, s[22:23]
	s_barrier
	s_waitcnt lgkmcnt(0)
	s_setprio 1
	s_waitcnt lgkmcnt(0)
	v_mfma_f32_16x16x32_bf16 v[62:65], v[130:133], v[156:159], v[62:65]
	v_mfma_f32_16x16x32_bf16 v[58:61], v[138:141], v[156:159], v[58:61]
	v_mfma_f32_16x16x32_bf16 v[50:53], v[130:133], v[164:167], v[50:53]
	v_mfma_f32_16x16x32_bf16 v[40:43], v[138:141], v[164:167], v[40:43]
	v_mfma_f32_16x16x32_bf16 v[32:35], v[130:133], v[172:175], v[32:35]
	v_mfma_f32_16x16x32_bf16 v[24:27], v[138:141], v[172:175], v[24:27]
	v_mfma_f32_16x16x32_bf16 v[16:19], v[130:133], v[180:183], v[16:19]
	v_mfma_f32_16x16x32_bf16 v[8:11], v[138:141], v[180:183], v[8:11]
	v_mfma_f32_16x16x32_bf16 v[62:65], v[134:137], v[160:163], v[62:65]
	v_mfma_f32_16x16x32_bf16 v[58:61], v[142:145], v[160:163], v[58:61]
	v_mfma_f32_16x16x32_bf16 v[50:53], v[134:137], v[168:171], v[50:53]
	v_mfma_f32_16x16x32_bf16 v[40:43], v[142:145], v[168:171], v[40:43]
	v_mfma_f32_16x16x32_bf16 v[32:35], v[134:137], v[176:179], v[32:35]
	v_mfma_f32_16x16x32_bf16 v[24:27], v[142:145], v[176:179], v[24:27]
	v_mfma_f32_16x16x32_bf16 v[16:19], v[134:137], v[184:187], v[16:19]
	v_mfma_f32_16x16x32_bf16 v[8:11], v[142:145], v[184:187], v[8:11]
	s_setprio 0
	s_barrier
	s_add_u32 s16, s20, 0xb0000
	s_addc_u32 s17, s21, 0
	s_add_i32 s47, s48, s25
	s_mov_b32 m0, s47
	s_nop 0
	global_load_lds_dwordx4 v48, s[16:17]
	s_add_i32 m0, s47, 0x2000
	s_nop 0
	global_load_lds_dwordx4 v146, s[16:17]
	s_waitcnt vmcnt(6)
	s_barrier
	s_setprio 1
	v_mfma_f32_16x16x32_bf16 v[54:57], v[188:191], v[156:159], v[54:57]
	v_mfma_f32_16x16x32_bf16 v[44:47], v[208:211], v[156:159], v[44:47]
	v_mfma_f32_16x16x32_bf16 v[36:39], v[188:191], v[164:167], v[36:39]
	v_mfma_f32_16x16x32_bf16 v[28:31], v[208:211], v[164:167], v[28:31]
	v_mfma_f32_16x16x32_bf16 v[20:23], v[188:191], v[172:175], v[20:23]
	v_mfma_f32_16x16x32_bf16 v[12:15], v[208:211], v[172:175], v[12:15]
	v_mfma_f32_16x16x32_bf16 v[4:7], v[188:191], v[180:183], v[4:7]
	v_mfma_f32_16x16x32_bf16 v[0:3], v[208:211], v[180:183], v[0:3]
	v_mfma_f32_16x16x32_bf16 v[54:57], v[198:201], v[160:163], v[54:57]
	v_mfma_f32_16x16x32_bf16 v[44:47], v[212:215], v[160:163], v[44:47]
	v_mfma_f32_16x16x32_bf16 v[36:39], v[198:201], v[168:171], v[36:39]
	v_mfma_f32_16x16x32_bf16 v[28:31], v[212:215], v[168:171], v[28:31]
	v_mfma_f32_16x16x32_bf16 v[20:23], v[198:201], v[176:179], v[20:23]
	v_mfma_f32_16x16x32_bf16 v[12:15], v[212:215], v[176:179], v[12:15]
	v_mfma_f32_16x16x32_bf16 v[4:7], v[198:201], v[184:187], v[4:7]
	v_mfma_f32_16x16x32_bf16 v[0:3], v[212:215], v[184:187], v[0:3]
	s_setprio 0
	s_add_i32 s47, 0, 0x18000
	s_barrier
	ds_read_b128 v[130:133], v202 offset:32768
	ds_read_b128 v[134:137], v202 offset:33792
	ds_read_b128 v[138:141], v202 offset:34816
	ds_read_b128 v[142:145], v202 offset:35840
	s_add_u32 s16, s22, 0xb0000
	s_addc_u32 s17, s23, 0
	s_mov_b32 m0, s35
	ds_read_b128 v[156:159], v206 offset:32768
	ds_read_b128 v[160:163], v206 offset:33792
	ds_read_b128 v[164:167], v206 offset:34816
	ds_read_b128 v[168:171], v206 offset:35840
	ds_read_b128 v[172:175], v206 offset:36864
	ds_read_b128 v[176:179], v206 offset:37888
	ds_read_b128 v[180:183], v206 offset:38912
	ds_read_b128 v[184:187], v206 offset:39936
	global_load_lds_dwordx4 v48, s[16:17]
	s_mov_b32 m0, s36
	s_nop 0
	global_load_lds_dwordx4 v146, s[16:17]
	s_waitcnt lgkmcnt(8)
	s_barrier
	s_waitcnt lgkmcnt(0)
	s_setprio 1
	s_waitcnt lgkmcnt(0)
	v_mfma_f32_16x16x32_bf16 v[126:129], v[130:133], v[156:159], v[126:129]
	v_mfma_f32_16x16x32_bf16 v[122:125], v[138:141], v[156:159], v[122:125]
	v_mfma_f32_16x16x32_bf16 v[114:117], v[130:133], v[164:167], v[114:117]
	v_mfma_f32_16x16x32_bf16 v[106:109], v[138:141], v[164:167], v[106:109]
	v_mfma_f32_16x16x32_bf16 v[98:101], v[130:133], v[172:175], v[98:101]
	v_mfma_f32_16x16x32_bf16 v[90:93], v[138:141], v[172:175], v[90:93]
	v_mfma_f32_16x16x32_bf16 v[82:85], v[130:133], v[180:183], v[82:85]
	v_mfma_f32_16x16x32_bf16 v[74:77], v[138:141], v[180:183], v[74:77]
	v_mfma_f32_16x16x32_bf16 v[126:129], v[134:137], v[160:163], v[126:129]
	v_mfma_f32_16x16x32_bf16 v[122:125], v[142:145], v[160:163], v[122:125]
	v_mfma_f32_16x16x32_bf16 v[114:117], v[134:137], v[168:171], v[114:117]
	v_mfma_f32_16x16x32_bf16 v[106:109], v[142:145], v[168:171], v[106:109]
	v_mfma_f32_16x16x32_bf16 v[98:101], v[134:137], v[176:179], v[98:101]
	v_mfma_f32_16x16x32_bf16 v[90:93], v[142:145], v[176:179], v[90:93]
	v_mfma_f32_16x16x32_bf16 v[82:85], v[134:137], v[184:187], v[82:85]
	v_mfma_f32_16x16x32_bf16 v[74:77], v[142:145], v[184:187], v[74:77]
	s_setprio 0
	s_barrier
	s_add_i32 s22, 0, 0x1c000
	s_add_i32 s16, s47, s25
	s_add_u32 s52, s20, s66
	s_addc_u32 s53, s21, s67
	s_mov_b32 m0, s16
	ds_read_b128 v[188:191], v202 offset:49152
	ds_read_b128 v[198:201], v202 offset:50176
	ds_read_b128 v[208:211], v202 offset:51200
	ds_read_b128 v[212:215], v202 offset:52224
	global_load_lds_dwordx4 v48, s[52:53]
	s_add_i32 m0, s16, 0x2000
	s_nop 0
	global_load_lds_dwordx4 v146, s[52:53]
	s_barrier
	s_waitcnt lgkmcnt(0)
	s_setprio 1
	s_waitcnt lgkmcnt(0)
	v_mfma_f32_16x16x32_bf16 v[118:121], v[188:191], v[156:159], v[118:121]
	v_mfma_f32_16x16x32_bf16 v[110:113], v[208:211], v[156:159], v[110:113]
	v_mfma_f32_16x16x32_bf16 v[102:105], v[188:191], v[164:167], v[102:105]
	v_mfma_f32_16x16x32_bf16 v[94:97], v[208:211], v[164:167], v[94:97]
	v_mfma_f32_16x16x32_bf16 v[86:89], v[188:191], v[172:175], v[86:89]
	v_mfma_f32_16x16x32_bf16 v[78:81], v[208:211], v[172:175], v[78:81]
	v_mfma_f32_16x16x32_bf16 v[70:73], v[188:191], v[180:183], v[70:73]
	v_mfma_f32_16x16x32_bf16 v[66:69], v[208:211], v[180:183], v[66:69]
	v_mfma_f32_16x16x32_bf16 v[118:121], v[198:201], v[160:163], v[118:121]
	v_mfma_f32_16x16x32_bf16 v[110:113], v[212:215], v[160:163], v[110:113]
	v_mfma_f32_16x16x32_bf16 v[102:105], v[198:201], v[168:171], v[102:105]
	v_mfma_f32_16x16x32_bf16 v[94:97], v[212:215], v[168:171], v[94:97]
	v_mfma_f32_16x16x32_bf16 v[86:89], v[198:201], v[176:179], v[86:89]
	v_mfma_f32_16x16x32_bf16 v[78:81], v[212:215], v[176:179], v[78:81]
	v_mfma_f32_16x16x32_bf16 v[70:73], v[198:201], v[184:187], v[70:73]
	v_mfma_f32_16x16x32_bf16 v[66:69], v[212:215], v[184:187], v[66:69]
	s_setprio 0
	s_mov_b32 m0, s39
	s_barrier
	ds_read_b128 v[156:159], v206 offset:49152
	ds_read_b128 v[160:163], v206 offset:50176
	ds_read_b128 v[164:167], v206 offset:51200
	ds_read_b128 v[168:171], v206 offset:52224
	ds_read_b128 v[172:175], v206 offset:53248
	ds_read_b128 v[176:179], v206 offset:54272
	ds_read_b128 v[180:183], v206 offset:55296
	ds_read_b128 v[184:187], v206 offset:56320
	global_load_lds_dwordx4 v48, s[58:59]
	s_mov_b32 m0, s40
	s_nop 0
	global_load_lds_dwordx4 v146, s[58:59]
	s_barrier
	s_waitcnt lgkmcnt(0)
	s_setprio 1
	s_waitcnt lgkmcnt(0)
	v_mfma_f32_16x16x32_bf16 v[62:65], v[130:133], v[156:159], v[62:65]
	v_mfma_f32_16x16x32_bf16 v[58:61], v[138:141], v[156:159], v[58:61]
	v_mfma_f32_16x16x32_bf16 v[50:53], v[130:133], v[164:167], v[50:53]
	v_mfma_f32_16x16x32_bf16 v[40:43], v[138:141], v[164:167], v[40:43]
	v_mfma_f32_16x16x32_bf16 v[32:35], v[130:133], v[172:175], v[32:35]
	v_mfma_f32_16x16x32_bf16 v[24:27], v[138:141], v[172:175], v[24:27]
	v_mfma_f32_16x16x32_bf16 v[16:19], v[130:133], v[180:183], v[16:19]
	v_mfma_f32_16x16x32_bf16 v[8:11], v[138:141], v[180:183], v[8:11]
	v_mfma_f32_16x16x32_bf16 v[62:65], v[134:137], v[160:163], v[62:65]
	v_mfma_f32_16x16x32_bf16 v[58:61], v[142:145], v[160:163], v[58:61]
	v_mfma_f32_16x16x32_bf16 v[50:53], v[134:137], v[168:171], v[50:53]
	v_mfma_f32_16x16x32_bf16 v[40:43], v[142:145], v[168:171], v[40:43]
	v_mfma_f32_16x16x32_bf16 v[32:35], v[134:137], v[176:179], v[32:35]
	v_mfma_f32_16x16x32_bf16 v[24:27], v[142:145], v[176:179], v[24:27]
	v_mfma_f32_16x16x32_bf16 v[16:19], v[134:137], v[184:187], v[16:19]
	v_mfma_f32_16x16x32_bf16 v[8:11], v[142:145], v[184:187], v[8:11]
	s_setprio 0
	s_barrier
	s_add_u32 s16, s20, 0xb0080
	s_addc_u32 s17, s21, 0
	s_add_i32 s20, s22, s25
	s_mov_b32 m0, s20
	s_nop 0
	global_load_lds_dwordx4 v48, s[16:17]
	s_add_i32 m0, s20, 0x2000
	s_nop 0
	global_load_lds_dwordx4 v146, s[16:17]
	s_waitcnt vmcnt(6)
	s_barrier
	s_setprio 1
	v_mfma_f32_16x16x32_bf16 v[54:57], v[188:191], v[156:159], v[54:57]
	v_mfma_f32_16x16x32_bf16 v[44:47], v[208:211], v[156:159], v[44:47]
	v_mfma_f32_16x16x32_bf16 v[36:39], v[188:191], v[164:167], v[36:39]
	v_mfma_f32_16x16x32_bf16 v[28:31], v[208:211], v[164:167], v[28:31]
	v_mfma_f32_16x16x32_bf16 v[20:23], v[188:191], v[172:175], v[20:23]
	v_mfma_f32_16x16x32_bf16 v[12:15], v[208:211], v[172:175], v[12:15]
	v_mfma_f32_16x16x32_bf16 v[4:7], v[188:191], v[180:183], v[4:7]
	v_mfma_f32_16x16x32_bf16 v[0:3], v[208:211], v[180:183], v[0:3]
	v_mfma_f32_16x16x32_bf16 v[54:57], v[198:201], v[160:163], v[54:57]
	v_mfma_f32_16x16x32_bf16 v[44:47], v[212:215], v[160:163], v[44:47]
	v_mfma_f32_16x16x32_bf16 v[36:39], v[198:201], v[168:171], v[36:39]
	v_mfma_f32_16x16x32_bf16 v[28:31], v[212:215], v[168:171], v[28:31]
	v_mfma_f32_16x16x32_bf16 v[20:23], v[198:201], v[176:179], v[20:23]
	v_mfma_f32_16x16x32_bf16 v[12:15], v[212:215], v[176:179], v[12:15]
	v_mfma_f32_16x16x32_bf16 v[4:7], v[198:201], v[184:187], v[4:7]
	v_mfma_f32_16x16x32_bf16 v[0:3], v[212:215], v[184:187], v[0:3]
	s_setprio 0
	s_add_i32 s46, s46, 2
	s_add_u32 s44, s44, 0x100
	s_addc_u32 s45, s45, 0
	s_cmp_gt_u32 s46, 41
	s_mov_b64 s[16:17], s[18:19]
	s_barrier
	s_cbranch_scc0 .LBB0_1421
	s_mul_hi_i32 s16, s14, 0x38e38e39
	s_lshr_b32 s17, s16, 31
	s_ashr_i32 s16, s16, 1
	s_add_i32 s16, s16, s17
	s_mul_i32 s17, s16, -9
	v_lshl_or_b32 v156, s15, 8, v205
	s_ashr_i32 s15, s14, 31
	s_add_i32 s18, s17, s14
	s_lshl_b64 s[14:15], s[14:15], 19
	s_ashr_i32 s17, s16, 31
	v_lshl_add_u64 v[158:159], v[150:151], 0, s[14:15]
	v_sub_co_u32_e64 v130, s[14:15], s18, 1
	s_lshl_b64 s[18:19], s[16:17], 23
	s_and_b64 s[14:15], s[14:15], exec
	v_ashrrev_i32_e32 v131, 31, v130
	s_cselect_b32 s14, 32, s16
	v_lshlrev_b64 v[130:131], 20, v[130:131]
	s_mul_hi_i32 s15, s14, 0x6000
	s_mulk_i32 s14, 0x6000
	v_ashrrev_i32_e32 v157, 31, v156
	v_lshl_add_u64 v[130:131], s[6:7], 0, v[130:131]
	s_add_u32 s14, s37, s14
	v_lshl_add_u64 v[130:131], v[130:131], 0, s[18:19]
	s_addc_u32 s15, s38, s15
	v_lshlrev_b64 v[208:209], 2, v[156:157]
	v_lshl_add_u64 v[162:163], v[130:131], 0, v[148:149]
	v_lshl_add_u64 v[130:131], s[14:15], 0, v[208:209]
	v_lshl_add_u64 v[156:157], v[156:157], 1, v[158:159]
	global_load_dwordx4 v[142:145], v[130:131], off
	global_load_dwordx4 v[138:141], v[130:131], off offset:64
	global_load_dwordx4 v[134:137], v[130:131], off offset:512
	s_nop 0
	global_load_dwordx4 v[130:133], v[130:131], off offset:576
	s_nop 0
	s_mov_b32 s14, 0x40000
	s_nop 0
	v_lshl_add_u64 v[162:163], v[162:163], 0, v[208:209]
	s_nop 0
	s_mov_b32 s15, s42
	s_nop 0
	s_mov_b32 s14, 0x48000
	s_nop 0
	s_mov_b32 s14, 0x50000
	s_nop 0
	s_mov_b32 s14, 0x58000
	s_nop 0
	s_mov_b32 s14, 0x20000
	s_nop 0
	s_nop 0
	s_mov_b64 s[18:19], s[12:13]
	s_mov_b64 s[16:17], s[10:11]
	v_and_b32_e32 v202, 16, v224
	v_lshrrev_b32_e32 v203, 1, v202
	v_add_u32_e32 v202, v202, v203
	v_mov_b32_e32 v203, 0
	v_mov_b32_e32 v223, 0
	v_lshl_add_u64 v[246:247], v[156:157], 0, v[202:203]
	v_mov_b32_e32 v222, 0x0
	v_lshl_add_u64 v[190:191], v[246:247], 0, v[222:223]
	global_load_dwordx4 v[198:201], v[190:191], off
	global_load_dwordx4 v[218:221], v[190:191], off offset:256
	v_mov_b32_e32 v222, 0x8000
	v_lshl_add_u64 v[190:191], v[246:247], 0, v[222:223]
	global_load_dwordx4 v[242:245], v[190:191], off
	global_load_dwordx4 v[164:167], v[190:191], off offset:256
	v_mov_b32_e32 v222, 0x10000
	v_lshl_add_u64 v[190:191], v[246:247], 0, v[222:223]
	global_load_dwordx4 v[168:171], v[190:191], off
	global_load_dwordx4 v[172:175], v[190:191], off offset:256
	v_mov_b32_e32 v222, 0x18000
	v_lshl_add_u64 v[190:191], v[246:247], 0, v[222:223]
	global_load_dwordx4 v[176:179], v[190:191], off
	global_load_dwordx4 v[180:183], v[190:191], off offset:256
	v_mov_b32_e32 v222, 0x40000
	v_lshl_add_u64 v[190:191], v[246:247], 0, v[222:223]
	global_load_dwordx4 v[184:187], v[190:191], off
	s_waitcnt vmcnt(8)
	v_permlane16_swap_b32 v198, v200
	v_permlane16_swap_b32 v199, v201
	s_nop 1
	v_lshlrev_b32_e32 v210, 16, v198
	v_and_b32_e32 v211, 0xffff0000, v198
	v_lshlrev_b32_e32 v212, 16, v199
	v_and_b32_e32 v213, 0xffff0000, v199
	v_pk_fma_f32 v[126:127], v[126:127], v[142:143], v[210:211]
	v_pk_fma_f32 v[128:129], v[128:129], v[144:145], v[212:213]
	v_lshlrev_b32_e32 v214, 16, v200
	v_and_b32_e32 v215, 0xffff0000, v200
	v_lshlrev_b32_e32 v216, 16, v201
	v_and_b32_e32 v217, 0xffff0000, v201
	v_pk_fma_f32 v[122:123], v[122:123], v[138:139], v[214:215]
	v_pk_fma_f32 v[124:125], v[124:125], v[140:141], v[216:217]
	v_mov_b32_e32 v222, 0x0
	v_lshl_add_u64 v[192:193], v[162:163], 0, v[222:223]
	global_store_dwordx4 v[192:193], v[126:129], off
	global_store_dwordx4 v[192:193], v[122:125], off offset:64
	global_load_dwordx4 v[198:201], v[190:191], off offset:256
	s_waitcnt vmcnt(10)
	v_permlane16_swap_b32 v218, v220
	v_permlane16_swap_b32 v219, v221
	s_nop 1
	v_lshlrev_b32_e32 v210, 16, v218
	v_and_b32_e32 v211, 0xffff0000, v218
	v_lshlrev_b32_e32 v212, 16, v219
	v_and_b32_e32 v213, 0xffff0000, v219
	v_pk_fma_f32 v[118:119], v[118:119], v[134:135], v[210:211]
	v_pk_fma_f32 v[120:121], v[120:121], v[136:137], v[212:213]
	v_lshlrev_b32_e32 v214, 16, v220
	v_and_b32_e32 v215, 0xffff0000, v220
	v_lshlrev_b32_e32 v216, 16, v221
	v_and_b32_e32 v217, 0xffff0000, v221
	v_pk_fma_f32 v[110:111], v[110:111], v[130:131], v[214:215]
	v_pk_fma_f32 v[112:113], v[112:113], v[132:133], v[216:217]
	v_mov_b32_e32 v222, 0x0
	v_lshl_add_u64 v[192:193], v[162:163], 0, v[222:223]
	global_store_dwordx4 v[192:193], v[118:121], off offset:512
	global_store_dwordx4 v[192:193], v[110:113], off offset:576
	v_mov_b32_e32 v222, 0x48000
	v_lshl_add_u64 v[190:191], v[246:247], 0, v[222:223]
	global_load_dwordx4 v[218:221], v[190:191], off
	s_waitcnt vmcnt(12)
	v_permlane16_swap_b32 v242, v244
	v_permlane16_swap_b32 v243, v245
	s_nop 1
	v_lshlrev_b32_e32 v210, 16, v242
	v_and_b32_e32 v211, 0xffff0000, v242
	v_lshlrev_b32_e32 v212, 16, v243
	v_and_b32_e32 v213, 0xffff0000, v243
	v_pk_fma_f32 v[114:115], v[114:115], v[142:143], v[210:211]
	v_pk_fma_f32 v[116:117], v[116:117], v[144:145], v[212:213]
	v_lshlrev_b32_e32 v214, 16, v244
	v_and_b32_e32 v215, 0xffff0000, v244
	v_lshlrev_b32_e32 v216, 16, v245
	v_and_b32_e32 v217, 0xffff0000, v245
	v_pk_fma_f32 v[106:107], v[106:107], v[138:139], v[214:215]
	v_pk_fma_f32 v[108:109], v[108:109], v[140:141], v[216:217]
	v_mov_b32_e32 v222, 0x10000
	v_lshl_add_u64 v[192:193], v[162:163], 0, v[222:223]
	global_store_dwordx4 v[192:193], v[114:117], off
	global_store_dwordx4 v[192:193], v[106:109], off offset:64
	global_load_dwordx4 v[242:245], v[190:191], off offset:256
	s_waitcnt vmcnt(14)
	v_permlane16_swap_b32 v164, v166
	v_permlane16_swap_b32 v165, v167
	s_nop 1
	v_lshlrev_b32_e32 v210, 16, v164
	v_and_b32_e32 v211, 0xffff0000, v164
	v_lshlrev_b32_e32 v212, 16, v165
	v_and_b32_e32 v213, 0xffff0000, v165
	v_pk_fma_f32 v[102:103], v[102:103], v[134:135], v[210:211]
	v_pk_fma_f32 v[104:105], v[104:105], v[136:137], v[212:213]
	v_lshlrev_b32_e32 v214, 16, v166
	v_and_b32_e32 v215, 0xffff0000, v166
	v_lshlrev_b32_e32 v216, 16, v167
	v_and_b32_e32 v217, 0xffff0000, v167
	v_pk_fma_f32 v[94:95], v[94:95], v[130:131], v[214:215]
	v_pk_fma_f32 v[96:97], v[96:97], v[132:133], v[216:217]
	v_mov_b32_e32 v222, 0x10000
	v_lshl_add_u64 v[192:193], v[162:163], 0, v[222:223]
	global_store_dwordx4 v[192:193], v[102:105], off offset:512
	global_store_dwordx4 v[192:193], v[94:97], off offset:576
	v_mov_b32_e32 v222, 0x50000
	v_lshl_add_u64 v[190:191], v[246:247], 0, v[222:223]
	global_load_dwordx4 v[164:167], v[190:191], off
	s_waitcnt vmcnt(16)
	v_permlane16_swap_b32 v168, v170
	v_permlane16_swap_b32 v169, v171
	s_nop 1
	v_lshlrev_b32_e32 v210, 16, v168
	v_and_b32_e32 v211, 0xffff0000, v168
	v_lshlrev_b32_e32 v212, 16, v169
	v_and_b32_e32 v213, 0xffff0000, v169
	v_pk_fma_f32 v[98:99], v[98:99], v[142:143], v[210:211]
	v_pk_fma_f32 v[100:101], v[100:101], v[144:145], v[212:213]
	v_lshlrev_b32_e32 v214, 16, v170
	v_and_b32_e32 v215, 0xffff0000, v170
	v_lshlrev_b32_e32 v216, 16, v171
	v_and_b32_e32 v217, 0xffff0000, v171
	v_pk_fma_f32 v[90:91], v[90:91], v[138:139], v[214:215]
	v_pk_fma_f32 v[92:93], v[92:93], v[140:141], v[216:217]
	v_mov_b32_e32 v222, 0x20000
	v_lshl_add_u64 v[192:193], v[162:163], 0, v[222:223]
	global_store_dwordx4 v[192:193], v[98:101], off
	global_store_dwordx4 v[192:193], v[90:93], off offset:64
	global_load_dwordx4 v[168:171], v[190:191], off offset:256
	s_waitcnt vmcnt(18)
	v_permlane16_swap_b32 v172, v174
	v_permlane16_swap_b32 v173, v175
	s_nop 1
	v_lshlrev_b32_e32 v210, 16, v172
	v_and_b32_e32 v211, 0xffff0000, v172
	v_lshlrev_b32_e32 v212, 16, v173
	v_and_b32_e32 v213, 0xffff0000, v173
	v_pk_fma_f32 v[86:87], v[86:87], v[134:135], v[210:211]
	v_pk_fma_f32 v[88:89], v[88:89], v[136:137], v[212:213]
	v_lshlrev_b32_e32 v214, 16, v174
	v_and_b32_e32 v215, 0xffff0000, v174
	v_lshlrev_b32_e32 v216, 16, v175
	v_and_b32_e32 v217, 0xffff0000, v175
	v_pk_fma_f32 v[78:79], v[78:79], v[130:131], v[214:215]
	v_pk_fma_f32 v[80:81], v[80:81], v[132:133], v[216:217]
	v_mov_b32_e32 v222, 0x20000
	v_lshl_add_u64 v[192:193], v[162:163], 0, v[222:223]
	global_store_dwordx4 v[192:193], v[86:89], off offset:512
	global_store_dwordx4 v[192:193], v[78:81], off offset:576
	v_mov_b32_e32 v222, 0x58000
	v_lshl_add_u64 v[190:191], v[246:247], 0, v[222:223]
	global_load_dwordx4 v[172:175], v[190:191], off
	s_waitcnt vmcnt(20)
	v_permlane16_swap_b32 v176, v178
	v_permlane16_swap_b32 v177, v179
	s_nop 1
	v_lshlrev_b32_e32 v210, 16, v176
	v_and_b32_e32 v211, 0xffff0000, v176
	v_lshlrev_b32_e32 v212, 16, v177
	v_and_b32_e32 v213, 0xffff0000, v177
	v_pk_fma_f32 v[82:83], v[82:83], v[142:143], v[210:211]
	v_pk_fma_f32 v[84:85], v[84:85], v[144:145], v[212:213]
	v_lshlrev_b32_e32 v214, 16, v178
	v_and_b32_e32 v215, 0xffff0000, v178
	v_lshlrev_b32_e32 v216, 16, v179
	v_and_b32_e32 v217, 0xffff0000, v179
	v_pk_fma_f32 v[74:75], v[74:75], v[138:139], v[214:215]
	v_pk_fma_f32 v[76:77], v[76:77], v[140:141], v[216:217]
	v_mov_b32_e32 v222, 0x30000
	v_lshl_add_u64 v[192:193], v[162:163], 0, v[222:223]
	global_store_dwordx4 v[192:193], v[82:85], off
	global_store_dwordx4 v[192:193], v[74:77], off offset:64
	global_load_dwordx4 v[176:179], v[190:191], off offset:256
	s_waitcnt vmcnt(22)
	v_permlane16_swap_b32 v180, v182
	v_permlane16_swap_b32 v181, v183
	s_nop 1
	v_lshlrev_b32_e32 v210, 16, v180
	v_and_b32_e32 v211, 0xffff0000, v180
	v_lshlrev_b32_e32 v212, 16, v181
	v_and_b32_e32 v213, 0xffff0000, v181
	v_pk_fma_f32 v[70:71], v[70:71], v[134:135], v[210:211]
	v_pk_fma_f32 v[72:73], v[72:73], v[136:137], v[212:213]
	v_lshlrev_b32_e32 v214, 16, v182
	v_and_b32_e32 v215, 0xffff0000, v182
	v_lshlrev_b32_e32 v216, 16, v183
	v_and_b32_e32 v217, 0xffff0000, v183
	v_pk_fma_f32 v[66:67], v[66:67], v[130:131], v[214:215]
	v_pk_fma_f32 v[68:69], v[68:69], v[132:133], v[216:217]
	v_mov_b32_e32 v222, 0x30000
	v_lshl_add_u64 v[192:193], v[162:163], 0, v[222:223]
	global_store_dwordx4 v[192:193], v[70:73], off offset:512
	global_store_dwordx4 v[192:193], v[66:69], off offset:576
	s_waitcnt vmcnt(23)
	v_permlane16_swap_b32 v184, v186
	v_permlane16_swap_b32 v185, v187
	s_nop 1
	v_lshlrev_b32_e32 v210, 16, v184
	v_and_b32_e32 v211, 0xffff0000, v184
	v_lshlrev_b32_e32 v212, 16, v185
	v_and_b32_e32 v213, 0xffff0000, v185
	v_pk_fma_f32 v[62:63], v[62:63], v[142:143], v[210:211]
	v_pk_fma_f32 v[64:65], v[64:65], v[144:145], v[212:213]
	v_lshlrev_b32_e32 v214, 16, v186
	v_and_b32_e32 v215, 0xffff0000, v186
	v_lshlrev_b32_e32 v216, 16, v187
	v_and_b32_e32 v217, 0xffff0000, v187
	v_pk_fma_f32 v[58:59], v[58:59], v[138:139], v[214:215]
	v_pk_fma_f32 v[60:61], v[60:61], v[140:141], v[216:217]
	v_mov_b32_e32 v222, 0x80000
	v_lshl_add_u64 v[192:193], v[162:163], 0, v[222:223]
	global_store_dwordx4 v[192:193], v[62:65], off
	global_store_dwordx4 v[192:193], v[58:61], off offset:64
	s_waitcnt vmcnt(22)
	v_permlane16_swap_b32 v198, v200
	v_permlane16_swap_b32 v199, v201
	s_nop 1
	v_lshlrev_b32_e32 v210, 16, v198
	v_and_b32_e32 v211, 0xffff0000, v198
	v_lshlrev_b32_e32 v212, 16, v199
	v_and_b32_e32 v213, 0xffff0000, v199
	v_pk_fma_f32 v[54:55], v[54:55], v[134:135], v[210:211]
	v_pk_fma_f32 v[56:57], v[56:57], v[136:137], v[212:213]
	v_lshlrev_b32_e32 v214, 16, v200
	v_and_b32_e32 v215, 0xffff0000, v200
	v_lshlrev_b32_e32 v216, 16, v201
	v_and_b32_e32 v217, 0xffff0000, v201
	v_pk_fma_f32 v[44:45], v[44:45], v[130:131], v[214:215]
	v_pk_fma_f32 v[46:47], v[46:47], v[132:133], v[216:217]
	v_mov_b32_e32 v222, 0x80000
	v_lshl_add_u64 v[192:193], v[162:163], 0, v[222:223]
	global_store_dwordx4 v[192:193], v[54:57], off offset:512
	global_store_dwordx4 v[192:193], v[44:47], off offset:576
	s_waitcnt vmcnt(21)
	v_permlane16_swap_b32 v218, v220
	v_permlane16_swap_b32 v219, v221
	s_nop 1
	v_lshlrev_b32_e32 v210, 16, v218
	v_and_b32_e32 v211, 0xffff0000, v218
	v_lshlrev_b32_e32 v212, 16, v219
	v_and_b32_e32 v213, 0xffff0000, v219
	v_pk_fma_f32 v[50:51], v[50:51], v[142:143], v[210:211]
	v_pk_fma_f32 v[52:53], v[52:53], v[144:145], v[212:213]
	v_lshlrev_b32_e32 v214, 16, v220
	v_and_b32_e32 v215, 0xffff0000, v220
	v_lshlrev_b32_e32 v216, 16, v221
	v_and_b32_e32 v217, 0xffff0000, v221
	v_pk_fma_f32 v[40:41], v[40:41], v[138:139], v[214:215]
	v_pk_fma_f32 v[42:43], v[42:43], v[140:141], v[216:217]
	v_mov_b32_e32 v222, 0x90000
	v_lshl_add_u64 v[192:193], v[162:163], 0, v[222:223]
	global_store_dwordx4 v[192:193], v[50:53], off
	global_store_dwordx4 v[192:193], v[40:43], off offset:64
	s_waitcnt vmcnt(20)
	v_permlane16_swap_b32 v242, v244
	v_permlane16_swap_b32 v243, v245
	s_nop 1
	v_lshlrev_b32_e32 v210, 16, v242
	v_and_b32_e32 v211, 0xffff0000, v242
	v_lshlrev_b32_e32 v212, 16, v243
	v_and_b32_e32 v213, 0xffff0000, v243
	v_pk_fma_f32 v[36:37], v[36:37], v[134:135], v[210:211]
	v_pk_fma_f32 v[38:39], v[38:39], v[136:137], v[212:213]
	v_lshlrev_b32_e32 v214, 16, v244
	v_and_b32_e32 v215, 0xffff0000, v244
	v_lshlrev_b32_e32 v216, 16, v245
	v_and_b32_e32 v217, 0xffff0000, v245
	v_pk_fma_f32 v[28:29], v[28:29], v[130:131], v[214:215]
	v_pk_fma_f32 v[30:31], v[30:31], v[132:133], v[216:217]
	v_mov_b32_e32 v222, 0x90000
	v_lshl_add_u64 v[192:193], v[162:163], 0, v[222:223]
	global_store_dwordx4 v[192:193], v[36:39], off offset:512
	global_store_dwordx4 v[192:193], v[28:31], off offset:576
	s_waitcnt vmcnt(19)
	v_permlane16_swap_b32 v164, v166
	v_permlane16_swap_b32 v165, v167
	s_nop 1
	v_lshlrev_b32_e32 v210, 16, v164
	v_and_b32_e32 v211, 0xffff0000, v164
	v_lshlrev_b32_e32 v212, 16, v165
	v_and_b32_e32 v213, 0xffff0000, v165
	v_pk_fma_f32 v[32:33], v[32:33], v[142:143], v[210:211]
	v_pk_fma_f32 v[34:35], v[34:35], v[144:145], v[212:213]
	v_lshlrev_b32_e32 v214, 16, v166
	v_and_b32_e32 v215, 0xffff0000, v166
	v_lshlrev_b32_e32 v216, 16, v167
	v_and_b32_e32 v217, 0xffff0000, v167
	v_pk_fma_f32 v[24:25], v[24:25], v[138:139], v[214:215]
	v_pk_fma_f32 v[26:27], v[26:27], v[140:141], v[216:217]
	v_mov_b32_e32 v222, 0xa0000
	v_lshl_add_u64 v[192:193], v[162:163], 0, v[222:223]
	global_store_dwordx4 v[192:193], v[32:35], off
	global_store_dwordx4 v[192:193], v[24:27], off offset:64
	s_waitcnt vmcnt(18)
	v_permlane16_swap_b32 v168, v170
	v_permlane16_swap_b32 v169, v171
	s_nop 1
	v_lshlrev_b32_e32 v210, 16, v168
	v_and_b32_e32 v211, 0xffff0000, v168
	v_lshlrev_b32_e32 v212, 16, v169
	v_and_b32_e32 v213, 0xffff0000, v169
	v_pk_fma_f32 v[20:21], v[20:21], v[134:135], v[210:211]
	v_pk_fma_f32 v[22:23], v[22:23], v[136:137], v[212:213]
	v_lshlrev_b32_e32 v214, 16, v170
	v_and_b32_e32 v215, 0xffff0000, v170
	v_lshlrev_b32_e32 v216, 16, v171
	v_and_b32_e32 v217, 0xffff0000, v171
	v_pk_fma_f32 v[12:13], v[12:13], v[130:131], v[214:215]
	v_pk_fma_f32 v[14:15], v[14:15], v[132:133], v[216:217]
	v_mov_b32_e32 v222, 0xa0000
	v_lshl_add_u64 v[192:193], v[162:163], 0, v[222:223]
	global_store_dwordx4 v[192:193], v[20:23], off offset:512
	global_store_dwordx4 v[192:193], v[12:15], off offset:576
	s_waitcnt vmcnt(17)
	v_permlane16_swap_b32 v172, v174
	v_permlane16_swap_b32 v173, v175
	s_nop 1
	v_lshlrev_b32_e32 v210, 16, v172
	v_and_b32_e32 v211, 0xffff0000, v172
	v_lshlrev_b32_e32 v212, 16, v173
	v_and_b32_e32 v213, 0xffff0000, v173
	v_pk_fma_f32 v[16:17], v[16:17], v[142:143], v[210:211]
	v_pk_fma_f32 v[18:19], v[18:19], v[144:145], v[212:213]
	v_lshlrev_b32_e32 v214, 16, v174
	v_and_b32_e32 v215, 0xffff0000, v174
	v_lshlrev_b32_e32 v216, 16, v175
	v_and_b32_e32 v217, 0xffff0000, v175
	v_pk_fma_f32 v[8:9], v[8:9], v[138:139], v[214:215]
	v_pk_fma_f32 v[10:11], v[10:11], v[140:141], v[216:217]
	v_mov_b32_e32 v222, 0xb0000
	v_lshl_add_u64 v[192:193], v[162:163], 0, v[222:223]
	global_store_dwordx4 v[192:193], v[16:19], off
	global_store_dwordx4 v[192:193], v[8:11], off offset:64
	s_waitcnt vmcnt(16)
	v_permlane16_swap_b32 v176, v178
	v_permlane16_swap_b32 v177, v179
	s_nop 1
	v_lshlrev_b32_e32 v210, 16, v176
	v_and_b32_e32 v211, 0xffff0000, v176
	v_lshlrev_b32_e32 v212, 16, v177
	v_and_b32_e32 v213, 0xffff0000, v177
	v_pk_fma_f32 v[4:5], v[4:5], v[134:135], v[210:211]
	v_pk_fma_f32 v[6:7], v[6:7], v[136:137], v[212:213]
	v_lshlrev_b32_e32 v214, 16, v178
	v_and_b32_e32 v215, 0xffff0000, v178
	v_lshlrev_b32_e32 v216, 16, v179
	v_and_b32_e32 v217, 0xffff0000, v179
	v_pk_fma_f32 v[0:1], v[0:1], v[130:131], v[214:215]
	v_pk_fma_f32 v[2:3], v[2:3], v[132:133], v[216:217]
	v_mov_b32_e32 v222, 0xb0000
	v_lshl_add_u64 v[192:193], v[162:163], 0, v[222:223]
	global_store_dwordx4 v[192:193], v[4:7], off offset:512
	global_store_dwordx4 v[192:193], v[0:3], off offset:576
	s_mov_b32 s14, 0x30000
	s_mov_b32 s14, 0x80000
	s_mov_b32 s14, 0x90000
	s_mov_b32 s14, 0xa0000
	s_mov_b32 s14, 0xb0000
	s_and_b64 vcc, exec, s[0:1]
	s_mov_b32 s14, s43
	s_cbranch_vccz .LBB0_1418
	s_waitcnt vmcnt(0)
	s_cmpk_gt_u32 s24, 0xff
	s_cbranch_scc1 .LBB0_1425
	s_barrier

.LBB0_1435:
	s_add_u32 s20, s18, 0x100
	s_addc_u32 s21, s19, 0
	s_add_i32 s47, 0, 0x10000
	ds_read_b128 v[130:133], v214
	ds_read_b128 v[134:137], v214 offset:1024
	ds_read_b128 v[138:141], v214 offset:2048
	ds_read_b128 v[142:145], v214 offset:3072
	s_cmp_eq_u32 s46, 40
	s_cselect_b32 s25, s13, s21
	s_cselect_b32 s24, s12, s20
	s_cselect_b32 s23, s15, s45
	s_cselect_b32 s22, s14, s44
	v_lshl_add_u64 v[186:187], s[18:19], 0, v[150:151]
	s_add_i32 m0, s31, 0xc000
	ds_read_b128 v[154:157], v244
	ds_read_b128 v[158:161], v244 offset:1024
	ds_read_b128 v[162:165], v244 offset:2048
	ds_read_b128 v[166:169], v244 offset:3072
	ds_read_b128 v[170:173], v244 offset:4096
	ds_read_b128 v[174:177], v244 offset:5120
	ds_read_b128 v[178:181], v244 offset:6144
	ds_read_b128 v[182:185], v244 offset:7168
	global_load_lds_dwordx4 v[186:187], off
	v_lshl_add_u64 v[186:187], s[18:19], 0, v[152:153]
	s_add_i32 m0, s31, 0xe000
	s_nop 0
	global_load_lds_dwordx4 v[186:187], off
	s_waitcnt lgkmcnt(8)
	s_barrier
	s_waitcnt lgkmcnt(0)
	s_setprio 1
	s_waitcnt lgkmcnt(0)
	v_mfma_f32_16x16x32_bf16 v[126:129], v[130:133], v[154:157], v[126:129]
	v_mfma_f32_16x16x32_bf16 v[122:125], v[138:141], v[154:157], v[122:125]
	v_mfma_f32_16x16x32_bf16 v[114:117], v[130:133], v[162:165], v[114:117]
	v_mfma_f32_16x16x32_bf16 v[106:109], v[138:141], v[162:165], v[106:109]
	v_mfma_f32_16x16x32_bf16 v[98:101], v[130:133], v[170:173], v[98:101]
	v_mfma_f32_16x16x32_bf16 v[90:93], v[138:141], v[170:173], v[90:93]
	v_mfma_f32_16x16x32_bf16 v[82:85], v[130:133], v[178:181], v[82:85]
	v_mfma_f32_16x16x32_bf16 v[74:77], v[138:141], v[178:181], v[74:77]
	v_mfma_f32_16x16x32_bf16 v[126:129], v[134:137], v[158:161], v[126:129]
	v_mfma_f32_16x16x32_bf16 v[122:125], v[142:145], v[158:161], v[122:125]
	v_mfma_f32_16x16x32_bf16 v[114:117], v[134:137], v[166:169], v[114:117]
	v_mfma_f32_16x16x32_bf16 v[106:109], v[142:145], v[166:169], v[106:109]
	v_mfma_f32_16x16x32_bf16 v[98:101], v[134:137], v[174:177], v[98:101]
	v_mfma_f32_16x16x32_bf16 v[90:93], v[142:145], v[174:177], v[90:93]
	v_mfma_f32_16x16x32_bf16 v[82:85], v[134:137], v[182:185], v[82:85]
	v_mfma_f32_16x16x32_bf16 v[74:77], v[142:145], v[182:185], v[74:77]
	s_setprio 0
	s_barrier
	s_add_i32 s48, 0, 0x14000
	s_add_i32 s18, s47, s30
	s_mov_b32 m0, s18
	ds_read_b128 v[186:189], v214 offset:16384
	ds_read_b128 v[190:193], v214 offset:17408
	ds_read_b128 v[198:201], v214 offset:18432
	ds_read_b128 v[202:205], v214 offset:19456
	global_load_lds_dwordx4 v48, s[22:23]
	v_lshl_add_u64 v[208:209], s[22:23], 0, v[146:147]
	s_add_i32 m0, s18, 0x2000
	s_nop 0
	global_load_lds_dwordx4 v[208:209], off
	s_barrier
	s_waitcnt lgkmcnt(0)
	s_setprio 1
	s_waitcnt lgkmcnt(0)
	v_mfma_f32_16x16x32_bf16 v[118:121], v[186:189], v[154:157], v[118:121]
	v_mfma_f32_16x16x32_bf16 v[110:113], v[198:201], v[154:157], v[110:113]
	v_mfma_f32_16x16x32_bf16 v[102:105], v[186:189], v[162:165], v[102:105]
	v_mfma_f32_16x16x32_bf16 v[94:97], v[198:201], v[162:165], v[94:97]
	v_mfma_f32_16x16x32_bf16 v[86:89], v[186:189], v[170:173], v[86:89]
	v_mfma_f32_16x16x32_bf16 v[78:81], v[198:201], v[170:173], v[78:81]
	v_mfma_f32_16x16x32_bf16 v[70:73], v[186:189], v[178:181], v[70:73]
	v_mfma_f32_16x16x32_bf16 v[66:69], v[198:201], v[178:181], v[66:69]
	v_mfma_f32_16x16x32_bf16 v[118:121], v[190:193], v[158:161], v[118:121]
	v_mfma_f32_16x16x32_bf16 v[110:113], v[202:205], v[158:161], v[110:113]
	v_mfma_f32_16x16x32_bf16 v[102:105], v[190:193], v[166:169], v[102:105]
	v_mfma_f32_16x16x32_bf16 v[94:97], v[202:205], v[166:169], v[94:97]
	v_mfma_f32_16x16x32_bf16 v[86:89], v[190:193], v[174:177], v[86:89]
	v_mfma_f32_16x16x32_bf16 v[78:81], v[202:205], v[174:177], v[78:81]
	v_mfma_f32_16x16x32_bf16 v[70:73], v[190:193], v[182:185], v[70:73]
	v_mfma_f32_16x16x32_bf16 v[66:69], v[202:205], v[182:185], v[66:69]
	s_setprio 0
	s_mov_b32 m0, s31
	s_add_u32 s58, s24, s66
	s_addc_u32 s59, s25, s67
	s_barrier
	ds_read_b128 v[154:157], v244 offset:16384
	ds_read_b128 v[158:161], v244 offset:17408
	ds_read_b128 v[162:165], v244 offset:18432
	ds_read_b128 v[166:169], v244 offset:19456
	ds_read_b128 v[170:173], v244 offset:20480
	ds_read_b128 v[174:177], v244 offset:21504
	ds_read_b128 v[178:181], v244 offset:22528
	ds_read_b128 v[182:185], v244 offset:23552
	global_load_lds_dwordx4 v48, s[24:25]
	s_mov_b32 m0, s34
	s_nop 0
	global_load_lds_dwordx4 v146, s[24:25]
	s_barrier
	s_waitcnt lgkmcnt(0)
	s_setprio 1
	s_waitcnt lgkmcnt(0)
	v_mfma_f32_16x16x32_bf16 v[62:65], v[130:133], v[154:157], v[62:65]
	v_mfma_f32_16x16x32_bf16 v[58:61], v[138:141], v[154:157], v[58:61]
	v_mfma_f32_16x16x32_bf16 v[50:53], v[130:133], v[162:165], v[50:53]
	v_mfma_f32_16x16x32_bf16 v[40:43], v[138:141], v[162:165], v[40:43]
	v_mfma_f32_16x16x32_bf16 v[32:35], v[130:133], v[170:173], v[32:35]
	v_mfma_f32_16x16x32_bf16 v[24:27], v[138:141], v[170:173], v[24:27]
	v_mfma_f32_16x16x32_bf16 v[16:19], v[130:133], v[178:181], v[16:19]
	v_mfma_f32_16x16x32_bf16 v[8:11], v[138:141], v[178:181], v[8:11]
	v_mfma_f32_16x16x32_bf16 v[62:65], v[134:137], v[158:161], v[62:65]
	v_mfma_f32_16x16x32_bf16 v[58:61], v[142:145], v[158:161], v[58:61]
	v_mfma_f32_16x16x32_bf16 v[50:53], v[134:137], v[166:169], v[50:53]
	v_mfma_f32_16x16x32_bf16 v[40:43], v[142:145], v[166:169], v[40:43]
	v_mfma_f32_16x16x32_bf16 v[32:35], v[134:137], v[174:177], v[32:35]
	v_mfma_f32_16x16x32_bf16 v[24:27], v[142:145], v[174:177], v[24:27]
	v_mfma_f32_16x16x32_bf16 v[16:19], v[134:137], v[182:185], v[16:19]
	v_mfma_f32_16x16x32_bf16 v[8:11], v[142:145], v[182:185], v[8:11]
	s_setprio 0
	s_barrier
	s_add_u32 s18, s22, 0xb0000
	s_addc_u32 s19, s23, 0
	s_add_i32 s47, s48, s30
	s_mov_b32 m0, s47
	s_nop 0
	global_load_lds_dwordx4 v48, s[18:19]
	s_add_i32 m0, s47, 0x2000
	s_nop 0
	global_load_lds_dwordx4 v146, s[18:19]
	s_waitcnt vmcnt(6)
	s_barrier
	s_setprio 1
	v_mfma_f32_16x16x32_bf16 v[54:57], v[186:189], v[154:157], v[54:57]
	v_mfma_f32_16x16x32_bf16 v[44:47], v[198:201], v[154:157], v[44:47]
	v_mfma_f32_16x16x32_bf16 v[36:39], v[186:189], v[162:165], v[36:39]
	v_mfma_f32_16x16x32_bf16 v[28:31], v[198:201], v[162:165], v[28:31]
	v_mfma_f32_16x16x32_bf16 v[20:23], v[186:189], v[170:173], v[20:23]
	v_mfma_f32_16x16x32_bf16 v[12:15], v[198:201], v[170:173], v[12:15]
	v_mfma_f32_16x16x32_bf16 v[4:7], v[186:189], v[178:181], v[4:7]
	v_mfma_f32_16x16x32_bf16 v[0:3], v[198:201], v[178:181], v[0:3]
	v_mfma_f32_16x16x32_bf16 v[54:57], v[190:193], v[158:161], v[54:57]
	v_mfma_f32_16x16x32_bf16 v[44:47], v[202:205], v[158:161], v[44:47]
	v_mfma_f32_16x16x32_bf16 v[36:39], v[190:193], v[166:169], v[36:39]
	v_mfma_f32_16x16x32_bf16 v[28:31], v[202:205], v[166:169], v[28:31]
	v_mfma_f32_16x16x32_bf16 v[20:23], v[190:193], v[174:177], v[20:23]
	v_mfma_f32_16x16x32_bf16 v[12:15], v[202:205], v[174:177], v[12:15]
	v_mfma_f32_16x16x32_bf16 v[4:7], v[190:193], v[182:185], v[4:7]
	v_mfma_f32_16x16x32_bf16 v[0:3], v[202:205], v[182:185], v[0:3]
	s_setprio 0
	s_add_i32 s47, 0, 0x18000
	s_barrier
	ds_read_b128 v[130:133], v214 offset:32768
	ds_read_b128 v[134:137], v214 offset:33792
	ds_read_b128 v[138:141], v214 offset:34816
	ds_read_b128 v[142:145], v214 offset:35840
	s_add_u32 s18, s24, 0xb0000
	s_addc_u32 s19, s25, 0
	s_mov_b32 m0, s35
	ds_read_b128 v[154:157], v244 offset:32768
	ds_read_b128 v[158:161], v244 offset:33792
	ds_read_b128 v[162:165], v244 offset:34816
	ds_read_b128 v[166:169], v244 offset:35840
	ds_read_b128 v[170:173], v244 offset:36864
	ds_read_b128 v[174:177], v244 offset:37888
	ds_read_b128 v[178:181], v244 offset:38912
	ds_read_b128 v[182:185], v244 offset:39936
	global_load_lds_dwordx4 v48, s[18:19]
	s_mov_b32 m0, s36
	s_nop 0
	global_load_lds_dwordx4 v146, s[18:19]
	s_waitcnt lgkmcnt(8)
	s_barrier
	s_waitcnt lgkmcnt(0)
	s_setprio 1
	s_waitcnt lgkmcnt(0)
	v_mfma_f32_16x16x32_bf16 v[126:129], v[130:133], v[154:157], v[126:129]
	v_mfma_f32_16x16x32_bf16 v[122:125], v[138:141], v[154:157], v[122:125]
	v_mfma_f32_16x16x32_bf16 v[114:117], v[130:133], v[162:165], v[114:117]
	v_mfma_f32_16x16x32_bf16 v[106:109], v[138:141], v[162:165], v[106:109]
	v_mfma_f32_16x16x32_bf16 v[98:101], v[130:133], v[170:173], v[98:101]
	v_mfma_f32_16x16x32_bf16 v[90:93], v[138:141], v[170:173], v[90:93]
	v_mfma_f32_16x16x32_bf16 v[82:85], v[130:133], v[178:181], v[82:85]
	v_mfma_f32_16x16x32_bf16 v[74:77], v[138:141], v[178:181], v[74:77]
	v_mfma_f32_16x16x32_bf16 v[126:129], v[134:137], v[158:161], v[126:129]
	v_mfma_f32_16x16x32_bf16 v[122:125], v[142:145], v[158:161], v[122:125]
	v_mfma_f32_16x16x32_bf16 v[114:117], v[134:137], v[166:169], v[114:117]
	v_mfma_f32_16x16x32_bf16 v[106:109], v[142:145], v[166:169], v[106:109]
	v_mfma_f32_16x16x32_bf16 v[98:101], v[134:137], v[174:177], v[98:101]
	v_mfma_f32_16x16x32_bf16 v[90:93], v[142:145], v[174:177], v[90:93]
	v_mfma_f32_16x16x32_bf16 v[82:85], v[134:137], v[182:185], v[82:85]
	v_mfma_f32_16x16x32_bf16 v[74:77], v[142:145], v[182:185], v[74:77]
	s_setprio 0
	s_barrier
	s_add_i32 s24, 0, 0x1c000
	s_add_i32 s18, s47, s30
	s_add_u32 s52, s22, s66
	s_addc_u32 s53, s23, s67
	s_mov_b32 m0, s18
	ds_read_b128 v[186:189], v214 offset:49152
	ds_read_b128 v[190:193], v214 offset:50176
	ds_read_b128 v[198:201], v214 offset:51200
	ds_read_b128 v[202:205], v214 offset:52224
	global_load_lds_dwordx4 v48, s[52:53]
	s_add_i32 m0, s18, 0x2000
	s_nop 0
	global_load_lds_dwordx4 v146, s[52:53]
	s_barrier
	s_waitcnt lgkmcnt(0)
	s_setprio 1
	s_waitcnt lgkmcnt(0)
	v_mfma_f32_16x16x32_bf16 v[118:121], v[186:189], v[154:157], v[118:121]
	v_mfma_f32_16x16x32_bf16 v[110:113], v[198:201], v[154:157], v[110:113]
	v_mfma_f32_16x16x32_bf16 v[102:105], v[186:189], v[162:165], v[102:105]
	v_mfma_f32_16x16x32_bf16 v[94:97], v[198:201], v[162:165], v[94:97]
	v_mfma_f32_16x16x32_bf16 v[86:89], v[186:189], v[170:173], v[86:89]
	v_mfma_f32_16x16x32_bf16 v[78:81], v[198:201], v[170:173], v[78:81]
	v_mfma_f32_16x16x32_bf16 v[70:73], v[186:189], v[178:181], v[70:73]
	v_mfma_f32_16x16x32_bf16 v[66:69], v[198:201], v[178:181], v[66:69]
	v_mfma_f32_16x16x32_bf16 v[118:121], v[190:193], v[158:161], v[118:121]
	v_mfma_f32_16x16x32_bf16 v[110:113], v[202:205], v[158:161], v[110:113]
	v_mfma_f32_16x16x32_bf16 v[102:105], v[190:193], v[166:169], v[102:105]
	v_mfma_f32_16x16x32_bf16 v[94:97], v[202:205], v[166:169], v[94:97]
	v_mfma_f32_16x16x32_bf16 v[86:89], v[190:193], v[174:177], v[86:89]
	v_mfma_f32_16x16x32_bf16 v[78:81], v[202:205], v[174:177], v[78:81]
	v_mfma_f32_16x16x32_bf16 v[70:73], v[190:193], v[182:185], v[70:73]
	v_mfma_f32_16x16x32_bf16 v[66:69], v[202:205], v[182:185], v[66:69]
	s_setprio 0
	s_mov_b32 m0, s39
	s_barrier
	ds_read_b128 v[154:157], v244 offset:49152
	ds_read_b128 v[158:161], v244 offset:50176
	ds_read_b128 v[162:165], v244 offset:51200
	ds_read_b128 v[166:169], v244 offset:52224
	ds_read_b128 v[170:173], v244 offset:53248
	ds_read_b128 v[174:177], v244 offset:54272
	ds_read_b128 v[178:181], v244 offset:55296
	ds_read_b128 v[182:185], v244 offset:56320
	global_load_lds_dwordx4 v48, s[58:59]
	s_mov_b32 m0, s40
	s_nop 0
	global_load_lds_dwordx4 v146, s[58:59]
	s_barrier
	s_waitcnt lgkmcnt(0)
	s_setprio 1
	s_waitcnt lgkmcnt(0)
	v_mfma_f32_16x16x32_bf16 v[62:65], v[130:133], v[154:157], v[62:65]
	v_mfma_f32_16x16x32_bf16 v[58:61], v[138:141], v[154:157], v[58:61]
	v_mfma_f32_16x16x32_bf16 v[50:53], v[130:133], v[162:165], v[50:53]
	v_mfma_f32_16x16x32_bf16 v[40:43], v[138:141], v[162:165], v[40:43]
	v_mfma_f32_16x16x32_bf16 v[32:35], v[130:133], v[170:173], v[32:35]
	v_mfma_f32_16x16x32_bf16 v[24:27], v[138:141], v[170:173], v[24:27]
	v_mfma_f32_16x16x32_bf16 v[16:19], v[130:133], v[178:181], v[16:19]
	v_mfma_f32_16x16x32_bf16 v[8:11], v[138:141], v[178:181], v[8:11]
	v_mfma_f32_16x16x32_bf16 v[62:65], v[134:137], v[158:161], v[62:65]
	v_mfma_f32_16x16x32_bf16 v[58:61], v[142:145], v[158:161], v[58:61]
	v_mfma_f32_16x16x32_bf16 v[50:53], v[134:137], v[166:169], v[50:53]
	v_mfma_f32_16x16x32_bf16 v[40:43], v[142:145], v[166:169], v[40:43]
	v_mfma_f32_16x16x32_bf16 v[32:35], v[134:137], v[174:177], v[32:35]
	v_mfma_f32_16x16x32_bf16 v[24:27], v[142:145], v[174:177], v[24:27]
	v_mfma_f32_16x16x32_bf16 v[16:19], v[134:137], v[182:185], v[16:19]
	v_mfma_f32_16x16x32_bf16 v[8:11], v[142:145], v[182:185], v[8:11]
	s_setprio 0
	s_barrier
	s_add_u32 s18, s22, 0xb0080
	s_addc_u32 s19, s23, 0
	s_add_i32 s22, s24, s30
	s_mov_b32 m0, s22
	s_nop 0
	global_load_lds_dwordx4 v48, s[18:19]
	s_add_i32 m0, s22, 0x2000
	s_nop 0
	global_load_lds_dwordx4 v146, s[18:19]
	s_waitcnt vmcnt(6)
	s_barrier
	s_setprio 1
	v_mfma_f32_16x16x32_bf16 v[54:57], v[186:189], v[154:157], v[54:57]
	v_mfma_f32_16x16x32_bf16 v[44:47], v[198:201], v[154:157], v[44:47]
	v_mfma_f32_16x16x32_bf16 v[36:39], v[186:189], v[162:165], v[36:39]
	v_mfma_f32_16x16x32_bf16 v[28:31], v[198:201], v[162:165], v[28:31]
	v_mfma_f32_16x16x32_bf16 v[20:23], v[186:189], v[170:173], v[20:23]
	v_mfma_f32_16x16x32_bf16 v[12:15], v[198:201], v[170:173], v[12:15]
	v_mfma_f32_16x16x32_bf16 v[4:7], v[186:189], v[178:181], v[4:7]
	v_mfma_f32_16x16x32_bf16 v[0:3], v[198:201], v[178:181], v[0:3]
	v_mfma_f32_16x16x32_bf16 v[54:57], v[190:193], v[158:161], v[54:57]
	v_mfma_f32_16x16x32_bf16 v[44:47], v[202:205], v[158:161], v[44:47]
	v_mfma_f32_16x16x32_bf16 v[36:39], v[190:193], v[166:169], v[36:39]
	v_mfma_f32_16x16x32_bf16 v[28:31], v[202:205], v[166:169], v[28:31]
	v_mfma_f32_16x16x32_bf16 v[20:23], v[190:193], v[174:177], v[20:23]
	v_mfma_f32_16x16x32_bf16 v[12:15], v[202:205], v[174:177], v[12:15]
	v_mfma_f32_16x16x32_bf16 v[4:7], v[190:193], v[182:185], v[4:7]
	v_mfma_f32_16x16x32_bf16 v[0:3], v[202:205], v[182:185], v[0:3]
	s_setprio 0
	s_add_i32 s46, s46, 2
	s_add_u32 s44, s44, 0x100
	s_addc_u32 s45, s45, 0
	s_cmp_gt_u32 s46, 41
	s_mov_b64 s[18:19], s[20:21]
	s_barrier
	s_cbranch_scc0 .LBB0_1435
	s_mul_hi_i32 s18, s16, 0x38e38e39
	s_lshr_b32 s19, s18, 31
	s_ashr_i32 s18, s18, 1
	s_add_i32 s18, s18, s19
	s_mul_i32 s19, s18, -9
	v_lshl_or_b32 v154, s17, 8, v243
	s_sub_i32 s17, 0, s16
	s_cmp_lg_u32 s19, s17
	s_cselect_b32 s17, s18, 32
	s_mul_hi_i32 s19, s17, 0x6000
	s_mulk_i32 s17, 0x6000
	s_add_u32 s18, s37, s17
	s_addc_u32 s19, s38, s19
	s_ashr_i32 s17, s16, 31
	s_lshl_b64 s[16:17], s[16:17], 18
	v_ashrrev_i32_e32 v155, 31, v154
	v_lshl_add_u64 v[156:157], s[16:17], 0, v[148:149]
	v_lshl_add_u64 v[130:131], v[154:155], 2, s[18:19]
	v_lshl_add_u64 v[154:155], v[156:157], 0, v[154:155]
	v_lshlrev_b64 v[184:185], 1, v[154:155]
	v_lshl_add_u64 v[154:155], s[10:11], 0, v[184:185]
	global_load_dwordx4 v[142:145], v[130:131], off
	global_load_dwordx4 v[138:141], v[130:131], off offset:64
	global_load_dwordx4 v[134:137], v[130:131], off offset:512
	s_nop 0
	global_load_dwordx4 v[130:133], v[130:131], off offset:576
	s_nop 0
	s_mov_b32 s16, 0x40000
	s_nop 0
	s_mov_b32 s17, 0x48000
	s_nop 0
	s_mov_b32 s18, 0x50000
	s_nop 0
	s_mov_b32 s19, 0x58000
	s_nop 0
	v_lshl_add_u64 v[184:185], s[6:7], 0, v[184:185]
	s_nop 0
	s_mov_b64 s[20:21], s[14:15]
	s_nop 0
	v_and_b32_e32 v210, 16, v224
	v_lshrrev_b32_e32 v211, 1, v210
	v_add_u32_e32 v210, v210, v211
	v_mov_b32_e32 v211, 0
	v_mov_b32_e32 v213, 0
	v_lshl_add_u64 v[214:215], v[154:155], 0, v[210:211]
	v_lshl_add_u64 v[216:217], v[184:185], 0, v[210:211]
	v_mov_b32_e32 v212, 0x0
	v_lshl_add_u64 v[218:219], v[214:215], 0, v[212:213]
	global_load_dwordx4 v[164:167], v[218:219], off
	global_load_dwordx4 v[168:171], v[218:219], off offset:256
	v_mov_b32_e32 v212, 0x8000
	v_lshl_add_u64 v[218:219], v[214:215], 0, v[212:213]
	global_load_dwordx4 v[172:175], v[218:219], off
	global_load_dwordx4 v[176:179], v[218:219], off offset:256
	v_mov_b32_e32 v212, 0x10000
	v_lshl_add_u64 v[218:219], v[214:215], 0, v[212:213]
	global_load_dwordx4 v[180:183], v[218:219], off
	global_load_dwordx4 v[198:201], v[218:219], off offset:256
	v_mov_b32_e32 v212, 0x18000
	v_lshl_add_u64 v[218:219], v[214:215], 0, v[212:213]
	global_load_dwordx4 v[202:205], v[218:219], off
	global_load_dwordx4 v[206:209], v[218:219], off offset:256
	s_waitcnt vmcnt(7)
	v_permlane16_swap_b32 v164, v166
	v_permlane16_swap_b32 v165, v167
	s_nop 1
	v_lshlrev_b32_e32 v186, 16, v164
	v_and_b32_e32 v187, 0xffff0000, v164
	v_lshlrev_b32_e32 v188, 16, v165
	v_and_b32_e32 v189, 0xffff0000, v165
	v_pk_fma_f32 v[126:127], v[126:127], v[142:143], v[186:187]
	v_pk_fma_f32 v[128:129], v[128:129], v[144:145], v[188:189]
	v_lshlrev_b32_e32 v190, 16, v166
	v_and_b32_e32 v191, 0xffff0000, v166
	v_lshlrev_b32_e32 v192, 16, v167
	v_and_b32_e32 v193, 0xffff0000, v167
	v_pk_fma_f32 v[122:123], v[122:123], v[138:139], v[190:191]
	v_pk_fma_f32 v[124:125], v[124:125], v[140:141], v[192:193]
	v_cvt_pk_bf16_f32 v126, v126, v127
	v_cvt_pk_bf16_f32 v127, v128, v129
	v_cvt_pk_bf16_f32 v128, v122, v123
	v_cvt_pk_bf16_f32 v129, v124, v125
	s_nop 1
	v_permlane16_swap_b32 v126, v128
	v_permlane16_swap_b32 v127, v129
	v_mov_b32_e32 v212, 0x0
	v_lshl_add_u64 v[220:221], v[216:217], 0, v[212:213]
	global_store_dwordx4 v[220:221], v[126:129], off
	v_mov_b32_e32 v212, 0x40000
	v_lshl_add_u64 v[218:219], v[214:215], 0, v[212:213]
	global_load_dwordx4 v[164:167], v[218:219], off
	s_waitcnt vmcnt(8)
	v_permlane16_swap_b32 v168, v170
	v_permlane16_swap_b32 v169, v171
	s_nop 1
	v_lshlrev_b32_e32 v186, 16, v168
	v_and_b32_e32 v187, 0xffff0000, v168
	v_lshlrev_b32_e32 v188, 16, v169
	v_and_b32_e32 v189, 0xffff0000, v169
	v_pk_fma_f32 v[118:119], v[118:119], v[134:135], v[186:187]
	v_pk_fma_f32 v[120:121], v[120:121], v[136:137], v[188:189]
	v_lshlrev_b32_e32 v190, 16, v170
	v_and_b32_e32 v191, 0xffff0000, v170
	v_lshlrev_b32_e32 v192, 16, v171
	v_and_b32_e32 v193, 0xffff0000, v171
	v_pk_fma_f32 v[110:111], v[110:111], v[130:131], v[190:191]
	v_pk_fma_f32 v[112:113], v[112:113], v[132:133], v[192:193]
	v_cvt_pk_bf16_f32 v118, v118, v119
	v_cvt_pk_bf16_f32 v119, v120, v121
	v_cvt_pk_bf16_f32 v120, v110, v111
	v_cvt_pk_bf16_f32 v121, v112, v113
	s_nop 1
	v_permlane16_swap_b32 v118, v120
	v_permlane16_swap_b32 v119, v121
	v_mov_b32_e32 v212, 0x0
	v_lshl_add_u64 v[220:221], v[216:217], 0, v[212:213]
	global_store_dwordx4 v[220:221], v[118:121], off offset:256
	global_load_dwordx4 v[168:171], v[218:219], off offset:256
	s_waitcnt vmcnt(9)
	v_permlane16_swap_b32 v172, v174
	v_permlane16_swap_b32 v173, v175
	s_nop 1
	v_lshlrev_b32_e32 v186, 16, v172
	v_and_b32_e32 v187, 0xffff0000, v172
	v_lshlrev_b32_e32 v188, 16, v173
	v_and_b32_e32 v189, 0xffff0000, v173
	v_pk_fma_f32 v[114:115], v[114:115], v[142:143], v[186:187]
	v_pk_fma_f32 v[116:117], v[116:117], v[144:145], v[188:189]
	v_lshlrev_b32_e32 v190, 16, v174
	v_and_b32_e32 v191, 0xffff0000, v174
	v_lshlrev_b32_e32 v192, 16, v175
	v_and_b32_e32 v193, 0xffff0000, v175
	v_pk_fma_f32 v[106:107], v[106:107], v[138:139], v[190:191]
	v_pk_fma_f32 v[108:109], v[108:109], v[140:141], v[192:193]
	v_cvt_pk_bf16_f32 v114, v114, v115
	v_cvt_pk_bf16_f32 v115, v116, v117
	v_cvt_pk_bf16_f32 v116, v106, v107
	v_cvt_pk_bf16_f32 v117, v108, v109
	s_nop 1
	v_permlane16_swap_b32 v114, v116
	v_permlane16_swap_b32 v115, v117
	v_mov_b32_e32 v212, 0x8000
	v_lshl_add_u64 v[220:221], v[216:217], 0, v[212:213]
	global_store_dwordx4 v[220:221], v[114:117], off
	v_mov_b32_e32 v212, 0x48000
	v_lshl_add_u64 v[218:219], v[214:215], 0, v[212:213]
	global_load_dwordx4 v[172:175], v[218:219], off
	s_waitcnt vmcnt(10)
	v_permlane16_swap_b32 v176, v178
	v_permlane16_swap_b32 v177, v179
	s_nop 1
	v_lshlrev_b32_e32 v186, 16, v176
	v_and_b32_e32 v187, 0xffff0000, v176
	v_lshlrev_b32_e32 v188, 16, v177
	v_and_b32_e32 v189, 0xffff0000, v177
	v_pk_fma_f32 v[102:103], v[102:103], v[134:135], v[186:187]
	v_pk_fma_f32 v[104:105], v[104:105], v[136:137], v[188:189]
	v_lshlrev_b32_e32 v190, 16, v178
	v_and_b32_e32 v191, 0xffff0000, v178
	v_lshlrev_b32_e32 v192, 16, v179
	v_and_b32_e32 v193, 0xffff0000, v179
	v_pk_fma_f32 v[94:95], v[94:95], v[130:131], v[190:191]
	v_pk_fma_f32 v[96:97], v[96:97], v[132:133], v[192:193]
	v_cvt_pk_bf16_f32 v102, v102, v103
	v_cvt_pk_bf16_f32 v103, v104, v105
	v_cvt_pk_bf16_f32 v104, v94, v95
	v_cvt_pk_bf16_f32 v105, v96, v97
	s_nop 1
	v_permlane16_swap_b32 v102, v104
	v_permlane16_swap_b32 v103, v105
	v_mov_b32_e32 v212, 0x8000
	v_lshl_add_u64 v[220:221], v[216:217], 0, v[212:213]
	global_store_dwordx4 v[220:221], v[102:105], off offset:256
	global_load_dwordx4 v[176:179], v[218:219], off offset:256
	s_waitcnt vmcnt(11)
	v_permlane16_swap_b32 v180, v182
	v_permlane16_swap_b32 v181, v183
	s_nop 1
	v_lshlrev_b32_e32 v186, 16, v180
	v_and_b32_e32 v187, 0xffff0000, v180
	v_lshlrev_b32_e32 v188, 16, v181
	v_and_b32_e32 v189, 0xffff0000, v181
	v_pk_fma_f32 v[98:99], v[98:99], v[142:143], v[186:187]
	v_pk_fma_f32 v[100:101], v[100:101], v[144:145], v[188:189]
	v_lshlrev_b32_e32 v190, 16, v182
	v_and_b32_e32 v191, 0xffff0000, v182
	v_lshlrev_b32_e32 v192, 16, v183
	v_and_b32_e32 v193, 0xffff0000, v183
	v_pk_fma_f32 v[90:91], v[90:91], v[138:139], v[190:191]
	v_pk_fma_f32 v[92:93], v[92:93], v[140:141], v[192:193]
	v_cvt_pk_bf16_f32 v98, v98, v99
	v_cvt_pk_bf16_f32 v99, v100, v101
	v_cvt_pk_bf16_f32 v100, v90, v91
	v_cvt_pk_bf16_f32 v101, v92, v93
	s_nop 1
	v_permlane16_swap_b32 v98, v100
	v_permlane16_swap_b32 v99, v101
	v_mov_b32_e32 v212, 0x10000
	v_lshl_add_u64 v[220:221], v[216:217], 0, v[212:213]
	global_store_dwordx4 v[220:221], v[98:101], off
	v_mov_b32_e32 v212, 0x50000
	v_lshl_add_u64 v[218:219], v[214:215], 0, v[212:213]
	global_load_dwordx4 v[180:183], v[218:219], off
	s_waitcnt vmcnt(12)
	v_permlane16_swap_b32 v198, v200
	v_permlane16_swap_b32 v199, v201
	s_nop 1
	v_lshlrev_b32_e32 v186, 16, v198
	v_and_b32_e32 v187, 0xffff0000, v198
	v_lshlrev_b32_e32 v188, 16, v199
	v_and_b32_e32 v189, 0xffff0000, v199
	v_pk_fma_f32 v[86:87], v[86:87], v[134:135], v[186:187]
	v_pk_fma_f32 v[88:89], v[88:89], v[136:137], v[188:189]
	v_lshlrev_b32_e32 v190, 16, v200
	v_and_b32_e32 v191, 0xffff0000, v200
	v_lshlrev_b32_e32 v192, 16, v201
	v_and_b32_e32 v193, 0xffff0000, v201
	v_pk_fma_f32 v[78:79], v[78:79], v[130:131], v[190:191]
	v_pk_fma_f32 v[80:81], v[80:81], v[132:133], v[192:193]
	v_cvt_pk_bf16_f32 v86, v86, v87
	v_cvt_pk_bf16_f32 v87, v88, v89
	v_cvt_pk_bf16_f32 v88, v78, v79
	v_cvt_pk_bf16_f32 v89, v80, v81
	s_nop 1
	v_permlane16_swap_b32 v86, v88
	v_permlane16_swap_b32 v87, v89
	v_mov_b32_e32 v212, 0x10000
	v_lshl_add_u64 v[220:221], v[216:217], 0, v[212:213]
	global_store_dwordx4 v[220:221], v[86:89], off offset:256
	global_load_dwordx4 v[198:201], v[218:219], off offset:256
	s_waitcnt vmcnt(13)
	v_permlane16_swap_b32 v202, v204
	v_permlane16_swap_b32 v203, v205
	s_nop 1
	v_lshlrev_b32_e32 v186, 16, v202
	v_and_b32_e32 v187, 0xffff0000, v202
	v_lshlrev_b32_e32 v188, 16, v203
	v_and_b32_e32 v189, 0xffff0000, v203
	v_pk_fma_f32 v[82:83], v[82:83], v[142:143], v[186:187]
	v_pk_fma_f32 v[84:85], v[84:85], v[144:145], v[188:189]
	v_lshlrev_b32_e32 v190, 16, v204
	v_and_b32_e32 v191, 0xffff0000, v204
	v_lshlrev_b32_e32 v192, 16, v205
	v_and_b32_e32 v193, 0xffff0000, v205
	v_pk_fma_f32 v[74:75], v[74:75], v[138:139], v[190:191]
	v_pk_fma_f32 v[76:77], v[76:77], v[140:141], v[192:193]
	v_cvt_pk_bf16_f32 v82, v82, v83
	v_cvt_pk_bf16_f32 v83, v84, v85
	v_cvt_pk_bf16_f32 v84, v74, v75
	v_cvt_pk_bf16_f32 v85, v76, v77
	s_nop 1
	v_permlane16_swap_b32 v82, v84
	v_permlane16_swap_b32 v83, v85
	v_mov_b32_e32 v212, 0x18000
	v_lshl_add_u64 v[220:221], v[216:217], 0, v[212:213]
	global_store_dwordx4 v[220:221], v[82:85], off
	v_mov_b32_e32 v212, 0x58000
	v_lshl_add_u64 v[218:219], v[214:215], 0, v[212:213]
	global_load_dwordx4 v[202:205], v[218:219], off
	s_waitcnt vmcnt(14)
	v_permlane16_swap_b32 v206, v208
	v_permlane16_swap_b32 v207, v209
	s_nop 1
	v_lshlrev_b32_e32 v186, 16, v206
	v_and_b32_e32 v187, 0xffff0000, v206
	v_lshlrev_b32_e32 v188, 16, v207
	v_and_b32_e32 v189, 0xffff0000, v207
	v_pk_fma_f32 v[70:71], v[70:71], v[134:135], v[186:187]
	v_pk_fma_f32 v[72:73], v[72:73], v[136:137], v[188:189]
	v_lshlrev_b32_e32 v190, 16, v208
	v_and_b32_e32 v191, 0xffff0000, v208
	v_lshlrev_b32_e32 v192, 16, v209
	v_and_b32_e32 v193, 0xffff0000, v209
	v_pk_fma_f32 v[66:67], v[66:67], v[130:131], v[190:191]
	v_pk_fma_f32 v[68:69], v[68:69], v[132:133], v[192:193]
	v_cvt_pk_bf16_f32 v70, v70, v71
	v_cvt_pk_bf16_f32 v71, v72, v73
	v_cvt_pk_bf16_f32 v72, v66, v67
	v_cvt_pk_bf16_f32 v73, v68, v69
	s_nop 1
	v_permlane16_swap_b32 v70, v72
	v_permlane16_swap_b32 v71, v73
	v_mov_b32_e32 v212, 0x18000
	v_lshl_add_u64 v[220:221], v[216:217], 0, v[212:213]
	global_store_dwordx4 v[220:221], v[70:73], off offset:256
	global_load_dwordx4 v[206:209], v[218:219], off offset:256
	s_waitcnt vmcnt(14)
	v_permlane16_swap_b32 v164, v166
	v_permlane16_swap_b32 v165, v167
	s_nop 1
	v_lshlrev_b32_e32 v186, 16, v164
	v_and_b32_e32 v187, 0xffff0000, v164
	v_lshlrev_b32_e32 v188, 16, v165
	v_and_b32_e32 v189, 0xffff0000, v165
	v_pk_fma_f32 v[62:63], v[62:63], v[142:143], v[186:187]
	v_pk_fma_f32 v[64:65], v[64:65], v[144:145], v[188:189]
	v_lshlrev_b32_e32 v190, 16, v166
	v_and_b32_e32 v191, 0xffff0000, v166
	v_lshlrev_b32_e32 v192, 16, v167
	v_and_b32_e32 v193, 0xffff0000, v167
	v_pk_fma_f32 v[58:59], v[58:59], v[138:139], v[190:191]
	v_pk_fma_f32 v[60:61], v[60:61], v[140:141], v[192:193]
	v_cvt_pk_bf16_f32 v62, v62, v63
	v_cvt_pk_bf16_f32 v63, v64, v65
	v_cvt_pk_bf16_f32 v64, v58, v59
	v_cvt_pk_bf16_f32 v65, v60, v61
	s_nop 1
	v_permlane16_swap_b32 v62, v64
	v_permlane16_swap_b32 v63, v65
	v_mov_b32_e32 v212, 0x40000
	v_lshl_add_u64 v[220:221], v[216:217], 0, v[212:213]
	global_store_dwordx4 v[220:221], v[62:65], off
	s_waitcnt vmcnt(13)
	v_permlane16_swap_b32 v168, v170
	v_permlane16_swap_b32 v169, v171
	s_nop 1
	v_lshlrev_b32_e32 v186, 16, v168
	v_and_b32_e32 v187, 0xffff0000, v168
	v_lshlrev_b32_e32 v188, 16, v169
	v_and_b32_e32 v189, 0xffff0000, v169
	v_pk_fma_f32 v[54:55], v[54:55], v[134:135], v[186:187]
	v_pk_fma_f32 v[56:57], v[56:57], v[136:137], v[188:189]
	v_lshlrev_b32_e32 v190, 16, v170
	v_and_b32_e32 v191, 0xffff0000, v170
	v_lshlrev_b32_e32 v192, 16, v171
	v_and_b32_e32 v193, 0xffff0000, v171
	v_pk_fma_f32 v[44:45], v[44:45], v[130:131], v[190:191]
	v_pk_fma_f32 v[46:47], v[46:47], v[132:133], v[192:193]
	v_cvt_pk_bf16_f32 v54, v54, v55
	v_cvt_pk_bf16_f32 v55, v56, v57
	v_cvt_pk_bf16_f32 v56, v44, v45
	v_cvt_pk_bf16_f32 v57, v46, v47
	s_nop 1
	v_permlane16_swap_b32 v54, v56
	v_permlane16_swap_b32 v55, v57
	v_mov_b32_e32 v212, 0x40000
	v_lshl_add_u64 v[220:221], v[216:217], 0, v[212:213]
	global_store_dwordx4 v[220:221], v[54:57], off offset:256
	s_waitcnt vmcnt(12)
	v_permlane16_swap_b32 v172, v174
	v_permlane16_swap_b32 v173, v175
	s_nop 1
	v_lshlrev_b32_e32 v186, 16, v172
	v_and_b32_e32 v187, 0xffff0000, v172
	v_lshlrev_b32_e32 v188, 16, v173
	v_and_b32_e32 v189, 0xffff0000, v173
	v_pk_fma_f32 v[50:51], v[50:51], v[142:143], v[186:187]
	v_pk_fma_f32 v[52:53], v[52:53], v[144:145], v[188:189]
	v_lshlrev_b32_e32 v190, 16, v174
	v_and_b32_e32 v191, 0xffff0000, v174
	v_lshlrev_b32_e32 v192, 16, v175
	v_and_b32_e32 v193, 0xffff0000, v175
	v_pk_fma_f32 v[40:41], v[40:41], v[138:139], v[190:191]
	v_pk_fma_f32 v[42:43], v[42:43], v[140:141], v[192:193]
	v_cvt_pk_bf16_f32 v50, v50, v51
	v_cvt_pk_bf16_f32 v51, v52, v53
	v_cvt_pk_bf16_f32 v52, v40, v41
	v_cvt_pk_bf16_f32 v53, v42, v43
	s_nop 1
	v_permlane16_swap_b32 v50, v52
	v_permlane16_swap_b32 v51, v53
	v_mov_b32_e32 v212, 0x48000
	v_lshl_add_u64 v[220:221], v[216:217], 0, v[212:213]
	global_store_dwordx4 v[220:221], v[50:53], off
	s_waitcnt vmcnt(11)
	v_permlane16_swap_b32 v176, v178
	v_permlane16_swap_b32 v177, v179
	s_nop 1
	v_lshlrev_b32_e32 v186, 16, v176
	v_and_b32_e32 v187, 0xffff0000, v176
	v_lshlrev_b32_e32 v188, 16, v177
	v_and_b32_e32 v189, 0xffff0000, v177
	v_pk_fma_f32 v[36:37], v[36:37], v[134:135], v[186:187]
	v_pk_fma_f32 v[38:39], v[38:39], v[136:137], v[188:189]
	v_lshlrev_b32_e32 v190, 16, v178
	v_and_b32_e32 v191, 0xffff0000, v178
	v_lshlrev_b32_e32 v192, 16, v179
	v_and_b32_e32 v193, 0xffff0000, v179
	v_pk_fma_f32 v[28:29], v[28:29], v[130:131], v[190:191]
	v_pk_fma_f32 v[30:31], v[30:31], v[132:133], v[192:193]
	v_cvt_pk_bf16_f32 v36, v36, v37
	v_cvt_pk_bf16_f32 v37, v38, v39
	v_cvt_pk_bf16_f32 v38, v28, v29
	v_cvt_pk_bf16_f32 v39, v30, v31
	s_nop 1
	v_permlane16_swap_b32 v36, v38
	v_permlane16_swap_b32 v37, v39
	v_mov_b32_e32 v212, 0x48000
	v_lshl_add_u64 v[220:221], v[216:217], 0, v[212:213]
	global_store_dwordx4 v[220:221], v[36:39], off offset:256
	s_waitcnt vmcnt(10)
	v_permlane16_swap_b32 v180, v182
	v_permlane16_swap_b32 v181, v183
	s_nop 1
	v_lshlrev_b32_e32 v186, 16, v180
	v_and_b32_e32 v187, 0xffff0000, v180
	v_lshlrev_b32_e32 v188, 16, v181
	v_and_b32_e32 v189, 0xffff0000, v181
	v_pk_fma_f32 v[32:33], v[32:33], v[142:143], v[186:187]
	v_pk_fma_f32 v[34:35], v[34:35], v[144:145], v[188:189]
	v_lshlrev_b32_e32 v190, 16, v182
	v_and_b32_e32 v191, 0xffff0000, v182
	v_lshlrev_b32_e32 v192, 16, v183
	v_and_b32_e32 v193, 0xffff0000, v183
	v_pk_fma_f32 v[24:25], v[24:25], v[138:139], v[190:191]
	v_pk_fma_f32 v[26:27], v[26:27], v[140:141], v[192:193]
	v_cvt_pk_bf16_f32 v32, v32, v33
	v_cvt_pk_bf16_f32 v33, v34, v35
	v_cvt_pk_bf16_f32 v34, v24, v25
	v_cvt_pk_bf16_f32 v35, v26, v27
	s_nop 1
	v_permlane16_swap_b32 v32, v34
	v_permlane16_swap_b32 v33, v35
	v_mov_b32_e32 v212, 0x50000
	v_lshl_add_u64 v[220:221], v[216:217], 0, v[212:213]
	global_store_dwordx4 v[220:221], v[32:35], off
	s_waitcnt vmcnt(9)
	v_permlane16_swap_b32 v198, v200
	v_permlane16_swap_b32 v199, v201
	s_nop 1
	v_lshlrev_b32_e32 v186, 16, v198
	v_and_b32_e32 v187, 0xffff0000, v198
	v_lshlrev_b32_e32 v188, 16, v199
	v_and_b32_e32 v189, 0xffff0000, v199
	v_pk_fma_f32 v[20:21], v[20:21], v[134:135], v[186:187]
	v_pk_fma_f32 v[22:23], v[22:23], v[136:137], v[188:189]
	v_lshlrev_b32_e32 v190, 16, v200
	v_and_b32_e32 v191, 0xffff0000, v200
	v_lshlrev_b32_e32 v192, 16, v201
	v_and_b32_e32 v193, 0xffff0000, v201
	v_pk_fma_f32 v[12:13], v[12:13], v[130:131], v[190:191]
	v_pk_fma_f32 v[14:15], v[14:15], v[132:133], v[192:193]
	v_cvt_pk_bf16_f32 v20, v20, v21
	v_cvt_pk_bf16_f32 v21, v22, v23
	v_cvt_pk_bf16_f32 v22, v12, v13
	v_cvt_pk_bf16_f32 v23, v14, v15
	s_nop 1
	v_permlane16_swap_b32 v20, v22
	v_permlane16_swap_b32 v21, v23
	v_mov_b32_e32 v212, 0x50000
	v_lshl_add_u64 v[220:221], v[216:217], 0, v[212:213]
	global_store_dwordx4 v[220:221], v[20:23], off offset:256
	s_waitcnt vmcnt(8)
	v_permlane16_swap_b32 v202, v204
	v_permlane16_swap_b32 v203, v205
	s_nop 1
	v_lshlrev_b32_e32 v186, 16, v202
	v_and_b32_e32 v187, 0xffff0000, v202
	v_lshlrev_b32_e32 v188, 16, v203
	v_and_b32_e32 v189, 0xffff0000, v203
	v_pk_fma_f32 v[16:17], v[16:17], v[142:143], v[186:187]
	v_pk_fma_f32 v[18:19], v[18:19], v[144:145], v[188:189]
	v_lshlrev_b32_e32 v190, 16, v204
	v_and_b32_e32 v191, 0xffff0000, v204
	v_lshlrev_b32_e32 v192, 16, v205
	v_and_b32_e32 v193, 0xffff0000, v205
	v_pk_fma_f32 v[8:9], v[8:9], v[138:139], v[190:191]
	v_pk_fma_f32 v[10:11], v[10:11], v[140:141], v[192:193]
	v_cvt_pk_bf16_f32 v16, v16, v17
	v_cvt_pk_bf16_f32 v17, v18, v19
	v_cvt_pk_bf16_f32 v18, v8, v9
	v_cvt_pk_bf16_f32 v19, v10, v11
	s_nop 1
	v_permlane16_swap_b32 v16, v18
	v_permlane16_swap_b32 v17, v19
	v_mov_b32_e32 v212, 0x58000
	v_lshl_add_u64 v[220:221], v[216:217], 0, v[212:213]
	global_store_dwordx4 v[220:221], v[16:19], off
	s_waitcnt vmcnt(7)
	v_permlane16_swap_b32 v206, v208
	v_permlane16_swap_b32 v207, v209
	s_nop 1
	v_lshlrev_b32_e32 v186, 16, v206
	v_and_b32_e32 v187, 0xffff0000, v206
	v_lshlrev_b32_e32 v188, 16, v207
	v_and_b32_e32 v189, 0xffff0000, v207
	v_pk_fma_f32 v[4:5], v[4:5], v[134:135], v[186:187]
	v_pk_fma_f32 v[6:7], v[6:7], v[136:137], v[188:189]
	v_lshlrev_b32_e32 v190, 16, v208
	v_and_b32_e32 v191, 0xffff0000, v208
	v_lshlrev_b32_e32 v192, 16, v209
	v_and_b32_e32 v193, 0xffff0000, v209
	v_pk_fma_f32 v[0:1], v[0:1], v[130:131], v[190:191]
	v_pk_fma_f32 v[2:3], v[2:3], v[132:133], v[192:193]
	v_cvt_pk_bf16_f32 v4, v4, v5
	v_cvt_pk_bf16_f32 v5, v6, v7
	v_cvt_pk_bf16_f32 v6, v0, v1
	v_cvt_pk_bf16_f32 v7, v2, v3
	s_nop 1
	v_permlane16_swap_b32 v4, v6
	v_permlane16_swap_b32 v5, v7
	v_mov_b32_e32 v212, 0x58000
	v_lshl_add_u64 v[220:221], v[216:217], 0, v[212:213]
	global_store_dwordx4 v[220:221], v[4:7], off offset:256
	s_mov_b32 s16, s43
	s_mov_b32 s17, s42
	s_and_b64 vcc, exec, s[0:1]
	s_mov_b64 s[18:19], s[12:13]
	s_cbranch_vccz .LBB0_1432
	s_waitcnt vmcnt(0)
	s_cmpk_gt_u32 s29, 0xff
	s_cbranch_scc1 .LBB0_1439
	s_barrier
